# plus compute-segment slimming: middle setprio pair removed, head waitcnt removed, setprio moved across barriers
# speedup vs baseline: 1.0123x; 1.0017x over previous
; #define PG8_STAGEX(b, gbase) do { if constexpr (XR) { if (lane < 16) __builtin_amdgcn_global_load_lds((const unsigned*)((const char*)(gbase) + voffX), (PG8_LAS unsigned*)(lds + XR_OFF + (b) * 2048 + wid * 256), 16, 0, 0); } } while (0)
; #define PG8_LDX(b) do { if constexpr (XR) { _Pragma("unroll") for (int k = 0; k < 2; ++k) Ax_[k] = *(const PG8_LAS bf16x8*)(lds + XR_OFF + (b) * 2048 + aoffx + k * 1024); } } while (0)
; #define PG8_MMAX() do { if constexpr (XR) { if (hasx) { __builtin_amdgcn_s_setprio(1); if (wr == 0) PG8_MMAX_(B0); else PG8_MMAX_(B1); __builtin_amdgcn_s_setprio(0); } } } while (0)
; #define PG8_WAIT_LOOP() do { if constexpr (XR) PG8_WAIT_V(9); else PG8_WAIT_V(8); } while (0)
; #define PG8_STAGE(bufoff, gbase, voff) do { _Pragma("unroll") for (int _i = 0; _i < 2; ++_i) \
;         __builtin_amdgcn_global_load_lds((const unsigned*)((const char*)(gbase) + (voff)[_i]), (PG8_LAS unsigned*)(lds + (bufoff) + ldsw + _i * 8192), 16, 0, 0); } while (0)
; #define PG8_WAIT_L(n) asm volatile("s_waitcnt lgkmcnt(" #n ")" ::: "memory")
; template <class Epi, class Sched, bool ALIGN_EPI = false, bool SP2 = false, bool DRAIN = true, bool XR = false>
; __device__ __forceinline__ void gemm_phase(PG8_LAS unsigned char* lds, const Gemm g, const Sched& S, const Epi& E) {
;     ...
;         for (int t = 0; t < nt; t += 2) {
;             if constexpr (Epi::MIDSCALE) { if (t == (nt >> 1)) E.midscale(acc, cur, wr, fr); }
;             const bool last = (t == nt - 2);
;             const char* a1 = cA + PG8_KOA(t) + kstep;
;             const char* a2 = last ? nA + ka0 : cA + PG8_KOA(t + 2); const char* b2 = last ? nB + kb0 : cB + PG8_KOB(t + 2);
;             const char* x2 = XR ? (last ? nX + kx0 : cX + PG8_KOX(t + 2)) : nullptr; const char* x3 = XR ? x2 + kstep : nullptr;
;             const char* a3 = a2 + kstep; const char* b3 = b2 + kstep;
;             if (last && has_next) S.a_ready(nxt);
;             if constexpr (SP2) {
;             PG8_LDB(B0, 0, 0); PG8_LDB(B1, 0, 1); PG8_SCHED; PG8_LDA(At, 0, 0); PG8_LDX(0); PG8_STAGE(PG8_SA(1, 1), a1 + hstepA, voffA);
;             PG8_WAIT_LOOP(); PG8_WAIT_L(0); PG8_BAR; PG8_MMA(0, 0, At, B0); PG8_MMA(0, 1, At, B1); PG8_MMAX(); PG8_BAR; PG8_SCHED;
;             PG8_LDA(At, 0, 1); PG8_STAGE(PG8_SB(0, 0), b2, voffB); PG8_STAGE(PG8_SB(0, 1), b2 + hstep, voffB); PG8_STAGE(PG8_SA(0, 0), a2, voffA); PG8_STAGEX(0, x2);
.LBB0_325:
	s_add_i32 s26, s61, s25
	s_and_b32 s27, s26, s43
	s_lshr_b32 s84, s27, 2
	s_lshl_b32 s27, s27, 7
	s_lshl_b64 s[0:1], s[84:85], 9
	s_and_b32 s27, s27, 0x100
	s_add_u32 s0, s80, s0
	s_addc_u32 s1, s81, s1
	s_add_u32 s40, s0, s27
	s_addc_u32 s41, s1, 0
	s_add_i32 s26, s26, 2
	s_and_b32 s0, s26, s43
	s_lshr_b32 s84, s0, 2
	s_lshl_b32 s1, s0, 7
	s_lshl_b64 s[26:27], s[84:85], 9
	s_and_b32 s1, s1, 0x100
	s_add_u32 s26, s80, s26
	s_addc_u32 s27, s81, s27
	s_add_u32 s26, s26, s1
	s_mov_b32 s1, s85
	s_addc_u32 s27, s27, 0
	s_lshl_b64 s[0:1], s[0:1], 7
	s_add_u32 s36, s76, s0
	s_addc_u32 vcc_lo, s77, s1
	s_add_i32 vcc_hi, 0, 0x10000
	s_cmp_eq_u32 s42, s25
	s_cselect_b32 s1, s22, s27
	s_cselect_b32 s0, s5, s26
	v_add_u32_e32 v2, vcc_hi, v183
	s_cselect_b32 s27, s24, vcc_lo
	s_cselect_b32 s26, s23, s36
	s_add_i32 s36, 0, 0x14000
	ds_read_b128 v[134:137], v2
	ds_read_b128 v[148:151], v2 offset:1024
	ds_read_b128 v[152:155], v2 offset:2048
	ds_read_b128 v[156:159], v2 offset:3072
	v_add_u32_e32 v2, s36, v183
	ds_read_b128 v[160:163], v2
	ds_read_b128 v[164:167], v2 offset:1024
	ds_read_b128 v[168:171], v2 offset:2048
	ds_read_b128 v[172:175], v2 offset:3072
	s_add_u32 s40, s40, s30
	s_addc_u32 s41, s41, s31
	v_lshl_add_u64 v[4:5], s[40:41], 0, v[144:145]
	v_lshl_add_u64 v[4:5], v[4:5], 0, s[86:87]
	s_add_i32 m0, s46, 0xc000
	ds_read_b128 v[176:179], v186
	ds_read_b128 v[188:191], v186 offset:1024
	ds_read_b128 v[192:195], v186 offset:2048
	ds_read_b128 v[196:199], v186 offset:3072
	ds_read_b128 v[200:203], v186 offset:4096
	ds_read_b128 v[214:217], v186 offset:5120
	ds_read_b128 v[218:221], v186 offset:6144
	ds_read_b128 v[222:225], v186 offset:7168
	global_load_lds_dwordx4 v[4:5], off
	v_lshl_add_u64 v[4:5], s[40:41], 0, v[140:141]
	v_lshl_add_u64 v[4:5], v[4:5], 0, s[86:87]
	s_add_i32 m0, s46, 0xe000
	s_nop 0
	global_load_lds_dwordx4 v[4:5], off
	s_waitcnt vmcnt(8)
	s_waitcnt lgkmcnt(0)
	s_setprio 1
	s_barrier
	v_mfma_f32_16x16x32_bf16 v[130:133], v[134:137], v[176:179], v[130:133]
	v_mfma_f32_16x16x32_bf16 v[126:129], v[152:155], v[176:179], v[126:129]
	v_mfma_f32_16x16x32_bf16 v[122:125], v[134:137], v[192:195], v[122:125]
	v_mfma_f32_16x16x32_bf16 v[118:121], v[152:155], v[192:195], v[118:121]
	v_mfma_f32_16x16x32_bf16 v[114:117], v[134:137], v[200:203], v[114:117]
	v_mfma_f32_16x16x32_bf16 v[110:113], v[152:155], v[200:203], v[110:113]
	v_mfma_f32_16x16x32_bf16 v[106:109], v[134:137], v[218:221], v[106:109]
	v_mfma_f32_16x16x32_bf16 v[102:105], v[152:155], v[218:221], v[102:105]
	v_mfma_f32_16x16x32_bf16 v[130:133], v[148:151], v[188:191], v[130:133]
	v_mfma_f32_16x16x32_bf16 v[126:129], v[156:159], v[188:191], v[126:129]
	v_mfma_f32_16x16x32_bf16 v[122:125], v[148:151], v[196:199], v[122:125]
	v_mfma_f32_16x16x32_bf16 v[118:121], v[156:159], v[196:199], v[118:121]
	v_mfma_f32_16x16x32_bf16 v[114:117], v[148:151], v[214:217], v[114:117]
	v_mfma_f32_16x16x32_bf16 v[110:113], v[156:159], v[214:217], v[110:113]
	v_mfma_f32_16x16x32_bf16 v[106:109], v[148:151], v[222:225], v[106:109]
	v_mfma_f32_16x16x32_bf16 v[102:105], v[156:159], v[222:225], v[102:105]
	v_mfma_f32_16x16x32_bf16 v[98:101], v[160:163], v[176:179], v[98:101]
	v_mfma_f32_16x16x32_bf16 v[94:97], v[168:171], v[176:179], v[94:97]
	v_mfma_f32_16x16x32_bf16 v[90:93], v[160:163], v[192:195], v[90:93]
	v_mfma_f32_16x16x32_bf16 v[86:89], v[168:171], v[192:195], v[86:89]
	v_mfma_f32_16x16x32_bf16 v[82:85], v[160:163], v[200:203], v[82:85]
	v_mfma_f32_16x16x32_bf16 v[78:81], v[168:171], v[200:203], v[78:81]
	v_mfma_f32_16x16x32_bf16 v[74:77], v[160:163], v[218:221], v[74:77]
	v_mfma_f32_16x16x32_bf16 v[70:73], v[168:171], v[218:221], v[70:73]
	v_mfma_f32_16x16x32_bf16 v[98:101], v[164:167], v[188:191], v[98:101]
	v_mfma_f32_16x16x32_bf16 v[94:97], v[172:175], v[188:191], v[94:97]
	v_mfma_f32_16x16x32_bf16 v[90:93], v[164:167], v[196:199], v[90:93]
	v_mfma_f32_16x16x32_bf16 v[86:89], v[172:175], v[196:199], v[86:89]
	v_mfma_f32_16x16x32_bf16 v[82:85], v[164:167], v[214:217], v[82:85]
	v_mfma_f32_16x16x32_bf16 v[78:81], v[172:175], v[214:217], v[78:81]
	v_mfma_f32_16x16x32_bf16 v[74:77], v[164:167], v[222:225], v[74:77]
	v_mfma_f32_16x16x32_bf16 v[70:73], v[172:175], v[222:225], v[70:73]
	s_barrier
	s_setprio 0
	s_add_i32 s40, vcc_hi, s44
	v_lshl_add_u64 v[180:181], s[26:27], 0, v[142:143]
	s_mov_b32 m0, s40
	ds_read_b128 v[176:179], v186 offset:16384
	ds_read_b128 v[188:191], v186 offset:17408
	ds_read_b128 v[192:195], v186 offset:18432
	ds_read_b128 v[196:199], v186 offset:19456
	ds_read_b128 v[200:203], v186 offset:20480
	ds_read_b128 v[214:217], v186 offset:21504
	ds_read_b128 v[218:221], v186 offset:22528
	ds_read_b128 v[222:225], v186 offset:23552
	global_load_lds_dwordx4 v[180:181], off
	s_add_i32 m0, s40, 0x2000
	v_lshl_add_u64 v[204:205], s[26:27], 0, v[138:139]
	s_add_u32 s26, s26, s30
	s_addc_u32 s27, s27, s31
	s_add_i32 s36, s36, s44
	global_load_lds_dwordx4 v[204:205], off
	v_lshl_add_u64 v[206:207], s[26:27], 0, v[142:143]
	s_mov_b32 m0, s36
	v_lshl_add_u64 v[208:209], s[26:27], 0, v[138:139]
	global_load_lds_dwordx4 v[206:207], off
	s_add_i32 m0, s36, 0x2000
	v_lshl_add_u64 v[226:227], s[0:1], 0, v[144:145]
	global_load_lds_dwordx4 v[208:209], off
	s_mov_b32 m0, s46
	v_lshl_add_u64 v[228:229], s[0:1], 0, v[140:141]
	global_load_lds_dwordx4 v[226:227], off
	s_mov_b32 m0, s47
	s_nop 0
	global_load_lds_dwordx4 v[228:229], off
	s_waitcnt vmcnt(8)
	s_waitcnt lgkmcnt(0)
	s_setprio 1
	s_barrier
; #define PG8_LDX(b) do { if constexpr (XR) { _Pragma("unroll") for (int k = 0; k < 2; ++k) Ax_[k] = *(const PG8_LAS bf16x8*)(lds + XR_OFF + (b) * 2048 + aoffx + k * 1024); } } while (0)
; #define PG8_MMAX() do { if constexpr (XR) { if (hasx) { __builtin_amdgcn_s_setprio(1); if (wr == 0) PG8_MMAX_(B0); else PG8_MMAX_(B1); __builtin_amdgcn_s_setprio(0); } } } while (0)
; #define PG8_WAIT_LOOP() do { if constexpr (XR) PG8_WAIT_V(9); else PG8_WAIT_V(8); } while (0)
; #define PG8_STAGE(bufoff, gbase, voff) do { _Pragma("unroll") for (int _i = 0; _i < 2; ++_i) \
;         __builtin_amdgcn_global_load_lds((const unsigned*)((const char*)(gbase) + (voff)[_i]), (PG8_LAS unsigned*)(lds + (bufoff) + ldsw + _i * 8192), 16, 0, 0); } while (0)
; #define PG8_LDA(dst, b, h) do { _Pragma("unroll") for (int m = 0; m < 4; ++m) _Pragma("unroll") for (int k = 0; k < 2; ++k) dst[m][k] = *(const PG8_LAS bf16x8*)(lds + PG8_SA(b, h) + aoff + m * 2048 + k * 1024); } while (0)
; #define PG8_LDB(dst, b, h) do { _Pragma("unroll") for (int n = 0; n < 2; ++n) _Pragma("unroll") for (int k = 0; k < 2; ++k) dst[n][k] = *(const PG8_LAS bf16x8*)(lds + PG8_SB(b, h) + boff + n * 2048 + k * 1024); } while (0)
; #define PG8_MMA(ai, bj, At, Bt) do { __builtin_amdgcn_s_setprio(1); _Pragma("unroll") for (int m = 0; m < 4; ++m) _Pragma("unroll") for (int n = 0; n < 2; ++n) _Pragma("unroll") for (int k = 0; k < 2; ++k) \
;         acc[ai][bj][m][n] = __builtin_amdgcn_mfma_f32_16x16x32_bf16(Bt[n][k], At[m][k], acc[ai][bj][m][n], 0, 0, 0); __builtin_amdgcn_s_setprio(0); } while (0)
; #define PG8_WAIT_L(n) asm volatile("s_waitcnt lgkmcnt(" #n ")" ::: "memory")
; #define PG8_BAR __builtin_amdgcn_s_barrier()
; #define PG8_SCHED __builtin_amdgcn_sched_barrier(0)
; template <class Epi, class Sched, bool ALIGN_EPI = false, bool SP2 = false, bool DRAIN = true, bool XR = false>
; __device__ __forceinline__ void gemm_phase(PG8_LAS unsigned char* lds, const Gemm g, const Sched& S, const Epi& E) {
;     ...
;             PG8_WAIT_LOOP(); PG8_WAIT_L(0); PG8_BAR; PG8_MMA(1, 0, At, B0); PG8_MMA(1, 1, At, B1); PG8_BAR; PG8_SCHED;
;             PG8_LDB(B0, 1, 0); PG8_LDB(B1, 1, 1); PG8_SCHED; PG8_LDA(At, 1, 0); PG8_LDX(1); PG8_STAGE(PG8_SA(0, 1), a2 + hstepA, voffA);
;             PG8_WAIT_LOOP(); PG8_WAIT_L(0); PG8_BAR; PG8_MMA(0, 0, At, B0); PG8_MMA(0, 1, At, B1); PG8_MMAX(); PG8_BAR; PG8_SCHED;
	v_mfma_f32_16x16x32_bf16 v[66:69], v[134:137], v[176:179], v[66:69]
	v_mfma_f32_16x16x32_bf16 v[62:65], v[152:155], v[176:179], v[62:65]
	v_mfma_f32_16x16x32_bf16 v[58:61], v[134:137], v[192:195], v[58:61]
	v_mfma_f32_16x16x32_bf16 v[54:57], v[152:155], v[192:195], v[54:57]
	v_mfma_f32_16x16x32_bf16 v[50:53], v[134:137], v[200:203], v[50:53]
	v_mfma_f32_16x16x32_bf16 v[46:49], v[152:155], v[200:203], v[46:49]
	v_mfma_f32_16x16x32_bf16 v[42:45], v[134:137], v[218:221], v[42:45]
	v_mfma_f32_16x16x32_bf16 v[38:41], v[152:155], v[218:221], v[38:41]
	v_mfma_f32_16x16x32_bf16 v[66:69], v[148:151], v[188:191], v[66:69]
	v_mfma_f32_16x16x32_bf16 v[62:65], v[156:159], v[188:191], v[62:65]
	v_mfma_f32_16x16x32_bf16 v[58:61], v[148:151], v[196:199], v[58:61]
	v_mfma_f32_16x16x32_bf16 v[54:57], v[156:159], v[196:199], v[54:57]
	v_mfma_f32_16x16x32_bf16 v[50:53], v[148:151], v[214:217], v[50:53]
	v_mfma_f32_16x16x32_bf16 v[46:49], v[156:159], v[214:217], v[46:49]
	v_mfma_f32_16x16x32_bf16 v[42:45], v[148:151], v[222:225], v[42:45]
	v_mfma_f32_16x16x32_bf16 v[38:41], v[156:159], v[222:225], v[38:41]
	v_mfma_f32_16x16x32_bf16 v[34:37], v[160:163], v[176:179], v[34:37]
	v_mfma_f32_16x16x32_bf16 v[30:33], v[168:171], v[176:179], v[30:33]
	v_mfma_f32_16x16x32_bf16 v[26:29], v[160:163], v[192:195], v[26:29]
	v_mfma_f32_16x16x32_bf16 v[22:25], v[168:171], v[192:195], v[22:25]
	v_mfma_f32_16x16x32_bf16 v[18:21], v[160:163], v[200:203], v[18:21]
	v_mfma_f32_16x16x32_bf16 v[14:17], v[168:171], v[200:203], v[14:17]
	v_mfma_f32_16x16x32_bf16 v[10:13], v[160:163], v[218:221], v[10:13]
	v_mfma_f32_16x16x32_bf16 v[4:7], v[168:171], v[218:221], v[6:9]
	v_mfma_f32_16x16x32_bf16 v[34:37], v[164:167], v[188:191], v[34:37]
	v_mfma_f32_16x16x32_bf16 v[30:33], v[172:175], v[188:191], v[30:33]
	v_mfma_f32_16x16x32_bf16 v[26:29], v[164:167], v[196:199], v[26:29]
	v_mfma_f32_16x16x32_bf16 v[22:25], v[172:175], v[196:199], v[22:25]
	v_mfma_f32_16x16x32_bf16 v[18:21], v[164:167], v[214:217], v[18:21]
	v_mfma_f32_16x16x32_bf16 v[14:17], v[172:175], v[214:217], v[14:17]
	v_mfma_f32_16x16x32_bf16 v[10:13], v[164:167], v[222:225], v[10:13]
	v_mfma_f32_16x16x32_bf16 v[4:7], v[172:175], v[222:225], v[4:7]
	s_barrier
	s_setprio 0
	s_add_i32 s26, 0, 0x18000
	v_add_u32_e32 v2, s26, v183
	s_add_i32 s27, 0, 0x1c000
	ds_read_b128 v[134:137], v2
	ds_read_b128 v[148:151], v2 offset:1024
	ds_read_b128 v[152:155], v2 offset:2048
	ds_read_b128 v[156:159], v2 offset:3072
	v_add_u32_e32 v2, s27, v183
	ds_read_b128 v[160:163], v2
	ds_read_b128 v[164:167], v2 offset:1024
	ds_read_b128 v[168:171], v2 offset:2048
	ds_read_b128 v[172:175], v2 offset:3072
	s_add_u32 s0, s0, s30
	s_addc_u32 s1, s1, s31
	s_mov_b32 m0, s48
	v_lshl_add_u64 v[8:9], s[0:1], 0, v[144:145]
	ds_read_b128 v[176:179], v186 offset:32768
	ds_read_b128 v[188:191], v186 offset:33792
	ds_read_b128 v[192:195], v186 offset:34816
	ds_read_b128 v[196:199], v186 offset:35840
	ds_read_b128 v[200:203], v186 offset:36864
	ds_read_b128 v[214:217], v186 offset:37888
	ds_read_b128 v[218:221], v186 offset:38912
	ds_read_b128 v[222:225], v186 offset:39936
	global_load_lds_dwordx4 v[8:9], off
	v_lshl_add_u64 v[8:9], s[0:1], 0, v[140:141]
	s_mov_b32 m0, s49
	s_nop 0
	global_load_lds_dwordx4 v[8:9], off
	s_waitcnt vmcnt(8)
	s_waitcnt lgkmcnt(0)
	s_setprio 1
	s_barrier
	v_mfma_f32_16x16x32_bf16 v[130:133], v[134:137], v[176:179], v[130:133]
	v_mfma_f32_16x16x32_bf16 v[126:129], v[152:155], v[176:179], v[126:129]
	v_mfma_f32_16x16x32_bf16 v[122:125], v[134:137], v[192:195], v[122:125]
	v_mfma_f32_16x16x32_bf16 v[118:121], v[152:155], v[192:195], v[118:121]
	v_mfma_f32_16x16x32_bf16 v[114:117], v[134:137], v[200:203], v[114:117]
	v_mfma_f32_16x16x32_bf16 v[110:113], v[152:155], v[200:203], v[110:113]
	v_mfma_f32_16x16x32_bf16 v[106:109], v[134:137], v[218:221], v[106:109]
	v_mfma_f32_16x16x32_bf16 v[102:105], v[152:155], v[218:221], v[102:105]
	v_mfma_f32_16x16x32_bf16 v[130:133], v[148:151], v[188:191], v[130:133]
	v_mfma_f32_16x16x32_bf16 v[126:129], v[156:159], v[188:191], v[126:129]
	v_mfma_f32_16x16x32_bf16 v[122:125], v[148:151], v[196:199], v[122:125]
	v_mfma_f32_16x16x32_bf16 v[118:121], v[156:159], v[196:199], v[118:121]
	v_mfma_f32_16x16x32_bf16 v[114:117], v[148:151], v[214:217], v[114:117]
	v_mfma_f32_16x16x32_bf16 v[110:113], v[156:159], v[214:217], v[110:113]
	v_mfma_f32_16x16x32_bf16 v[106:109], v[148:151], v[222:225], v[106:109]
	v_mfma_f32_16x16x32_bf16 v[102:105], v[156:159], v[222:225], v[102:105]
	v_mfma_f32_16x16x32_bf16 v[98:101], v[160:163], v[176:179], v[98:101]
	v_mfma_f32_16x16x32_bf16 v[94:97], v[168:171], v[176:179], v[94:97]
	v_mfma_f32_16x16x32_bf16 v[90:93], v[160:163], v[192:195], v[90:93]
	v_mfma_f32_16x16x32_bf16 v[86:89], v[168:171], v[192:195], v[86:89]
	v_mfma_f32_16x16x32_bf16 v[82:85], v[160:163], v[200:203], v[82:85]
	v_mfma_f32_16x16x32_bf16 v[78:81], v[168:171], v[200:203], v[78:81]
	v_mfma_f32_16x16x32_bf16 v[74:77], v[160:163], v[218:221], v[74:77]
	v_mfma_f32_16x16x32_bf16 v[70:73], v[168:171], v[218:221], v[70:73]
	v_mfma_f32_16x16x32_bf16 v[98:101], v[164:167], v[188:191], v[98:101]
	v_mfma_f32_16x16x32_bf16 v[94:97], v[172:175], v[188:191], v[94:97]
	v_mfma_f32_16x16x32_bf16 v[90:93], v[164:167], v[196:199], v[90:93]
	v_mfma_f32_16x16x32_bf16 v[86:89], v[172:175], v[196:199], v[86:89]
	v_mfma_f32_16x16x32_bf16 v[82:85], v[164:167], v[214:217], v[82:85]
	v_mfma_f32_16x16x32_bf16 v[78:81], v[172:175], v[214:217], v[78:81]
	v_mfma_f32_16x16x32_bf16 v[74:77], v[164:167], v[222:225], v[74:77]
	v_mfma_f32_16x16x32_bf16 v[70:73], v[172:175], v[222:225], v[70:73]
	s_barrier
; #define PG8_STAGEX(b, gbase) do { if constexpr (XR) { if (lane < 16) __builtin_amdgcn_global_load_lds((const unsigned*)((const char*)(gbase) + voffX), (PG8_LAS unsigned*)(lds + XR_OFF + (b) * 2048 + wid * 256), 16, 0, 0); } } while (0)
; #define PG8_WAIT_LOOP() do { if constexpr (XR) PG8_WAIT_V(9); else PG8_WAIT_V(8); } while (0)
; #define PG8_STAGE(bufoff, gbase, voff) do { _Pragma("unroll") for (int _i = 0; _i < 2; ++_i) \
;         __builtin_amdgcn_global_load_lds((const unsigned*)((const char*)(gbase) + (voff)[_i]), (PG8_LAS unsigned*)(lds + (bufoff) + ldsw + _i * 8192), 16, 0, 0); } while (0)
; #define PG8_LDA(dst, b, h) do { _Pragma("unroll") for (int m = 0; m < 4; ++m) _Pragma("unroll") for (int k = 0; k < 2; ++k) dst[m][k] = *(const PG8_LAS bf16x8*)(lds + PG8_SA(b, h) + aoff + m * 2048 + k * 1024); } while (0)
; #define PG8_MMA(ai, bj, At, Bt) do { __builtin_amdgcn_s_setprio(1); _Pragma("unroll") for (int m = 0; m < 4; ++m) _Pragma("unroll") for (int n = 0; n < 2; ++n) _Pragma("unroll") for (int k = 0; k < 2; ++k) \
;         acc[ai][bj][m][n] = __builtin_amdgcn_mfma_f32_16x16x32_bf16(Bt[n][k], At[m][k], acc[ai][bj][m][n], 0, 0, 0); __builtin_amdgcn_s_setprio(0); } while (0)
; #define PG8_WAIT_L(n) asm volatile("s_waitcnt lgkmcnt(" #n ")" ::: "memory")
; #define PG8_BAR __builtin_amdgcn_s_barrier()
; #define PG8_SCHED __builtin_amdgcn_sched_barrier(0)
; template <class Epi, class Sched, bool ALIGN_EPI = false, bool SP2 = false, bool DRAIN = true, bool XR = false>
; __device__ __forceinline__ void gemm_phase(PG8_LAS unsigned char* lds, const Gemm g, const Sched& S, const Epi& E) {
;     ...
;             PG8_LDA(At, 1, 1); PG8_STAGE(PG8_SB(1, 0), b3, voffB); PG8_STAGE(PG8_SB(1, 1), b3 + hstep, voffB); PG8_STAGE(PG8_SA(1, 0), a3, voffA); PG8_STAGEX(1, x3);
;             PG8_WAIT_LOOP(); PG8_WAIT_L(0); PG8_BAR; PG8_MMA(1, 0, At, B0); PG8_MMA(1, 1, At, B1); PG8_BAR; PG8_SCHED;
	s_setprio 0
	s_add_i32 s0, s26, s44
	v_lshl_add_u64 v[8:9], v[180:181], 0, s[86:87]
	s_mov_b32 m0, s0
	ds_read_b128 v[176:179], v186 offset:49152
	ds_read_b128 v[188:191], v186 offset:50176
	ds_read_b128 v[192:195], v186 offset:51200
	ds_read_b128 v[196:199], v186 offset:52224
	ds_read_b128 v[200:203], v186 offset:53248
	ds_read_b128 v[214:217], v186 offset:54272
	ds_read_b128 v[218:221], v186 offset:55296
	ds_read_b128 v[222:225], v186 offset:56320
	global_load_lds_dwordx4 v[8:9], off
	v_lshl_add_u64 v[8:9], v[204:205], 0, s[86:87]
	s_add_i32 m0, s0, 0x2000
	s_add_i32 s0, s27, s44
	global_load_lds_dwordx4 v[8:9], off
	v_lshl_add_u64 v[8:9], v[206:207], 0, s[86:87]
	s_mov_b32 m0, s0
	s_nop 0
	global_load_lds_dwordx4 v[8:9], off
	v_lshl_add_u64 v[8:9], v[208:209], 0, s[86:87]
	s_add_i32 m0, s0, 0x2000
	s_nop 0
	global_load_lds_dwordx4 v[8:9], off
	v_lshl_add_u64 v[8:9], v[226:227], 0, s[86:87]
	s_mov_b32 m0, s67
	s_nop 0
	global_load_lds_dwordx4 v[8:9], off
	v_lshl_add_u64 v[8:9], v[228:229], 0, s[86:87]
	s_mov_b32 m0, s71
	s_nop 0
	global_load_lds_dwordx4 v[8:9], off
	s_waitcnt vmcnt(8)
	s_waitcnt lgkmcnt(0)
	s_setprio 1
	s_barrier
	v_mfma_f32_16x16x32_bf16 v[66:69], v[134:137], v[176:179], v[66:69]
	v_mfma_f32_16x16x32_bf16 v[62:65], v[152:155], v[176:179], v[62:65]
	v_mfma_f32_16x16x32_bf16 v[58:61], v[134:137], v[192:195], v[58:61]
	v_mfma_f32_16x16x32_bf16 v[54:57], v[152:155], v[192:195], v[54:57]
	v_mfma_f32_16x16x32_bf16 v[50:53], v[134:137], v[200:203], v[50:53]
	v_mfma_f32_16x16x32_bf16 v[46:49], v[152:155], v[200:203], v[46:49]
	v_mfma_f32_16x16x32_bf16 v[42:45], v[134:137], v[218:221], v[42:45]
	v_mfma_f32_16x16x32_bf16 v[38:41], v[152:155], v[218:221], v[38:41]
	v_mfma_f32_16x16x32_bf16 v[66:69], v[148:151], v[188:191], v[66:69]
	v_mfma_f32_16x16x32_bf16 v[62:65], v[156:159], v[188:191], v[62:65]
	v_mfma_f32_16x16x32_bf16 v[58:61], v[148:151], v[196:199], v[58:61]
	v_mfma_f32_16x16x32_bf16 v[54:57], v[156:159], v[196:199], v[54:57]
	v_mfma_f32_16x16x32_bf16 v[50:53], v[148:151], v[214:217], v[50:53]
	v_mfma_f32_16x16x32_bf16 v[46:49], v[156:159], v[214:217], v[46:49]
	v_mfma_f32_16x16x32_bf16 v[42:45], v[148:151], v[222:225], v[42:45]
	v_mfma_f32_16x16x32_bf16 v[38:41], v[156:159], v[222:225], v[38:41]
	v_mfma_f32_16x16x32_bf16 v[34:37], v[160:163], v[176:179], v[34:37]
	v_mfma_f32_16x16x32_bf16 v[30:33], v[168:171], v[176:179], v[30:33]
	v_mfma_f32_16x16x32_bf16 v[26:29], v[160:163], v[192:195], v[26:29]
	v_mfma_f32_16x16x32_bf16 v[22:25], v[168:171], v[192:195], v[22:25]
	v_mfma_f32_16x16x32_bf16 v[18:21], v[160:163], v[200:203], v[18:21]
	v_mfma_f32_16x16x32_bf16 v[14:17], v[168:171], v[200:203], v[14:17]
	v_mfma_f32_16x16x32_bf16 v[8:11], v[160:163], v[218:221], v[10:13]
	v_mfma_f32_16x16x32_bf16 v[4:7], v[168:171], v[218:221], v[4:7]
	v_mfma_f32_16x16x32_bf16 v[34:37], v[164:167], v[188:191], v[34:37]
	v_mfma_f32_16x16x32_bf16 v[30:33], v[172:175], v[188:191], v[30:33]
	v_mfma_f32_16x16x32_bf16 v[26:29], v[164:167], v[196:199], v[26:29]
	v_mfma_f32_16x16x32_bf16 v[22:25], v[172:175], v[196:199], v[22:25]
	v_mfma_f32_16x16x32_bf16 v[18:21], v[164:167], v[214:217], v[18:21]
	v_mfma_f32_16x16x32_bf16 v[14:17], v[172:175], v[214:217], v[14:17]
	v_mfma_f32_16x16x32_bf16 v[10:13], v[164:167], v[222:225], v[8:11]
	v_mfma_f32_16x16x32_bf16 v[6:9], v[172:175], v[222:225], v[4:7]
	s_barrier
	s_setprio 0
	s_add_i32 s25, s25, 2
	s_cmp_ge_i32 s25, s89
	s_cbranch_scc0 .LBB0_325

; #define PG8_STAGEX(b, gbase) do { if constexpr (XR) { if (lane < 16) __builtin_amdgcn_global_load_lds((const unsigned*)((const char*)(gbase) + voffX), (PG8_LAS unsigned*)(lds + XR_OFF + (b) * 2048 + wid * 256), 16, 0, 0); } } while (0)
; #define PG8_LDX(b) do { if constexpr (XR) { _Pragma("unroll") for (int k = 0; k < 2; ++k) Ax_[k] = *(const PG8_LAS bf16x8*)(lds + XR_OFF + (b) * 2048 + aoffx + k * 1024); } } while (0)
; #define PG8_MMAX() do { if constexpr (XR) { if (hasx) { __builtin_amdgcn_s_setprio(1); if (wr == 0) PG8_MMAX_(B0); else PG8_MMAX_(B1); __builtin_amdgcn_s_setprio(0); } } } while (0)
; #define PG8_WAIT_LOOP() do { if constexpr (XR) PG8_WAIT_V(9); else PG8_WAIT_V(8); } while (0)
; #define PG8_STAGE(bufoff, gbase, voff) do { _Pragma("unroll") for (int _i = 0; _i < 2; ++_i) \
;         __builtin_amdgcn_global_load_lds((const unsigned*)((const char*)(gbase) + (voff)[_i]), (PG8_LAS unsigned*)(lds + (bufoff) + ldsw + _i * 8192), 16, 0, 0); } while (0)
; #define PG8_WAIT_L(n) asm volatile("s_waitcnt lgkmcnt(" #n ")" ::: "memory")
; template <class Epi, class Sched, bool ALIGN_EPI = false, bool SP2 = false, bool DRAIN = true, bool XR = false>
; __device__ __forceinline__ void gemm_phase(PG8_LAS unsigned char* lds, const Gemm g, const Sched& S, const Epi& E) {
;     ...
;         for (int t = 0; t < nt; t += 2) {
;             if constexpr (Epi::MIDSCALE) { if (t == (nt >> 1)) E.midscale(acc, cur, wr, fr); }
;             const bool last = (t == nt - 2);
;             const char* a1 = cA + PG8_KOA(t) + kstep;
;             const char* a2 = last ? nA + ka0 : cA + PG8_KOA(t + 2); const char* b2 = last ? nB + kb0 : cB + PG8_KOB(t + 2);
;             const char* x2 = XR ? (last ? nX + kx0 : cX + PG8_KOX(t + 2)) : nullptr; const char* x3 = XR ? x2 + kstep : nullptr;
;             const char* a3 = a2 + kstep; const char* b3 = b2 + kstep;
;             if (last && has_next) S.a_ready(nxt);
;             if constexpr (SP2) {
;             PG8_LDB(B0, 0, 0); PG8_LDB(B1, 0, 1); PG8_SCHED; PG8_LDA(At, 0, 0); PG8_LDX(0); PG8_STAGE(PG8_SA(1, 1), a1 + hstepA, voffA);
;             PG8_WAIT_LOOP(); PG8_WAIT_L(0); PG8_BAR; PG8_MMA(0, 0, At, B0); PG8_MMA(0, 1, At, B1); PG8_MMAX(); PG8_BAR; PG8_SCHED;
;             PG8_LDA(At, 0, 1); PG8_STAGE(PG8_SB(0, 0), b2, voffB); PG8_STAGE(PG8_SB(0, 1), b2 + hstep, voffB); PG8_STAGE(PG8_SA(0, 0), a2, voffA); PG8_STAGEX(0, x2);
.LBB0_1020:
	s_add_i32 s4, s72, -2
	s_and_b32 s73, s4, s61
	s_lshr_b32 s84, s73, 2
	s_lshl_b32 s36, s73, 7
	s_lshl_b64 s[4:5], s[84:85], 9
	s_and_b32 s36, s36, 0x100
	s_add_u32 s4, s44, s4
	s_addc_u32 s5, s45, s5
	s_add_u32 s73, s4, s36
	s_addc_u32 s77, s5, 0
	s_and_b32 s4, s72, s61
	s_lshr_b32 s84, s4, 2
	s_lshl_b32 s5, s4, 7
	s_lshl_b64 s[74:75], s[84:85], 9
	s_and_b32 s5, s5, 0x100
	s_add_u32 s36, s44, s74
	s_addc_u32 s74, s45, s75
	s_add_u32 s36, s36, s5
	s_mov_b32 s5, s85
	s_addc_u32 s74, s74, 0
	s_lshl_b64 s[4:5], s[4:5], 7
	s_add_u32 s76, s42, s4
	s_addc_u32 s75, s43, s5
	s_add_i32 s78, 0, 0x10000
	s_cmp_eq_u32 s60, s72
	s_cselect_b32 s5, s35, s74
	s_cselect_b32 s4, s34, s36
	s_cselect_b32 s75, s41, s75
	s_cselect_b32 s74, s40, s76
	s_add_i32 s36, 0, 0x14000
	v_add_u32_e32 v104, s78, v176
	v_add_u32_e32 v168, s36, v176
	ds_read_b128 v[84:87], v104
	ds_read_b128 v[88:91], v104 offset:1024
	ds_read_b128 v[96:99], v104 offset:2048
	ds_read_b128 v[104:107], v104 offset:3072
	ds_read_b128 v[148:151], v168
	ds_read_b128 v[152:155], v168 offset:1024
	ds_read_b128 v[156:159], v168 offset:2048
	ds_read_b128 v[168:171], v168 offset:3072
	s_add_u32 s76, s73, s18
	s_addc_u32 s77, s77, s19
	v_lshl_add_u64 v[204:205], s[76:77], 0, v[162:163]
	v_lshl_add_u64 v[204:205], v[204:205], 0, s[86:87]
	s_add_i32 m0, s54, 0xc000
	ds_read_b128 v[172:175], v178
	ds_read_b128 v[180:183], v178 offset:1024
	ds_read_b128 v[184:187], v178 offset:2048
	ds_read_b128 v[188:191], v178 offset:3072
	ds_read_b128 v[192:195], v178 offset:4096
	ds_read_b128 v[196:199], v178 offset:5120
	ds_read_b128 v[200:203], v178 offset:6144
	ds_read_b128 v[214:217], v178 offset:7168
	global_load_lds_dwordx4 v[204:205], off
	v_lshl_add_u64 v[204:205], s[76:77], 0, v[164:165]
	v_lshl_add_u64 v[204:205], v[204:205], 0, s[86:87]
	s_add_i32 m0, s54, 0xe000
	s_nop 0
	global_load_lds_dwordx4 v[204:205], off
	s_waitcnt vmcnt(8)
	s_waitcnt lgkmcnt(0)
	s_setprio 1
	s_barrier
	v_mfma_f32_16x16x32_bf16 v[144:147], v[84:87], v[172:175], v[144:147]
	v_mfma_f32_16x16x32_bf16 v[140:143], v[96:99], v[172:175], v[140:143]
	v_mfma_f32_16x16x32_bf16 v[128:131], v[84:87], v[184:187], v[128:131]
	v_mfma_f32_16x16x32_bf16 v[124:127], v[96:99], v[184:187], v[124:127]
	v_mfma_f32_16x16x32_bf16 v[112:115], v[84:87], v[192:195], v[112:115]
	v_mfma_f32_16x16x32_bf16 v[108:111], v[96:99], v[192:195], v[108:111]
	v_mfma_f32_16x16x32_bf16 v[80:83], v[84:87], v[200:203], v[80:83]
	v_mfma_f32_16x16x32_bf16 v[76:79], v[96:99], v[200:203], v[76:79]
	v_mfma_f32_16x16x32_bf16 v[144:147], v[88:91], v[180:183], v[144:147]
	v_mfma_f32_16x16x32_bf16 v[140:143], v[104:107], v[180:183], v[140:143]
	v_mfma_f32_16x16x32_bf16 v[128:131], v[88:91], v[188:191], v[128:131]
	v_mfma_f32_16x16x32_bf16 v[124:127], v[104:107], v[188:191], v[124:127]
	v_mfma_f32_16x16x32_bf16 v[112:115], v[88:91], v[196:199], v[112:115]
	v_mfma_f32_16x16x32_bf16 v[108:111], v[104:107], v[196:199], v[108:111]
	v_mfma_f32_16x16x32_bf16 v[80:83], v[88:91], v[214:217], v[80:83]
	v_mfma_f32_16x16x32_bf16 v[76:79], v[104:107], v[214:217], v[76:79]
	v_mfma_f32_16x16x32_bf16 v[136:139], v[148:151], v[172:175], v[136:139]
	v_mfma_f32_16x16x32_bf16 v[132:135], v[156:159], v[172:175], v[132:135]
	v_mfma_f32_16x16x32_bf16 v[120:123], v[148:151], v[184:187], v[120:123]
	v_mfma_f32_16x16x32_bf16 v[116:119], v[156:159], v[184:187], v[116:119]
	v_mfma_f32_16x16x32_bf16 v[100:103], v[148:151], v[192:195], v[100:103]
	v_mfma_f32_16x16x32_bf16 v[92:95], v[156:159], v[192:195], v[92:95]
	v_mfma_f32_16x16x32_bf16 v[72:75], v[148:151], v[200:203], v[72:75]
	v_mfma_f32_16x16x32_bf16 v[68:71], v[156:159], v[200:203], v[68:71]
	v_mfma_f32_16x16x32_bf16 v[136:139], v[152:155], v[180:183], v[136:139]
	v_mfma_f32_16x16x32_bf16 v[132:135], v[168:171], v[180:183], v[132:135]
	v_mfma_f32_16x16x32_bf16 v[120:123], v[152:155], v[188:191], v[120:123]
	v_mfma_f32_16x16x32_bf16 v[116:119], v[168:171], v[188:191], v[116:119]
	v_mfma_f32_16x16x32_bf16 v[100:103], v[152:155], v[196:199], v[100:103]
	v_mfma_f32_16x16x32_bf16 v[92:95], v[168:171], v[196:199], v[92:95]
	v_mfma_f32_16x16x32_bf16 v[72:75], v[152:155], v[214:217], v[72:75]
	v_mfma_f32_16x16x32_bf16 v[68:71], v[168:171], v[214:217], v[68:71]
	s_barrier
	s_setprio 0
	s_add_i32 s73, s78, s51
	v_lshl_add_u64 v[204:205], s[74:75], 0, v[2:3]
	s_mov_b32 m0, s73
	ds_read_b128 v[172:175], v178 offset:16384
	ds_read_b128 v[180:183], v178 offset:17408
	ds_read_b128 v[184:187], v178 offset:18432
	ds_read_b128 v[188:191], v178 offset:19456
	ds_read_b128 v[192:195], v178 offset:20480
	ds_read_b128 v[196:199], v178 offset:21504
	ds_read_b128 v[200:203], v178 offset:22528
	ds_read_b128 v[214:217], v178 offset:23552
	global_load_lds_dwordx4 v[204:205], off
	s_add_i32 m0, s73, 0x2000
	v_lshl_add_u64 v[206:207], s[74:75], 0, v[166:167]
	s_add_u32 s74, s74, s18
	s_addc_u32 s75, s75, s19
	s_add_i32 s36, s36, s51
	global_load_lds_dwordx4 v[206:207], off
	v_lshl_add_u64 v[208:209], s[74:75], 0, v[2:3]
	s_mov_b32 m0, s36
	v_lshl_add_u64 v[212:213], s[74:75], 0, v[166:167]
	global_load_lds_dwordx4 v[208:209], off
	s_add_i32 m0, s36, 0x2000
	v_lshl_add_u64 v[218:219], s[4:5], 0, v[162:163]
	global_load_lds_dwordx4 v[212:213], off
	s_mov_b32 m0, s54
	v_lshl_add_u64 v[220:221], s[4:5], 0, v[164:165]
	global_load_lds_dwordx4 v[218:219], off
	s_mov_b32 m0, s55
	s_nop 0
	global_load_lds_dwordx4 v[220:221], off
	s_waitcnt vmcnt(8)
	s_waitcnt lgkmcnt(0)
	s_setprio 1
	s_barrier
; #define PG8_LDX(b) do { if constexpr (XR) { _Pragma("unroll") for (int k = 0; k < 2; ++k) Ax_[k] = *(const PG8_LAS bf16x8*)(lds + XR_OFF + (b) * 2048 + aoffx + k * 1024); } } while (0)
; #define PG8_MMAX() do { if constexpr (XR) { if (hasx) { __builtin_amdgcn_s_setprio(1); if (wr == 0) PG8_MMAX_(B0); else PG8_MMAX_(B1); __builtin_amdgcn_s_setprio(0); } } } while (0)
; #define PG8_WAIT_LOOP() do { if constexpr (XR) PG8_WAIT_V(9); else PG8_WAIT_V(8); } while (0)
; #define PG8_STAGE(bufoff, gbase, voff) do { _Pragma("unroll") for (int _i = 0; _i < 2; ++_i) \
;         __builtin_amdgcn_global_load_lds((const unsigned*)((const char*)(gbase) + (voff)[_i]), (PG8_LAS unsigned*)(lds + (bufoff) + ldsw + _i * 8192), 16, 0, 0); } while (0)
; #define PG8_LDA(dst, b, h) do { _Pragma("unroll") for (int m = 0; m < 4; ++m) _Pragma("unroll") for (int k = 0; k < 2; ++k) dst[m][k] = *(const PG8_LAS bf16x8*)(lds + PG8_SA(b, h) + aoff + m * 2048 + k * 1024); } while (0)
; #define PG8_LDB(dst, b, h) do { _Pragma("unroll") for (int n = 0; n < 2; ++n) _Pragma("unroll") for (int k = 0; k < 2; ++k) dst[n][k] = *(const PG8_LAS bf16x8*)(lds + PG8_SB(b, h) + boff + n * 2048 + k * 1024); } while (0)
; #define PG8_MMA(ai, bj, At, Bt) do { __builtin_amdgcn_s_setprio(1); _Pragma("unroll") for (int m = 0; m < 4; ++m) _Pragma("unroll") for (int n = 0; n < 2; ++n) _Pragma("unroll") for (int k = 0; k < 2; ++k) \
;         acc[ai][bj][m][n] = __builtin_amdgcn_mfma_f32_16x16x32_bf16(Bt[n][k], At[m][k], acc[ai][bj][m][n], 0, 0, 0); __builtin_amdgcn_s_setprio(0); } while (0)
; #define PG8_WAIT_L(n) asm volatile("s_waitcnt lgkmcnt(" #n ")" ::: "memory")
; #define PG8_BAR __builtin_amdgcn_s_barrier()
; #define PG8_SCHED __builtin_amdgcn_sched_barrier(0)
; template <class Epi, class Sched, bool ALIGN_EPI = false, bool SP2 = false, bool DRAIN = true, bool XR = false>
; __device__ __forceinline__ void gemm_phase(PG8_LAS unsigned char* lds, const Gemm g, const Sched& S, const Epi& E) {
;     ...
;             PG8_WAIT_LOOP(); PG8_WAIT_L(0); PG8_BAR; PG8_MMA(1, 0, At, B0); PG8_MMA(1, 1, At, B1); PG8_BAR; PG8_SCHED;
;             PG8_LDB(B0, 1, 0); PG8_LDB(B1, 1, 1); PG8_SCHED; PG8_LDA(At, 1, 0); PG8_LDX(1); PG8_STAGE(PG8_SA(0, 1), a2 + hstepA, voffA);
;             PG8_WAIT_LOOP(); PG8_WAIT_L(0); PG8_BAR; PG8_MMA(0, 0, At, B0); PG8_MMA(0, 1, At, B1); PG8_MMAX(); PG8_BAR; PG8_SCHED;
	v_mfma_f32_16x16x32_bf16 v[64:67], v[84:87], v[172:175], v[64:67]
	v_mfma_f32_16x16x32_bf16 v[60:63], v[96:99], v[172:175], v[60:63]
	v_mfma_f32_16x16x32_bf16 v[48:51], v[84:87], v[184:187], v[48:51]
	v_mfma_f32_16x16x32_bf16 v[44:47], v[96:99], v[184:187], v[44:47]
	v_mfma_f32_16x16x32_bf16 v[32:35], v[84:87], v[192:195], v[32:35]
	v_mfma_f32_16x16x32_bf16 v[28:31], v[96:99], v[192:195], v[28:31]
	v_mfma_f32_16x16x32_bf16 v[16:19], v[84:87], v[200:203], v[16:19]
	v_mfma_f32_16x16x32_bf16 v[12:15], v[96:99], v[200:203], v[12:15]
	v_mfma_f32_16x16x32_bf16 v[64:67], v[88:91], v[180:183], v[64:67]
	v_mfma_f32_16x16x32_bf16 v[60:63], v[104:107], v[180:183], v[60:63]
	v_mfma_f32_16x16x32_bf16 v[48:51], v[88:91], v[188:191], v[48:51]
	v_mfma_f32_16x16x32_bf16 v[44:47], v[104:107], v[188:191], v[44:47]
	v_mfma_f32_16x16x32_bf16 v[32:35], v[88:91], v[196:199], v[32:35]
	v_mfma_f32_16x16x32_bf16 v[28:31], v[104:107], v[196:199], v[28:31]
	v_mfma_f32_16x16x32_bf16 v[16:19], v[88:91], v[214:217], v[16:19]
	v_mfma_f32_16x16x32_bf16 v[12:15], v[104:107], v[214:217], v[12:15]
	v_mfma_f32_16x16x32_bf16 v[56:59], v[148:151], v[172:175], v[56:59]
	v_mfma_f32_16x16x32_bf16 v[52:55], v[156:159], v[172:175], v[52:55]
	v_mfma_f32_16x16x32_bf16 v[40:43], v[148:151], v[184:187], v[40:43]
	v_mfma_f32_16x16x32_bf16 v[36:39], v[156:159], v[184:187], v[36:39]
	v_mfma_f32_16x16x32_bf16 v[24:27], v[148:151], v[192:195], v[24:27]
	v_mfma_f32_16x16x32_bf16 v[20:23], v[156:159], v[192:195], v[20:23]
	v_mfma_f32_16x16x32_bf16 v[8:11], v[148:151], v[200:203], v[8:11]
	v_mfma_f32_16x16x32_bf16 v[4:7], v[156:159], v[200:203], v[4:7]
	v_mfma_f32_16x16x32_bf16 v[56:59], v[152:155], v[180:183], v[56:59]
	v_mfma_f32_16x16x32_bf16 v[52:55], v[168:171], v[180:183], v[52:55]
	v_mfma_f32_16x16x32_bf16 v[40:43], v[152:155], v[188:191], v[40:43]
	v_mfma_f32_16x16x32_bf16 v[36:39], v[168:171], v[188:191], v[36:39]
	v_mfma_f32_16x16x32_bf16 v[24:27], v[152:155], v[196:199], v[24:27]
	v_mfma_f32_16x16x32_bf16 v[20:23], v[168:171], v[196:199], v[20:23]
	v_mfma_f32_16x16x32_bf16 v[8:11], v[152:155], v[214:217], v[8:11]
	v_mfma_f32_16x16x32_bf16 v[4:7], v[168:171], v[214:217], v[4:7]
	s_barrier
	s_setprio 0
	s_add_i32 s36, 0, 0x18000
	s_add_i32 s73, 0, 0x1c000
	v_add_u32_e32 v104, s36, v176
	v_add_u32_e32 v168, s73, v176
	ds_read_b128 v[84:87], v104
	ds_read_b128 v[88:91], v104 offset:1024
	ds_read_b128 v[96:99], v104 offset:2048
	ds_read_b128 v[104:107], v104 offset:3072
	ds_read_b128 v[148:151], v168
	ds_read_b128 v[152:155], v168 offset:1024
	ds_read_b128 v[156:159], v168 offset:2048
	ds_read_b128 v[168:171], v168 offset:3072
	s_add_u32 s4, s4, s18
	s_addc_u32 s5, s5, s19
	s_mov_b32 m0, s56
	v_lshl_add_u64 v[222:223], s[4:5], 0, v[162:163]
	ds_read_b128 v[172:175], v178 offset:32768
	ds_read_b128 v[180:183], v178 offset:33792
	ds_read_b128 v[184:187], v178 offset:34816
	ds_read_b128 v[188:191], v178 offset:35840
	ds_read_b128 v[192:195], v178 offset:36864
	ds_read_b128 v[196:199], v178 offset:37888
	ds_read_b128 v[200:203], v178 offset:38912
	ds_read_b128 v[214:217], v178 offset:39936
	global_load_lds_dwordx4 v[222:223], off
	v_lshl_add_u64 v[222:223], s[4:5], 0, v[164:165]
	s_mov_b32 m0, s57
	s_nop 0
	global_load_lds_dwordx4 v[222:223], off
	s_waitcnt vmcnt(8)
	s_waitcnt lgkmcnt(0)
	s_setprio 1
	s_barrier
	v_mfma_f32_16x16x32_bf16 v[144:147], v[84:87], v[172:175], v[144:147]
	v_mfma_f32_16x16x32_bf16 v[140:143], v[96:99], v[172:175], v[140:143]
	v_mfma_f32_16x16x32_bf16 v[128:131], v[84:87], v[184:187], v[128:131]
	v_mfma_f32_16x16x32_bf16 v[124:127], v[96:99], v[184:187], v[124:127]
	v_mfma_f32_16x16x32_bf16 v[112:115], v[84:87], v[192:195], v[112:115]
	v_mfma_f32_16x16x32_bf16 v[108:111], v[96:99], v[192:195], v[108:111]
	v_mfma_f32_16x16x32_bf16 v[80:83], v[84:87], v[200:203], v[80:83]
	v_mfma_f32_16x16x32_bf16 v[76:79], v[96:99], v[200:203], v[76:79]
	v_mfma_f32_16x16x32_bf16 v[144:147], v[88:91], v[180:183], v[144:147]
	v_mfma_f32_16x16x32_bf16 v[140:143], v[104:107], v[180:183], v[140:143]
	v_mfma_f32_16x16x32_bf16 v[128:131], v[88:91], v[188:191], v[128:131]
	v_mfma_f32_16x16x32_bf16 v[124:127], v[104:107], v[188:191], v[124:127]
	v_mfma_f32_16x16x32_bf16 v[112:115], v[88:91], v[196:199], v[112:115]
	v_mfma_f32_16x16x32_bf16 v[108:111], v[104:107], v[196:199], v[108:111]
	v_mfma_f32_16x16x32_bf16 v[80:83], v[88:91], v[214:217], v[80:83]
	v_mfma_f32_16x16x32_bf16 v[76:79], v[104:107], v[214:217], v[76:79]
	v_mfma_f32_16x16x32_bf16 v[136:139], v[148:151], v[172:175], v[136:139]
	v_mfma_f32_16x16x32_bf16 v[132:135], v[156:159], v[172:175], v[132:135]
	v_mfma_f32_16x16x32_bf16 v[120:123], v[148:151], v[184:187], v[120:123]
	v_mfma_f32_16x16x32_bf16 v[116:119], v[156:159], v[184:187], v[116:119]
	v_mfma_f32_16x16x32_bf16 v[100:103], v[148:151], v[192:195], v[100:103]
	v_mfma_f32_16x16x32_bf16 v[92:95], v[156:159], v[192:195], v[92:95]
	v_mfma_f32_16x16x32_bf16 v[72:75], v[148:151], v[200:203], v[72:75]
	v_mfma_f32_16x16x32_bf16 v[68:71], v[156:159], v[200:203], v[68:71]
	v_mfma_f32_16x16x32_bf16 v[136:139], v[152:155], v[180:183], v[136:139]
	v_mfma_f32_16x16x32_bf16 v[132:135], v[168:171], v[180:183], v[132:135]
	v_mfma_f32_16x16x32_bf16 v[120:123], v[152:155], v[188:191], v[120:123]
	v_mfma_f32_16x16x32_bf16 v[116:119], v[168:171], v[188:191], v[116:119]
	v_mfma_f32_16x16x32_bf16 v[100:103], v[152:155], v[196:199], v[100:103]
	v_mfma_f32_16x16x32_bf16 v[92:95], v[168:171], v[196:199], v[92:95]
	v_mfma_f32_16x16x32_bf16 v[72:75], v[152:155], v[214:217], v[72:75]
	v_mfma_f32_16x16x32_bf16 v[68:71], v[168:171], v[214:217], v[68:71]
	s_barrier
; #define PG8_STAGEX(b, gbase) do { if constexpr (XR) { if (lane < 16) __builtin_amdgcn_global_load_lds((const unsigned*)((const char*)(gbase) + voffX), (PG8_LAS unsigned*)(lds + XR_OFF + (b) * 2048 + wid * 256), 16, 0, 0); } } while (0)
; #define PG8_WAIT_LOOP() do { if constexpr (XR) PG8_WAIT_V(9); else PG8_WAIT_V(8); } while (0)
; #define PG8_STAGE(bufoff, gbase, voff) do { _Pragma("unroll") for (int _i = 0; _i < 2; ++_i) \
;         __builtin_amdgcn_global_load_lds((const unsigned*)((const char*)(gbase) + (voff)[_i]), (PG8_LAS unsigned*)(lds + (bufoff) + ldsw + _i * 8192), 16, 0, 0); } while (0)
; #define PG8_LDA(dst, b, h) do { _Pragma("unroll") for (int m = 0; m < 4; ++m) _Pragma("unroll") for (int k = 0; k < 2; ++k) dst[m][k] = *(const PG8_LAS bf16x8*)(lds + PG8_SA(b, h) + aoff + m * 2048 + k * 1024); } while (0)
; #define PG8_MMA(ai, bj, At, Bt) do { __builtin_amdgcn_s_setprio(1); _Pragma("unroll") for (int m = 0; m < 4; ++m) _Pragma("unroll") for (int n = 0; n < 2; ++n) _Pragma("unroll") for (int k = 0; k < 2; ++k) \
;         acc[ai][bj][m][n] = __builtin_amdgcn_mfma_f32_16x16x32_bf16(Bt[n][k], At[m][k], acc[ai][bj][m][n], 0, 0, 0); __builtin_amdgcn_s_setprio(0); } while (0)
; #define PG8_WAIT_L(n) asm volatile("s_waitcnt lgkmcnt(" #n ")" ::: "memory")
; #define PG8_BAR __builtin_amdgcn_s_barrier()
; #define PG8_SCHED __builtin_amdgcn_sched_barrier(0)
; template <class Epi, class Sched, bool ALIGN_EPI = false, bool SP2 = false, bool DRAIN = true, bool XR = false>
; __device__ __forceinline__ void gemm_phase(PG8_LAS unsigned char* lds, const Gemm g, const Sched& S, const Epi& E) {
;     ...
;             PG8_LDA(At, 1, 1); PG8_STAGE(PG8_SB(1, 0), b3, voffB); PG8_STAGE(PG8_SB(1, 1), b3 + hstep, voffB); PG8_STAGE(PG8_SA(1, 0), a3, voffA); PG8_STAGEX(1, x3);
;             PG8_WAIT_LOOP(); PG8_WAIT_L(0); PG8_BAR; PG8_MMA(1, 0, At, B0); PG8_MMA(1, 1, At, B1); PG8_BAR; PG8_SCHED;
	s_setprio 0
	s_add_i32 s4, s36, s51
	v_lshl_add_u64 v[204:205], v[204:205], 0, s[86:87]
	s_mov_b32 m0, s4
	ds_read_b128 v[172:175], v178 offset:49152
	ds_read_b128 v[180:183], v178 offset:50176
	ds_read_b128 v[184:187], v178 offset:51200
	ds_read_b128 v[188:191], v178 offset:52224
	ds_read_b128 v[192:195], v178 offset:53248
	ds_read_b128 v[196:199], v178 offset:54272
	ds_read_b128 v[200:203], v178 offset:55296
	ds_read_b128 v[214:217], v178 offset:56320
	global_load_lds_dwordx4 v[204:205], off
	v_lshl_add_u64 v[204:205], v[206:207], 0, s[86:87]
	s_add_i32 m0, s4, 0x2000
	s_add_i32 s4, s73, s51
	global_load_lds_dwordx4 v[204:205], off
	v_lshl_add_u64 v[204:205], v[208:209], 0, s[86:87]
	s_mov_b32 m0, s4
	s_nop 0
	global_load_lds_dwordx4 v[204:205], off
	v_lshl_add_u64 v[204:205], v[212:213], 0, s[86:87]
	s_add_i32 m0, s4, 0x2000
	s_nop 0
	global_load_lds_dwordx4 v[204:205], off
	v_lshl_add_u64 v[204:205], v[218:219], 0, s[86:87]
	s_mov_b32 m0, s62
	s_nop 0
	global_load_lds_dwordx4 v[204:205], off
	v_lshl_add_u64 v[204:205], v[220:221], 0, s[86:87]
	s_mov_b32 m0, s63
	s_nop 0
	global_load_lds_dwordx4 v[204:205], off
	s_waitcnt vmcnt(8)
	s_waitcnt lgkmcnt(0)
	s_setprio 1
	s_barrier
	v_mfma_f32_16x16x32_bf16 v[64:67], v[84:87], v[172:175], v[64:67]
	v_mfma_f32_16x16x32_bf16 v[60:63], v[96:99], v[172:175], v[60:63]
	v_mfma_f32_16x16x32_bf16 v[48:51], v[84:87], v[184:187], v[48:51]
	v_mfma_f32_16x16x32_bf16 v[44:47], v[96:99], v[184:187], v[44:47]
	v_mfma_f32_16x16x32_bf16 v[32:35], v[84:87], v[192:195], v[32:35]
	v_mfma_f32_16x16x32_bf16 v[28:31], v[96:99], v[192:195], v[28:31]
	v_mfma_f32_16x16x32_bf16 v[16:19], v[84:87], v[200:203], v[16:19]
	v_mfma_f32_16x16x32_bf16 v[12:15], v[96:99], v[200:203], v[12:15]
	v_mfma_f32_16x16x32_bf16 v[64:67], v[88:91], v[180:183], v[64:67]
	v_mfma_f32_16x16x32_bf16 v[60:63], v[104:107], v[180:183], v[60:63]
	v_mfma_f32_16x16x32_bf16 v[48:51], v[88:91], v[188:191], v[48:51]
	v_mfma_f32_16x16x32_bf16 v[44:47], v[104:107], v[188:191], v[44:47]
	v_mfma_f32_16x16x32_bf16 v[32:35], v[88:91], v[196:199], v[32:35]
	v_mfma_f32_16x16x32_bf16 v[28:31], v[104:107], v[196:199], v[28:31]
	v_mfma_f32_16x16x32_bf16 v[16:19], v[88:91], v[214:217], v[16:19]
	v_mfma_f32_16x16x32_bf16 v[12:15], v[104:107], v[214:217], v[12:15]
	v_mfma_f32_16x16x32_bf16 v[56:59], v[148:151], v[172:175], v[56:59]
	v_mfma_f32_16x16x32_bf16 v[52:55], v[156:159], v[172:175], v[52:55]
	v_mfma_f32_16x16x32_bf16 v[40:43], v[148:151], v[184:187], v[40:43]
	v_mfma_f32_16x16x32_bf16 v[36:39], v[156:159], v[184:187], v[36:39]
	v_mfma_f32_16x16x32_bf16 v[24:27], v[148:151], v[192:195], v[24:27]
	v_mfma_f32_16x16x32_bf16 v[20:23], v[156:159], v[192:195], v[20:23]
	v_mfma_f32_16x16x32_bf16 v[8:11], v[148:151], v[200:203], v[8:11]
	v_mfma_f32_16x16x32_bf16 v[4:7], v[156:159], v[200:203], v[4:7]
	v_mfma_f32_16x16x32_bf16 v[56:59], v[152:155], v[180:183], v[56:59]
	v_mfma_f32_16x16x32_bf16 v[52:55], v[168:171], v[180:183], v[52:55]
	v_mfma_f32_16x16x32_bf16 v[40:43], v[152:155], v[188:191], v[40:43]
	v_mfma_f32_16x16x32_bf16 v[36:39], v[168:171], v[188:191], v[36:39]
	v_mfma_f32_16x16x32_bf16 v[24:27], v[152:155], v[196:199], v[24:27]
	v_mfma_f32_16x16x32_bf16 v[20:23], v[168:171], v[196:199], v[20:23]
	v_mfma_f32_16x16x32_bf16 v[8:11], v[152:155], v[214:217], v[8:11]
	v_mfma_f32_16x16x32_bf16 v[4:7], v[168:171], v[214:217], v[4:7]
	s_barrier
	s_setprio 0
	s_add_i32 s4, s72, 2
	s_cmp_ge_i32 s72, s60
	s_mov_b32 s72, s4
	s_cbranch_scc0 .LBB0_1020

; #define PG8_LDX(b) do { if constexpr (XR) { _Pragma("unroll") for (int k = 0; k < 2; ++k) Ax_[k] = *(const PG8_LAS bf16x8*)(lds + XR_OFF + (b) * 2048 + aoffx + k * 1024); } } while (0)
; #define PG8_MMAX() do { if constexpr (XR) { if (hasx) { __builtin_amdgcn_s_setprio(1); if (wr == 0) PG8_MMAX_(B0); else PG8_MMAX_(B1); __builtin_amdgcn_s_setprio(0); } } } while (0)
; #define PG8_WAIT_LOOP() do { if constexpr (XR) PG8_WAIT_V(9); else PG8_WAIT_V(8); } while (0)
; #define PG8_STAGE(bufoff, gbase, voff) do { _Pragma("unroll") for (int _i = 0; _i < 2; ++_i) \
;         __builtin_amdgcn_global_load_lds((const unsigned*)((const char*)(gbase) + (voff)[_i]), (PG8_LAS unsigned*)(lds + (bufoff) + ldsw + _i * 8192), 16, 0, 0); } while (0)
; #define PG8_LDA(dst, b, h) do { _Pragma("unroll") for (int m = 0; m < 4; ++m) _Pragma("unroll") for (int k = 0; k < 2; ++k) dst[m][k] = *(const PG8_LAS bf16x8*)(lds + PG8_SA(b, h) + aoff + m * 2048 + k * 1024); } while (0)
; #define PG8_LDB(dst, b, h) do { _Pragma("unroll") for (int n = 0; n < 2; ++n) _Pragma("unroll") for (int k = 0; k < 2; ++k) dst[n][k] = *(const PG8_LAS bf16x8*)(lds + PG8_SB(b, h) + boff + n * 2048 + k * 1024); } while (0)
; #define PG8_MMA(ai, bj, At, Bt) do { __builtin_amdgcn_s_setprio(1); _Pragma("unroll") for (int m = 0; m < 4; ++m) _Pragma("unroll") for (int n = 0; n < 2; ++n) _Pragma("unroll") for (int k = 0; k < 2; ++k) \
;         acc[ai][bj][m][n] = __builtin_amdgcn_mfma_f32_16x16x32_bf16(Bt[n][k], At[m][k], acc[ai][bj][m][n], 0, 0, 0); __builtin_amdgcn_s_setprio(0); } while (0)
; #define PG8_WAIT_L(n) asm volatile("s_waitcnt lgkmcnt(" #n ")" ::: "memory")
; #define PG8_BAR __builtin_amdgcn_s_barrier()
; #define PG8_SCHED __builtin_amdgcn_sched_barrier(0)
; template <class Epi, class Sched, bool ALIGN_EPI = false, bool SP2 = false, bool DRAIN = true, bool XR = false>
; __device__ __forceinline__ void gemm_phase(PG8_LAS unsigned char* lds, const Gemm g, const Sched& S, const Epi& E) {
;     ...
;             PG8_LDB(B0, 0, 0); PG8_LDB(B1, 0, 1); PG8_SCHED; PG8_LDA(At, 0, 0); PG8_LDX(0); PG8_STAGE(PG8_SA(1, 1), a1 + hstepA, voffA);
;             PG8_WAIT_LOOP(); PG8_WAIT_L(0); PG8_BAR; PG8_MMA(0, 0, At, B0); PG8_MMA(0, 1, At, B1); PG8_MMAX(); PG8_BAR; PG8_SCHED;
.LBB0_1220:
	v_add_u32_e32 v4, 0x10000, v250
	ds_read_b128 v[158:161], v4
	ds_read_b128 v[162:165], v4 offset:1024
	ds_read_b128 v[166:169], v4 offset:2048
	ds_read_b128 v[170:173], v4 offset:3072
	v_add_u32_e32 v4, 0x14000, v250
	s_and_b32 s8, s50, s82
	ds_read_b128 v[142:145], v4
	ds_read_b128 v[146:149], v4 offset:1024
	ds_read_b128 v[150:153], v4 offset:2048
	ds_read_b128 v[154:157], v4 offset:3072
	s_lshr_b32 s84, s8, 2
	s_lshl_b32 s8, s8, 7
	s_lshl_b64 s[6:7], s[84:85], 9
	s_and_b32 s8, s8, 0x100
	s_add_u32 s6, s18, s6
	s_addc_u32 s7, s19, s7
	s_add_u32 s6, s6, s8
	s_addc_u32 s7, s7, 0
	s_add_u32 s6, s6, s10
	v_add_u32_e32 v4, 0x22400, v240
	s_addc_u32 s7, s7, s11
	ds_read_b128 v[182:185], v251
	ds_read_b128 v[186:189], v251 offset:1024
	ds_read_b128 v[190:193], v251 offset:2048
	ds_read_b128 v[194:197], v251 offset:3072
	ds_read_b128 v[198:201], v251 offset:4096
	ds_read_b128 v[202:205], v251 offset:5120
	ds_read_b128 v[224:227], v251 offset:6144
	ds_read_b128 v[228:231], v251 offset:7168
	ds_read_b128 v[174:177], v4
	ds_read_b128 v[178:181], v4 offset:1024
	v_lshl_add_u64 v[4:5], s[6:7], 0, v[214:215]
	v_lshl_add_u64 v[4:5], v[4:5], 0, s[86:87]
	s_add_i32 m0, s64, 0xc000
	s_nop 0
	global_load_lds_dwordx4 v[4:5], off
	v_lshl_add_u64 v[4:5], s[6:7], 0, v[218:219]
	v_lshl_add_u64 v[4:5], v[4:5], 0, s[86:87]
	s_add_i32 m0, s64, 0xe000
	s_nop 0
	global_load_lds_dwordx4 v[4:5], off
	s_waitcnt vmcnt(9)
	s_waitcnt lgkmcnt(0)
	s_setprio 1
	s_barrier
	v_mfma_f32_16x16x32_bf16 v[138:141], v[158:161], v[182:185], v[138:141]
	v_mfma_f32_16x16x32_bf16 v[134:137], v[166:169], v[182:185], v[134:137]
	v_mfma_f32_16x16x32_bf16 v[130:133], v[158:161], v[190:193], v[130:133]
	v_mfma_f32_16x16x32_bf16 v[126:129], v[166:169], v[190:193], v[126:129]
	v_mfma_f32_16x16x32_bf16 v[122:125], v[158:161], v[198:201], v[122:125]
	v_mfma_f32_16x16x32_bf16 v[118:121], v[166:169], v[198:201], v[118:121]
	v_mfma_f32_16x16x32_bf16 v[114:117], v[158:161], v[224:227], v[114:117]
	v_mfma_f32_16x16x32_bf16 v[110:113], v[166:169], v[224:227], v[110:113]
	v_mfma_f32_16x16x32_bf16 v[138:141], v[162:165], v[186:189], v[138:141]
	v_mfma_f32_16x16x32_bf16 v[134:137], v[170:173], v[186:189], v[134:137]
	v_mfma_f32_16x16x32_bf16 v[130:133], v[162:165], v[194:197], v[130:133]
	v_mfma_f32_16x16x32_bf16 v[126:129], v[170:173], v[194:197], v[126:129]
	v_mfma_f32_16x16x32_bf16 v[122:125], v[162:165], v[202:205], v[122:125]
	v_mfma_f32_16x16x32_bf16 v[118:121], v[170:173], v[202:205], v[118:121]
	v_mfma_f32_16x16x32_bf16 v[114:117], v[162:165], v[228:231], v[114:117]
	v_mfma_f32_16x16x32_bf16 v[110:113], v[170:173], v[228:231], v[110:113]
	v_mfma_f32_16x16x32_bf16 v[106:109], v[142:145], v[182:185], v[106:109]
	v_mfma_f32_16x16x32_bf16 v[102:105], v[150:153], v[182:185], v[102:105]
	v_mfma_f32_16x16x32_bf16 v[98:101], v[142:145], v[190:193], v[98:101]
	v_mfma_f32_16x16x32_bf16 v[94:97], v[150:153], v[190:193], v[94:97]
	v_mfma_f32_16x16x32_bf16 v[90:93], v[142:145], v[198:201], v[90:93]
	v_mfma_f32_16x16x32_bf16 v[86:89], v[150:153], v[198:201], v[86:89]
	v_mfma_f32_16x16x32_bf16 v[82:85], v[142:145], v[224:227], v[82:85]
	v_mfma_f32_16x16x32_bf16 v[78:81], v[150:153], v[224:227], v[78:81]
	v_mfma_f32_16x16x32_bf16 v[106:109], v[146:149], v[186:189], v[106:109]
	v_mfma_f32_16x16x32_bf16 v[102:105], v[154:157], v[186:189], v[102:105]
	v_mfma_f32_16x16x32_bf16 v[98:101], v[146:149], v[194:197], v[98:101]
	v_mfma_f32_16x16x32_bf16 v[94:97], v[154:157], v[194:197], v[94:97]
	v_mfma_f32_16x16x32_bf16 v[90:93], v[146:149], v[202:205], v[90:93]
	v_mfma_f32_16x16x32_bf16 v[86:89], v[154:157], v[202:205], v[86:89]
	v_mfma_f32_16x16x32_bf16 v[82:85], v[146:149], v[228:231], v[82:85]
	v_mfma_f32_16x16x32_bf16 v[78:81], v[154:157], v[228:231], v[78:81]
	s_setprio 0
	v_cndmask_b32_e64 v4, 0, 1, s[22:23]
	v_cmp_ne_u32_e64 s[8:9], 1, v4
	v_cndmask_b32_e64 v4, 0, 1, s[40:41]
	s_andn2_b64 vcc, exec, s[22:23]
	v_cmp_ne_u32_e64 s[6:7], 1, v4
	s_cbranch_vccnz .LBB0_1226
	s_setprio 1
	s_and_b64 vcc, exec, s[6:7]
	s_mov_b64 s[48:49], -1
	s_cbranch_vccnz .LBB0_1223
	v_mfma_f32_16x16x32_bf16 v[10:13], v[142:145], v[174:177], v[10:13]
	s_mov_b64 s[48:49], 0
	v_mfma_f32_16x16x32_bf16 v[6:9], v[150:153], v[174:177], v[6:9]
	v_mfma_f32_16x16x32_bf16 v[10:13], v[146:149], v[178:181], v[10:13]
	v_mfma_f32_16x16x32_bf16 v[6:9], v[154:157], v[178:181], v[6:9]

; #define PG8_LDX(b) do { if constexpr (XR) { _Pragma("unroll") for (int k = 0; k < 2; ++k) Ax_[k] = *(const PG8_LAS bf16x8*)(lds + XR_OFF + (b) * 2048 + aoffx + k * 1024); } } while (0)
; #define PG8_MMAX() do { if constexpr (XR) { if (hasx) { __builtin_amdgcn_s_setprio(1); if (wr == 0) PG8_MMAX_(B0); else PG8_MMAX_(B1); __builtin_amdgcn_s_setprio(0); } } } while (0)
; #define PG8_WAIT_LOOP() do { if constexpr (XR) PG8_WAIT_V(9); else PG8_WAIT_V(8); } while (0)
; #define PG8_STAGE(bufoff, gbase, voff) do { _Pragma("unroll") for (int _i = 0; _i < 2; ++_i) \
;         __builtin_amdgcn_global_load_lds((const unsigned*)((const char*)(gbase) + (voff)[_i]), (PG8_LAS unsigned*)(lds + (bufoff) + ldsw + _i * 8192), 16, 0, 0); } while (0)
; #define PG8_LDA(dst, b, h) do { _Pragma("unroll") for (int m = 0; m < 4; ++m) _Pragma("unroll") for (int k = 0; k < 2; ++k) dst[m][k] = *(const PG8_LAS bf16x8*)(lds + PG8_SA(b, h) + aoff + m * 2048 + k * 1024); } while (0)
; #define PG8_LDB(dst, b, h) do { _Pragma("unroll") for (int n = 0; n < 2; ++n) _Pragma("unroll") for (int k = 0; k < 2; ++k) dst[n][k] = *(const PG8_LAS bf16x8*)(lds + PG8_SB(b, h) + boff + n * 2048 + k * 1024); } while (0)
; #define PG8_MMA(ai, bj, At, Bt) do { __builtin_amdgcn_s_setprio(1); _Pragma("unroll") for (int m = 0; m < 4; ++m) _Pragma("unroll") for (int n = 0; n < 2; ++n) _Pragma("unroll") for (int k = 0; k < 2; ++k) \
;         acc[ai][bj][m][n] = __builtin_amdgcn_mfma_f32_16x16x32_bf16(Bt[n][k], At[m][k], acc[ai][bj][m][n], 0, 0, 0); __builtin_amdgcn_s_setprio(0); } while (0)
; #define PG8_WAIT_L(n) asm volatile("s_waitcnt lgkmcnt(" #n ")" ::: "memory")
; #define PG8_BAR __builtin_amdgcn_s_barrier()
; #define PG8_SCHED __builtin_amdgcn_sched_barrier(0)
; template <class Epi, class Sched, bool ALIGN_EPI = false, bool SP2 = false, bool DRAIN = true, bool XR = false>
; __device__ __forceinline__ void gemm_phase(PG8_LAS unsigned char* lds, const Gemm g, const Sched& S, const Epi& E) {
;     ...
;             PG8_WAIT_LOOP(); PG8_WAIT_L(0); PG8_BAR; PG8_MMA(1, 0, At, B0); PG8_MMA(1, 1, At, B1); PG8_BAR; PG8_SCHED;
;             PG8_LDB(B0, 1, 0); PG8_LDB(B1, 1, 1); PG8_SCHED; PG8_LDA(At, 1, 0); PG8_LDX(1); PG8_STAGE(PG8_SA(0, 1), a2 + hstepA, voffA);
;             PG8_WAIT_LOOP(); PG8_WAIT_L(0); PG8_BAR; PG8_MMA(0, 0, At, B0); PG8_MMA(0, 1, At, B1); PG8_MMAX(); PG8_BAR; PG8_SCHED;
.LBB0_1228:
	s_or_b64 exec, exec, s[50:51]
	s_waitcnt vmcnt(9)
	s_waitcnt lgkmcnt(0)
	s_setprio 1
	s_barrier
	v_mfma_f32_16x16x32_bf16 v[74:77], v[158:161], v[198:201], v[74:77]
	v_mfma_f32_16x16x32_bf16 v[70:73], v[166:169], v[198:201], v[70:73]
	v_mfma_f32_16x16x32_bf16 v[66:69], v[158:161], v[190:193], v[66:69]
	v_mfma_f32_16x16x32_bf16 v[62:65], v[166:169], v[190:193], v[62:65]
	v_mfma_f32_16x16x32_bf16 v[58:61], v[158:161], v[182:185], v[58:61]
	v_mfma_f32_16x16x32_bf16 v[54:57], v[166:169], v[182:185], v[54:57]
	v_mfma_f32_16x16x32_bf16 v[50:53], v[158:161], v[174:177], v[50:53]
	v_mfma_f32_16x16x32_bf16 v[46:49], v[166:169], v[174:177], v[46:49]
	v_mfma_f32_16x16x32_bf16 v[74:77], v[162:165], v[202:205], v[74:77]
	v_mfma_f32_16x16x32_bf16 v[70:73], v[170:173], v[202:205], v[70:73]
	v_mfma_f32_16x16x32_bf16 v[66:69], v[162:165], v[194:197], v[66:69]
	v_mfma_f32_16x16x32_bf16 v[62:65], v[170:173], v[194:197], v[62:65]
	v_mfma_f32_16x16x32_bf16 v[58:61], v[162:165], v[186:189], v[58:61]
	v_mfma_f32_16x16x32_bf16 v[54:57], v[170:173], v[186:189], v[54:57]
	v_mfma_f32_16x16x32_bf16 v[50:53], v[162:165], v[178:181], v[50:53]
	v_mfma_f32_16x16x32_bf16 v[46:49], v[170:173], v[178:181], v[46:49]
	v_mfma_f32_16x16x32_bf16 v[42:45], v[142:145], v[198:201], v[42:45]
	v_mfma_f32_16x16x32_bf16 v[38:41], v[150:153], v[198:201], v[38:41]
	v_mfma_f32_16x16x32_bf16 v[34:37], v[142:145], v[190:193], v[34:37]
	v_mfma_f32_16x16x32_bf16 v[30:33], v[150:153], v[190:193], v[30:33]
	v_mfma_f32_16x16x32_bf16 v[26:29], v[142:145], v[182:185], v[26:29]
	v_mfma_f32_16x16x32_bf16 v[22:25], v[150:153], v[182:185], v[22:25]
	v_mfma_f32_16x16x32_bf16 v[18:21], v[142:145], v[174:177], v[18:21]
	v_mfma_f32_16x16x32_bf16 v[14:17], v[150:153], v[174:177], v[14:17]
	v_mfma_f32_16x16x32_bf16 v[42:45], v[146:149], v[202:205], v[42:45]
	v_mfma_f32_16x16x32_bf16 v[38:41], v[154:157], v[202:205], v[38:41]
	v_mfma_f32_16x16x32_bf16 v[34:37], v[146:149], v[194:197], v[34:37]
	v_mfma_f32_16x16x32_bf16 v[30:33], v[154:157], v[194:197], v[30:33]
	v_mfma_f32_16x16x32_bf16 v[26:29], v[146:149], v[186:189], v[26:29]
	v_mfma_f32_16x16x32_bf16 v[22:25], v[154:157], v[186:189], v[22:25]
	v_mfma_f32_16x16x32_bf16 v[18:21], v[146:149], v[178:181], v[18:21]
	v_mfma_f32_16x16x32_bf16 v[14:17], v[154:157], v[178:181], v[14:17]
	s_barrier
	s_setprio 0
	v_add_u32_e32 v142, 0x18000, v250
	v_add_u32_e32 v154, 0x1c000, v250
	ds_read_b128 v[158:161], v142
	ds_read_b128 v[162:165], v142 offset:1024
	ds_read_b128 v[166:169], v142 offset:2048
	ds_read_b128 v[170:173], v142 offset:3072
	ds_read_b128 v[142:145], v154
	ds_read_b128 v[146:149], v154 offset:1024
	ds_read_b128 v[150:153], v154 offset:2048
	ds_read_b128 v[154:157], v154 offset:3072
	s_add_u32 s48, s48, s10
	s_addc_u32 s49, s49, s11
	s_mov_b32 m0, s71
	v_add_u32_e32 v178, 0x22c00, v240
	v_lshl_add_u64 v[212:213], s[48:49], 0, v[214:215]
	ds_read_b128 v[182:185], v251 offset:32768
	ds_read_b128 v[186:189], v251 offset:33792
	ds_read_b128 v[190:193], v251 offset:34816
	ds_read_b128 v[194:197], v251 offset:35840
	ds_read_b128 v[198:201], v251 offset:36864
	ds_read_b128 v[202:205], v251 offset:37888
	ds_read_b128 v[242:245], v251 offset:38912
	ds_read_b128 v[206:209], v251 offset:39936
	ds_read_b128 v[174:177], v178
	ds_read_b128 v[178:181], v178 offset:1024
	global_load_lds_dwordx4 v[212:213], off
	v_lshl_add_u64 v[212:213], s[48:49], 0, v[218:219]
	s_mov_b32 m0, s72
	s_nop 0
	global_load_lds_dwordx4 v[212:213], off
	s_waitcnt vmcnt(9)
	s_waitcnt lgkmcnt(0)
	s_setprio 1
	s_barrier
	v_mfma_f32_16x16x32_bf16 v[138:141], v[158:161], v[182:185], v[138:141]
	v_mfma_f32_16x16x32_bf16 v[134:137], v[166:169], v[182:185], v[134:137]
	v_mfma_f32_16x16x32_bf16 v[130:133], v[158:161], v[190:193], v[130:133]
	v_mfma_f32_16x16x32_bf16 v[126:129], v[166:169], v[190:193], v[126:129]
	v_mfma_f32_16x16x32_bf16 v[122:125], v[158:161], v[198:201], v[122:125]
	v_mfma_f32_16x16x32_bf16 v[118:121], v[166:169], v[198:201], v[118:121]
	v_mfma_f32_16x16x32_bf16 v[114:117], v[158:161], v[242:245], v[114:117]
	v_mfma_f32_16x16x32_bf16 v[110:113], v[166:169], v[242:245], v[110:113]
	v_mfma_f32_16x16x32_bf16 v[138:141], v[162:165], v[186:189], v[138:141]
	v_mfma_f32_16x16x32_bf16 v[134:137], v[170:173], v[186:189], v[134:137]
	v_mfma_f32_16x16x32_bf16 v[130:133], v[162:165], v[194:197], v[130:133]
	v_mfma_f32_16x16x32_bf16 v[126:129], v[170:173], v[194:197], v[126:129]
	v_mfma_f32_16x16x32_bf16 v[122:125], v[162:165], v[202:205], v[122:125]
	v_mfma_f32_16x16x32_bf16 v[118:121], v[170:173], v[202:205], v[118:121]
	v_mfma_f32_16x16x32_bf16 v[114:117], v[162:165], v[206:209], v[114:117]
	v_mfma_f32_16x16x32_bf16 v[110:113], v[170:173], v[206:209], v[110:113]
	v_mfma_f32_16x16x32_bf16 v[106:109], v[142:145], v[182:185], v[106:109]
	v_mfma_f32_16x16x32_bf16 v[102:105], v[150:153], v[182:185], v[102:105]
	v_mfma_f32_16x16x32_bf16 v[98:101], v[142:145], v[190:193], v[98:101]
	v_mfma_f32_16x16x32_bf16 v[94:97], v[150:153], v[190:193], v[94:97]
	v_mfma_f32_16x16x32_bf16 v[90:93], v[142:145], v[198:201], v[90:93]
	v_mfma_f32_16x16x32_bf16 v[86:89], v[150:153], v[198:201], v[86:89]
	v_mfma_f32_16x16x32_bf16 v[82:85], v[142:145], v[242:245], v[82:85]
	v_mfma_f32_16x16x32_bf16 v[78:81], v[150:153], v[242:245], v[78:81]
	v_mfma_f32_16x16x32_bf16 v[106:109], v[146:149], v[186:189], v[106:109]
	v_mfma_f32_16x16x32_bf16 v[102:105], v[154:157], v[186:189], v[102:105]
	v_mfma_f32_16x16x32_bf16 v[98:101], v[146:149], v[194:197], v[98:101]
	v_mfma_f32_16x16x32_bf16 v[94:97], v[154:157], v[194:197], v[94:97]
	v_mfma_f32_16x16x32_bf16 v[90:93], v[146:149], v[202:205], v[90:93]
	v_mfma_f32_16x16x32_bf16 v[86:89], v[154:157], v[202:205], v[86:89]
	v_mfma_f32_16x16x32_bf16 v[82:85], v[146:149], v[206:209], v[82:85]
	v_mfma_f32_16x16x32_bf16 v[78:81], v[154:157], v[206:209], v[78:81]
	s_setprio 0
	s_and_b64 vcc, exec, s[8:9]
	s_cbranch_vccnz .LBB0_1234
	s_setprio 1
	s_and_b64 vcc, exec, s[6:7]
	s_mov_b64 s[6:7], -1
	s_cbranch_vccnz .LBB0_1231
	v_mfma_f32_16x16x32_bf16 v[10:13], v[142:145], v[174:177], v[10:13]
	s_mov_b64 s[6:7], 0
	v_mfma_f32_16x16x32_bf16 v[6:9], v[150:153], v[174:177], v[6:9]
	v_mfma_f32_16x16x32_bf16 v[10:13], v[146:149], v[178:181], v[10:13]
	v_mfma_f32_16x16x32_bf16 v[6:9], v[154:157], v[178:181], v[6:9]

; #define PG8_STAGEX(b, gbase) do { if constexpr (XR) { if (lane < 16) __builtin_amdgcn_global_load_lds((const unsigned*)((const char*)(gbase) + voffX), (PG8_LAS unsigned*)(lds + XR_OFF + (b) * 2048 + wid * 256), 16, 0, 0); } } while (0)
; #define PG8_WAIT_LOOP() do { if constexpr (XR) PG8_WAIT_V(9); else PG8_WAIT_V(8); } while (0)
; #define PG8_STAGE(bufoff, gbase, voff) do { _Pragma("unroll") for (int _i = 0; _i < 2; ++_i) \
;         __builtin_amdgcn_global_load_lds((const unsigned*)((const char*)(gbase) + (voff)[_i]), (PG8_LAS unsigned*)(lds + (bufoff) + ldsw + _i * 8192), 16, 0, 0); } while (0)
; #define PG8_LDA(dst, b, h) do { _Pragma("unroll") for (int m = 0; m < 4; ++m) _Pragma("unroll") for (int k = 0; k < 2; ++k) dst[m][k] = *(const PG8_LAS bf16x8*)(lds + PG8_SA(b, h) + aoff + m * 2048 + k * 1024); } while (0)
; #define PG8_MMA(ai, bj, At, Bt) do { __builtin_amdgcn_s_setprio(1); _Pragma("unroll") for (int m = 0; m < 4; ++m) _Pragma("unroll") for (int n = 0; n < 2; ++n) _Pragma("unroll") for (int k = 0; k < 2; ++k) \
;         acc[ai][bj][m][n] = __builtin_amdgcn_mfma_f32_16x16x32_bf16(Bt[n][k], At[m][k], acc[ai][bj][m][n], 0, 0, 0); __builtin_amdgcn_s_setprio(0); } while (0)
; #define PG8_WAIT_L(n) asm volatile("s_waitcnt lgkmcnt(" #n ")" ::: "memory")
; #define PG8_BAR __builtin_amdgcn_s_barrier()
; #define PG8_SCHED __builtin_amdgcn_sched_barrier(0)
; template <class Epi, class Sched, bool ALIGN_EPI = false, bool SP2 = false, bool DRAIN = true, bool XR = false>
; __device__ __forceinline__ void gemm_phase(PG8_LAS unsigned char* lds, const Gemm g, const Sched& S, const Epi& E) {
;     ...
;             PG8_LDA(At, 1, 1); PG8_STAGE(PG8_SB(1, 0), b3, voffB); PG8_STAGE(PG8_SB(1, 1), b3 + hstep, voffB); PG8_STAGE(PG8_SA(1, 0), a3, voffA); PG8_STAGEX(1, x3);
;             PG8_WAIT_LOOP(); PG8_WAIT_L(0); PG8_BAR; PG8_MMA(1, 0, At, B0); PG8_MMA(1, 1, At, B1); PG8_BAR; PG8_SCHED;
.LBB0_1236:
	s_or_b64 exec, exec, s[6:7]
	s_waitcnt vmcnt(9)
	s_waitcnt lgkmcnt(0)
	s_setprio 1
	s_barrier
	v_mfma_f32_16x16x32_bf16 v[74:77], v[158:161], v[198:201], v[74:77]
	v_mfma_f32_16x16x32_bf16 v[70:73], v[166:169], v[198:201], v[70:73]
	v_mfma_f32_16x16x32_bf16 v[66:69], v[158:161], v[190:193], v[66:69]
	v_mfma_f32_16x16x32_bf16 v[62:65], v[166:169], v[190:193], v[62:65]
	v_mfma_f32_16x16x32_bf16 v[58:61], v[158:161], v[182:185], v[58:61]
	v_mfma_f32_16x16x32_bf16 v[54:57], v[166:169], v[182:185], v[54:57]
	v_mfma_f32_16x16x32_bf16 v[50:53], v[158:161], v[174:177], v[50:53]
	v_mfma_f32_16x16x32_bf16 v[46:49], v[166:169], v[174:177], v[46:49]
	v_mfma_f32_16x16x32_bf16 v[74:77], v[162:165], v[202:205], v[74:77]
	v_mfma_f32_16x16x32_bf16 v[70:73], v[170:173], v[202:205], v[70:73]
	v_mfma_f32_16x16x32_bf16 v[66:69], v[162:165], v[194:197], v[66:69]
	v_mfma_f32_16x16x32_bf16 v[62:65], v[170:173], v[194:197], v[62:65]
	v_mfma_f32_16x16x32_bf16 v[58:61], v[162:165], v[186:189], v[58:61]
	v_mfma_f32_16x16x32_bf16 v[54:57], v[170:173], v[186:189], v[54:57]
	v_mfma_f32_16x16x32_bf16 v[50:53], v[162:165], v[178:181], v[50:53]
	v_mfma_f32_16x16x32_bf16 v[46:49], v[170:173], v[178:181], v[46:49]
	v_mfma_f32_16x16x32_bf16 v[42:45], v[142:145], v[198:201], v[42:45]
	v_mfma_f32_16x16x32_bf16 v[38:41], v[150:153], v[198:201], v[38:41]
	v_mfma_f32_16x16x32_bf16 v[34:37], v[142:145], v[190:193], v[34:37]
	v_mfma_f32_16x16x32_bf16 v[30:33], v[150:153], v[190:193], v[30:33]
	v_mfma_f32_16x16x32_bf16 v[26:29], v[142:145], v[182:185], v[26:29]
	v_mfma_f32_16x16x32_bf16 v[22:25], v[150:153], v[182:185], v[22:25]
	v_mfma_f32_16x16x32_bf16 v[18:21], v[142:145], v[174:177], v[18:21]
	v_mfma_f32_16x16x32_bf16 v[14:17], v[150:153], v[174:177], v[14:17]
	v_mfma_f32_16x16x32_bf16 v[42:45], v[146:149], v[202:205], v[42:45]
	v_mfma_f32_16x16x32_bf16 v[38:41], v[154:157], v[202:205], v[38:41]
	v_mfma_f32_16x16x32_bf16 v[34:37], v[146:149], v[194:197], v[34:37]
	v_mfma_f32_16x16x32_bf16 v[30:33], v[154:157], v[194:197], v[30:33]
	v_mfma_f32_16x16x32_bf16 v[26:29], v[146:149], v[186:189], v[26:29]
	v_mfma_f32_16x16x32_bf16 v[22:25], v[154:157], v[186:189], v[22:25]
	v_mfma_f32_16x16x32_bf16 v[18:21], v[146:149], v[178:181], v[18:21]
	v_mfma_f32_16x16x32_bf16 v[14:17], v[154:157], v[178:181], v[14:17]
	s_barrier
	s_setprio 0
	s_cmp_ge_i32 s89, s81
	s_cbranch_scc1 .LBB0_1238
	s_mov_b32 s50, s89
	s_cmp_lg_u32 s83, s50
	s_cbranch_scc0 .LBB0_1219
	s_branch .LBB0_1220

; #define PG8_LDX(b) do { if constexpr (XR) { _Pragma("unroll") for (int k = 0; k < 2; ++k) Ax_[k] = *(const PG8_LAS bf16x8*)(lds + XR_OFF + (b) * 2048 + aoffx + k * 1024); } } while (0)
; #define PG8_MMAX() do { if constexpr (XR) { if (hasx) { __builtin_amdgcn_s_setprio(1); if (wr == 0) PG8_MMAX_(B0); else PG8_MMAX_(B1); __builtin_amdgcn_s_setprio(0); } } } while (0)
; #define PG8_WAIT_LOOP() do { if constexpr (XR) PG8_WAIT_V(9); else PG8_WAIT_V(8); } while (0)
; #define PG8_STAGE(bufoff, gbase, voff) do { _Pragma("unroll") for (int _i = 0; _i < 2; ++_i) \
;         __builtin_amdgcn_global_load_lds((const unsigned*)((const char*)(gbase) + (voff)[_i]), (PG8_LAS unsigned*)(lds + (bufoff) + ldsw + _i * 8192), 16, 0, 0); } while (0)
; #define PG8_LDA(dst, b, h) do { _Pragma("unroll") for (int m = 0; m < 4; ++m) _Pragma("unroll") for (int k = 0; k < 2; ++k) dst[m][k] = *(const PG8_LAS bf16x8*)(lds + PG8_SA(b, h) + aoff + m * 2048 + k * 1024); } while (0)
; #define PG8_LDB(dst, b, h) do { _Pragma("unroll") for (int n = 0; n < 2; ++n) _Pragma("unroll") for (int k = 0; k < 2; ++k) dst[n][k] = *(const PG8_LAS bf16x8*)(lds + PG8_SB(b, h) + boff + n * 2048 + k * 1024); } while (0)
; #define PG8_MMA(ai, bj, At, Bt) do { __builtin_amdgcn_s_setprio(1); _Pragma("unroll") for (int m = 0; m < 4; ++m) _Pragma("unroll") for (int n = 0; n < 2; ++n) _Pragma("unroll") for (int k = 0; k < 2; ++k) \
;         acc[ai][bj][m][n] = __builtin_amdgcn_mfma_f32_16x16x32_bf16(Bt[n][k], At[m][k], acc[ai][bj][m][n], 0, 0, 0); __builtin_amdgcn_s_setprio(0); } while (0)
; #define PG8_WAIT_L(n) asm volatile("s_waitcnt lgkmcnt(" #n ")" ::: "memory")
; #define PG8_BAR __builtin_amdgcn_s_barrier()
; #define PG8_SCHED __builtin_amdgcn_sched_barrier(0)
; template <class Epi, class Sched, bool ALIGN_EPI = false, bool SP2 = false, bool DRAIN = true, bool XR = false>
; __device__ __forceinline__ void gemm_phase(PG8_LAS unsigned char* lds, const Gemm g, const Sched& S, const Epi& E) {
;     ...
;             PG8_LDB(B0, 0, 0); PG8_LDB(B1, 0, 1); PG8_SCHED; PG8_LDA(At, 0, 0); PG8_LDX(0); PG8_STAGE(PG8_SA(1, 1), a1 + hstepA, voffA);
;             PG8_WAIT_LOOP(); PG8_WAIT_L(0); PG8_BAR; PG8_MMA(0, 0, At, B0); PG8_MMA(0, 1, At, B1); PG8_MMAX(); PG8_BAR; PG8_SCHED;
.LBB0_1359:
	v_add_u32_e32 v2, 0x10000, v248
	s_add_i32 s4, s90, -2
	ds_read_b128 v[158:161], v2
	ds_read_b128 v[162:165], v2 offset:1024
	ds_read_b128 v[166:169], v2 offset:2048
	ds_read_b128 v[170:173], v2 offset:3072
	v_add_u32_e32 v2, 0x14000, v248
	s_and_b32 s6, s4, s73
	ds_read_b128 v[142:145], v2
	ds_read_b128 v[146:149], v2 offset:1024
	ds_read_b128 v[150:153], v2 offset:2048
	ds_read_b128 v[154:157], v2 offset:3072
	s_lshr_b32 s84, s6, 2
	s_lshl_b32 s6, s6, 7
	s_lshl_b64 s[4:5], s[84:85], 9
	s_and_b32 s6, s6, 0x100
	s_add_u32 s4, s56, s4
	s_addc_u32 s5, s57, s5
	s_add_u32 s4, s4, s6
	s_addc_u32 s5, s5, 0
	s_add_u32 s4, s4, s28
	s_addc_u32 s5, s5, s29
	v_lshl_add_u64 v[4:5], s[4:5], 0, v[220:221]
	v_add_u32_e32 v2, 0x22400, v250
	v_lshl_add_u64 v[4:5], v[4:5], 0, s[86:87]
	s_add_i32 m0, s13, 0xc000
	ds_read_b128 v[182:185], v249
	ds_read_b128 v[186:189], v249 offset:1024
	ds_read_b128 v[190:193], v249 offset:2048
	ds_read_b128 v[194:197], v249 offset:3072
	ds_read_b128 v[198:201], v249 offset:4096
	ds_read_b128 v[202:205], v249 offset:5120
	ds_read_b128 v[206:209], v249 offset:6144
	ds_read_b128 v[224:227], v249 offset:7168
	ds_read_b128 v[174:177], v2
	ds_read_b128 v[178:181], v2 offset:1024
	global_load_lds_dwordx4 v[4:5], off
	v_lshl_add_u64 v[4:5], s[4:5], 0, v[216:217]
	v_lshl_add_u64 v[4:5], v[4:5], 0, s[86:87]
	s_add_i32 m0, s13, 0xe000
	s_nop 0
	global_load_lds_dwordx4 v[4:5], off
	s_waitcnt vmcnt(9)
	s_waitcnt lgkmcnt(0)
	s_setprio 1
	s_barrier
	v_mfma_f32_16x16x32_bf16 v[138:141], v[158:161], v[182:185], v[138:141]
	v_mfma_f32_16x16x32_bf16 v[134:137], v[166:169], v[182:185], v[134:137]
	v_mfma_f32_16x16x32_bf16 v[122:125], v[158:161], v[190:193], v[122:125]
	v_mfma_f32_16x16x32_bf16 v[118:121], v[166:169], v[190:193], v[118:121]
	v_mfma_f32_16x16x32_bf16 v[106:109], v[158:161], v[198:201], v[106:109]
	v_mfma_f32_16x16x32_bf16 v[102:105], v[166:169], v[198:201], v[102:105]
	v_mfma_f32_16x16x32_bf16 v[90:93], v[158:161], v[206:209], v[90:93]
	v_mfma_f32_16x16x32_bf16 v[86:89], v[166:169], v[206:209], v[86:89]
	v_mfma_f32_16x16x32_bf16 v[138:141], v[162:165], v[186:189], v[138:141]
	v_mfma_f32_16x16x32_bf16 v[134:137], v[170:173], v[186:189], v[134:137]
	v_mfma_f32_16x16x32_bf16 v[122:125], v[162:165], v[194:197], v[122:125]
	v_mfma_f32_16x16x32_bf16 v[118:121], v[170:173], v[194:197], v[118:121]
	v_mfma_f32_16x16x32_bf16 v[106:109], v[162:165], v[202:205], v[106:109]
	v_mfma_f32_16x16x32_bf16 v[102:105], v[170:173], v[202:205], v[102:105]
	v_mfma_f32_16x16x32_bf16 v[90:93], v[162:165], v[224:227], v[90:93]
	v_mfma_f32_16x16x32_bf16 v[86:89], v[170:173], v[224:227], v[86:89]
	v_mfma_f32_16x16x32_bf16 v[130:133], v[142:145], v[182:185], v[130:133]
	v_mfma_f32_16x16x32_bf16 v[126:129], v[150:153], v[182:185], v[126:129]
	v_mfma_f32_16x16x32_bf16 v[114:117], v[142:145], v[190:193], v[114:117]
	v_mfma_f32_16x16x32_bf16 v[110:113], v[150:153], v[190:193], v[110:113]
	v_mfma_f32_16x16x32_bf16 v[98:101], v[142:145], v[198:201], v[98:101]
	v_mfma_f32_16x16x32_bf16 v[94:97], v[150:153], v[198:201], v[94:97]
	v_mfma_f32_16x16x32_bf16 v[82:85], v[142:145], v[206:209], v[82:85]
	v_mfma_f32_16x16x32_bf16 v[78:81], v[150:153], v[206:209], v[78:81]
	v_mfma_f32_16x16x32_bf16 v[130:133], v[146:149], v[186:189], v[130:133]
	v_mfma_f32_16x16x32_bf16 v[126:129], v[154:157], v[186:189], v[126:129]
	v_mfma_f32_16x16x32_bf16 v[114:117], v[146:149], v[194:197], v[114:117]
	v_mfma_f32_16x16x32_bf16 v[110:113], v[154:157], v[194:197], v[110:113]
	v_mfma_f32_16x16x32_bf16 v[98:101], v[146:149], v[202:205], v[98:101]
	v_mfma_f32_16x16x32_bf16 v[94:97], v[154:157], v[202:205], v[94:97]
	v_mfma_f32_16x16x32_bf16 v[82:85], v[146:149], v[224:227], v[82:85]
	v_mfma_f32_16x16x32_bf16 v[78:81], v[154:157], v[224:227], v[78:81]
	s_setprio 0
	v_cndmask_b32_e64 v2, 0, 1, s[46:47]
	v_cmp_ne_u32_e64 s[6:7], 1, v2
	v_cndmask_b32_e64 v2, 0, 1, s[44:45]
	s_andn2_b64 vcc, exec, s[46:47]
	v_cmp_ne_u32_e64 s[4:5], 1, v2
	s_cbranch_vccnz .LBB0_1365
	s_setprio 1
	s_and_b64 vcc, exec, s[4:5]
	s_mov_b64 s[60:61], -1
	s_cbranch_vccnz .LBB0_1362
	v_mfma_f32_16x16x32_bf16 v[10:13], v[142:145], v[174:177], v[10:13]
	s_mov_b64 s[60:61], 0
	v_mfma_f32_16x16x32_bf16 v[6:9], v[150:153], v[174:177], v[6:9]
	v_mfma_f32_16x16x32_bf16 v[10:13], v[146:149], v[178:181], v[10:13]
	v_mfma_f32_16x16x32_bf16 v[6:9], v[154:157], v[178:181], v[6:9]

; #define PG8_LDX(b) do { if constexpr (XR) { _Pragma("unroll") for (int k = 0; k < 2; ++k) Ax_[k] = *(const PG8_LAS bf16x8*)(lds + XR_OFF + (b) * 2048 + aoffx + k * 1024); } } while (0)
; #define PG8_MMAX() do { if constexpr (XR) { if (hasx) { __builtin_amdgcn_s_setprio(1); if (wr == 0) PG8_MMAX_(B0); else PG8_MMAX_(B1); __builtin_amdgcn_s_setprio(0); } } } while (0)
; #define PG8_WAIT_LOOP() do { if constexpr (XR) PG8_WAIT_V(9); else PG8_WAIT_V(8); } while (0)
; #define PG8_STAGE(bufoff, gbase, voff) do { _Pragma("unroll") for (int _i = 0; _i < 2; ++_i) \
;         __builtin_amdgcn_global_load_lds((const unsigned*)((const char*)(gbase) + (voff)[_i]), (PG8_LAS unsigned*)(lds + (bufoff) + ldsw + _i * 8192), 16, 0, 0); } while (0)
; #define PG8_LDA(dst, b, h) do { _Pragma("unroll") for (int m = 0; m < 4; ++m) _Pragma("unroll") for (int k = 0; k < 2; ++k) dst[m][k] = *(const PG8_LAS bf16x8*)(lds + PG8_SA(b, h) + aoff + m * 2048 + k * 1024); } while (0)
; #define PG8_LDB(dst, b, h) do { _Pragma("unroll") for (int n = 0; n < 2; ++n) _Pragma("unroll") for (int k = 0; k < 2; ++k) dst[n][k] = *(const PG8_LAS bf16x8*)(lds + PG8_SB(b, h) + boff + n * 2048 + k * 1024); } while (0)
; #define PG8_MMA(ai, bj, At, Bt) do { __builtin_amdgcn_s_setprio(1); _Pragma("unroll") for (int m = 0; m < 4; ++m) _Pragma("unroll") for (int n = 0; n < 2; ++n) _Pragma("unroll") for (int k = 0; k < 2; ++k) \
;         acc[ai][bj][m][n] = __builtin_amdgcn_mfma_f32_16x16x32_bf16(Bt[n][k], At[m][k], acc[ai][bj][m][n], 0, 0, 0); __builtin_amdgcn_s_setprio(0); } while (0)
; #define PG8_WAIT_L(n) asm volatile("s_waitcnt lgkmcnt(" #n ")" ::: "memory")
; #define PG8_BAR __builtin_amdgcn_s_barrier()
; #define PG8_SCHED __builtin_amdgcn_sched_barrier(0)
; template <class Epi, class Sched, bool ALIGN_EPI = false, bool SP2 = false, bool DRAIN = true, bool XR = false>
; __device__ __forceinline__ void gemm_phase(PG8_LAS unsigned char* lds, const Gemm g, const Sched& S, const Epi& E) {
;     ...
;             PG8_WAIT_LOOP(); PG8_WAIT_L(0); PG8_BAR; PG8_MMA(1, 0, At, B0); PG8_MMA(1, 1, At, B1); PG8_BAR; PG8_SCHED;
;             PG8_LDB(B0, 1, 0); PG8_LDB(B1, 1, 1); PG8_SCHED; PG8_LDA(At, 1, 0); PG8_LDX(1); PG8_STAGE(PG8_SA(0, 1), a2 + hstepA, voffA);
;             PG8_WAIT_LOOP(); PG8_WAIT_L(0); PG8_BAR; PG8_MMA(0, 0, At, B0); PG8_MMA(0, 1, At, B1); PG8_MMAX(); PG8_BAR; PG8_SCHED;
.LBB0_1367:
	s_or_b64 exec, exec, s[62:63]
	s_waitcnt vmcnt(9)
	s_waitcnt lgkmcnt(0)
	s_setprio 1
	s_barrier
	v_mfma_f32_16x16x32_bf16 v[74:77], v[158:161], v[198:201], v[74:77]
	v_mfma_f32_16x16x32_bf16 v[70:73], v[166:169], v[198:201], v[70:73]
	v_mfma_f32_16x16x32_bf16 v[58:61], v[158:161], v[190:193], v[58:61]
	v_mfma_f32_16x16x32_bf16 v[54:57], v[166:169], v[190:193], v[54:57]
	v_mfma_f32_16x16x32_bf16 v[42:45], v[158:161], v[182:185], v[42:45]
	v_mfma_f32_16x16x32_bf16 v[38:41], v[166:169], v[182:185], v[38:41]
	v_mfma_f32_16x16x32_bf16 v[26:29], v[158:161], v[174:177], v[26:29]
	v_mfma_f32_16x16x32_bf16 v[22:25], v[166:169], v[174:177], v[22:25]
	v_mfma_f32_16x16x32_bf16 v[74:77], v[162:165], v[202:205], v[74:77]
	v_mfma_f32_16x16x32_bf16 v[70:73], v[170:173], v[202:205], v[70:73]
	v_mfma_f32_16x16x32_bf16 v[58:61], v[162:165], v[194:197], v[58:61]
	v_mfma_f32_16x16x32_bf16 v[54:57], v[170:173], v[194:197], v[54:57]
	v_mfma_f32_16x16x32_bf16 v[42:45], v[162:165], v[186:189], v[42:45]
	v_mfma_f32_16x16x32_bf16 v[38:41], v[170:173], v[186:189], v[38:41]
	v_mfma_f32_16x16x32_bf16 v[26:29], v[162:165], v[178:181], v[26:29]
	v_mfma_f32_16x16x32_bf16 v[22:25], v[170:173], v[178:181], v[22:25]
	v_mfma_f32_16x16x32_bf16 v[66:69], v[142:145], v[198:201], v[66:69]
	v_mfma_f32_16x16x32_bf16 v[62:65], v[150:153], v[198:201], v[62:65]
	v_mfma_f32_16x16x32_bf16 v[50:53], v[142:145], v[190:193], v[50:53]
	v_mfma_f32_16x16x32_bf16 v[46:49], v[150:153], v[190:193], v[46:49]
	v_mfma_f32_16x16x32_bf16 v[34:37], v[142:145], v[182:185], v[34:37]
	v_mfma_f32_16x16x32_bf16 v[30:33], v[150:153], v[182:185], v[30:33]
	v_mfma_f32_16x16x32_bf16 v[18:21], v[142:145], v[174:177], v[18:21]
	v_mfma_f32_16x16x32_bf16 v[14:17], v[150:153], v[174:177], v[14:17]
	v_mfma_f32_16x16x32_bf16 v[66:69], v[146:149], v[202:205], v[66:69]
	v_mfma_f32_16x16x32_bf16 v[62:65], v[154:157], v[202:205], v[62:65]
	v_mfma_f32_16x16x32_bf16 v[50:53], v[146:149], v[194:197], v[50:53]
	v_mfma_f32_16x16x32_bf16 v[46:49], v[154:157], v[194:197], v[46:49]
	v_mfma_f32_16x16x32_bf16 v[34:37], v[146:149], v[186:189], v[34:37]
	v_mfma_f32_16x16x32_bf16 v[30:33], v[154:157], v[186:189], v[30:33]
	v_mfma_f32_16x16x32_bf16 v[18:21], v[146:149], v[178:181], v[18:21]
	v_mfma_f32_16x16x32_bf16 v[14:17], v[154:157], v[178:181], v[14:17]
	s_barrier
	s_setprio 0
	v_add_u32_e32 v2, 0x18000, v248
	ds_read_b128 v[158:161], v2
	ds_read_b128 v[162:165], v2 offset:1024
	ds_read_b128 v[166:169], v2 offset:2048
	ds_read_b128 v[170:173], v2 offset:3072
	v_add_u32_e32 v2, 0x1c000, v248
	ds_read_b128 v[142:145], v2
	ds_read_b128 v[146:149], v2 offset:1024
	ds_read_b128 v[150:153], v2 offset:2048
	ds_read_b128 v[154:157], v2 offset:3072
	s_add_u32 s8, s60, s28
	s_addc_u32 s9, s61, s29
	s_mov_b32 m0, s19
	v_add_u32_e32 v2, 0x22c00, v250
	v_lshl_add_u64 v[212:213], s[8:9], 0, v[220:221]
	ds_read_b128 v[182:185], v249 offset:32768
	ds_read_b128 v[186:189], v249 offset:33792
	ds_read_b128 v[190:193], v249 offset:34816
	ds_read_b128 v[194:197], v249 offset:35840
	ds_read_b128 v[198:201], v249 offset:36864
	ds_read_b128 v[202:205], v249 offset:37888
	ds_read_b128 v[206:209], v249 offset:38912
	ds_read_b128 v[242:245], v249 offset:39936
	ds_read_b128 v[174:177], v2
	ds_read_b128 v[178:181], v2 offset:1024
	global_load_lds_dwordx4 v[212:213], off
	v_lshl_add_u64 v[212:213], s[8:9], 0, v[216:217]
	s_mov_b32 m0, s22
	s_nop 0
	global_load_lds_dwordx4 v[212:213], off
	s_waitcnt vmcnt(9)
	s_waitcnt lgkmcnt(0)
	s_setprio 1
	s_barrier
	v_mfma_f32_16x16x32_bf16 v[138:141], v[158:161], v[182:185], v[138:141]
	v_mfma_f32_16x16x32_bf16 v[134:137], v[166:169], v[182:185], v[134:137]
	v_mfma_f32_16x16x32_bf16 v[122:125], v[158:161], v[190:193], v[122:125]
	v_mfma_f32_16x16x32_bf16 v[118:121], v[166:169], v[190:193], v[118:121]
	v_mfma_f32_16x16x32_bf16 v[106:109], v[158:161], v[198:201], v[106:109]
	v_mfma_f32_16x16x32_bf16 v[102:105], v[166:169], v[198:201], v[102:105]
	v_mfma_f32_16x16x32_bf16 v[90:93], v[158:161], v[206:209], v[90:93]
	v_mfma_f32_16x16x32_bf16 v[86:89], v[166:169], v[206:209], v[86:89]
	v_mfma_f32_16x16x32_bf16 v[138:141], v[162:165], v[186:189], v[138:141]
	v_mfma_f32_16x16x32_bf16 v[134:137], v[170:173], v[186:189], v[134:137]
	v_mfma_f32_16x16x32_bf16 v[122:125], v[162:165], v[194:197], v[122:125]
	v_mfma_f32_16x16x32_bf16 v[118:121], v[170:173], v[194:197], v[118:121]
	v_mfma_f32_16x16x32_bf16 v[106:109], v[162:165], v[202:205], v[106:109]
	v_mfma_f32_16x16x32_bf16 v[102:105], v[170:173], v[202:205], v[102:105]
	v_mfma_f32_16x16x32_bf16 v[90:93], v[162:165], v[242:245], v[90:93]
	v_mfma_f32_16x16x32_bf16 v[86:89], v[170:173], v[242:245], v[86:89]
	v_mfma_f32_16x16x32_bf16 v[130:133], v[142:145], v[182:185], v[130:133]
	v_mfma_f32_16x16x32_bf16 v[126:129], v[150:153], v[182:185], v[126:129]
	v_mfma_f32_16x16x32_bf16 v[114:117], v[142:145], v[190:193], v[114:117]
	v_mfma_f32_16x16x32_bf16 v[110:113], v[150:153], v[190:193], v[110:113]
	v_mfma_f32_16x16x32_bf16 v[98:101], v[142:145], v[198:201], v[98:101]
	v_mfma_f32_16x16x32_bf16 v[94:97], v[150:153], v[198:201], v[94:97]
	v_mfma_f32_16x16x32_bf16 v[82:85], v[142:145], v[206:209], v[82:85]
	v_mfma_f32_16x16x32_bf16 v[78:81], v[150:153], v[206:209], v[78:81]
	v_mfma_f32_16x16x32_bf16 v[130:133], v[146:149], v[186:189], v[130:133]
	v_mfma_f32_16x16x32_bf16 v[126:129], v[154:157], v[186:189], v[126:129]
	v_mfma_f32_16x16x32_bf16 v[114:117], v[146:149], v[194:197], v[114:117]
	v_mfma_f32_16x16x32_bf16 v[110:113], v[154:157], v[194:197], v[110:113]
	v_mfma_f32_16x16x32_bf16 v[98:101], v[146:149], v[202:205], v[98:101]
	v_mfma_f32_16x16x32_bf16 v[94:97], v[154:157], v[202:205], v[94:97]
	v_mfma_f32_16x16x32_bf16 v[82:85], v[146:149], v[242:245], v[82:85]
	v_mfma_f32_16x16x32_bf16 v[78:81], v[154:157], v[242:245], v[78:81]
	s_setprio 0
	s_and_b64 vcc, exec, s[6:7]
	s_cbranch_vccnz .LBB0_1373
	s_setprio 1
	s_and_b64 vcc, exec, s[4:5]
	s_mov_b64 s[4:5], -1
	s_cbranch_vccnz .LBB0_1370
	v_mfma_f32_16x16x32_bf16 v[10:13], v[142:145], v[174:177], v[10:13]
	s_mov_b64 s[4:5], 0
	v_mfma_f32_16x16x32_bf16 v[6:9], v[150:153], v[174:177], v[6:9]
	v_mfma_f32_16x16x32_bf16 v[10:13], v[146:149], v[178:181], v[10:13]
	v_mfma_f32_16x16x32_bf16 v[6:9], v[154:157], v[178:181], v[6:9]

; #define PG8_STAGEX(b, gbase) do { if constexpr (XR) { if (lane < 16) __builtin_amdgcn_global_load_lds((const unsigned*)((const char*)(gbase) + voffX), (PG8_LAS unsigned*)(lds + XR_OFF + (b) * 2048 + wid * 256), 16, 0, 0); } } while (0)
; #define PG8_WAIT_LOOP() do { if constexpr (XR) PG8_WAIT_V(9); else PG8_WAIT_V(8); } while (0)
; #define PG8_STAGE(bufoff, gbase, voff) do { _Pragma("unroll") for (int _i = 0; _i < 2; ++_i) \
;         __builtin_amdgcn_global_load_lds((const unsigned*)((const char*)(gbase) + (voff)[_i]), (PG8_LAS unsigned*)(lds + (bufoff) + ldsw + _i * 8192), 16, 0, 0); } while (0)
; #define PG8_LDA(dst, b, h) do { _Pragma("unroll") for (int m = 0; m < 4; ++m) _Pragma("unroll") for (int k = 0; k < 2; ++k) dst[m][k] = *(const PG8_LAS bf16x8*)(lds + PG8_SA(b, h) + aoff + m * 2048 + k * 1024); } while (0)
; #define PG8_MMA(ai, bj, At, Bt) do { __builtin_amdgcn_s_setprio(1); _Pragma("unroll") for (int m = 0; m < 4; ++m) _Pragma("unroll") for (int n = 0; n < 2; ++n) _Pragma("unroll") for (int k = 0; k < 2; ++k) \
;         acc[ai][bj][m][n] = __builtin_amdgcn_mfma_f32_16x16x32_bf16(Bt[n][k], At[m][k], acc[ai][bj][m][n], 0, 0, 0); __builtin_amdgcn_s_setprio(0); } while (0)
; #define PG8_WAIT_L(n) asm volatile("s_waitcnt lgkmcnt(" #n ")" ::: "memory")
; #define PG8_BAR __builtin_amdgcn_s_barrier()
; #define PG8_SCHED __builtin_amdgcn_sched_barrier(0)
; template <class Epi, class Sched, bool ALIGN_EPI = false, bool SP2 = false, bool DRAIN = true, bool XR = false>
; __device__ __forceinline__ void gemm_phase(PG8_LAS unsigned char* lds, const Gemm g, const Sched& S, const Epi& E) {
;     ...
;             PG8_LDA(At, 1, 1); PG8_STAGE(PG8_SB(1, 0), b3, voffB); PG8_STAGE(PG8_SB(1, 1), b3 + hstep, voffB); PG8_STAGE(PG8_SA(1, 0), a3, voffA); PG8_STAGEX(1, x3);
;             PG8_WAIT_LOOP(); PG8_WAIT_L(0); PG8_BAR; PG8_MMA(1, 0, At, B0); PG8_MMA(1, 1, At, B1); PG8_BAR; PG8_SCHED;
.LBB0_1375:
	s_or_b64 exec, exec, s[4:5]
	s_waitcnt vmcnt(9)
	s_waitcnt lgkmcnt(0)
	s_setprio 1
	s_barrier
	v_mfma_f32_16x16x32_bf16 v[74:77], v[158:161], v[198:201], v[74:77]
	v_mfma_f32_16x16x32_bf16 v[70:73], v[166:169], v[198:201], v[70:73]
	v_mfma_f32_16x16x32_bf16 v[58:61], v[158:161], v[190:193], v[58:61]
	v_mfma_f32_16x16x32_bf16 v[54:57], v[166:169], v[190:193], v[54:57]
	v_mfma_f32_16x16x32_bf16 v[42:45], v[158:161], v[182:185], v[42:45]
	v_mfma_f32_16x16x32_bf16 v[38:41], v[166:169], v[182:185], v[38:41]
	v_mfma_f32_16x16x32_bf16 v[26:29], v[158:161], v[174:177], v[26:29]
	v_mfma_f32_16x16x32_bf16 v[22:25], v[166:169], v[174:177], v[22:25]
	v_mfma_f32_16x16x32_bf16 v[74:77], v[162:165], v[202:205], v[74:77]
	v_mfma_f32_16x16x32_bf16 v[70:73], v[170:173], v[202:205], v[70:73]
	v_mfma_f32_16x16x32_bf16 v[58:61], v[162:165], v[194:197], v[58:61]
	v_mfma_f32_16x16x32_bf16 v[54:57], v[170:173], v[194:197], v[54:57]
	v_mfma_f32_16x16x32_bf16 v[42:45], v[162:165], v[186:189], v[42:45]
	v_mfma_f32_16x16x32_bf16 v[38:41], v[170:173], v[186:189], v[38:41]
	v_mfma_f32_16x16x32_bf16 v[26:29], v[162:165], v[178:181], v[26:29]
	v_mfma_f32_16x16x32_bf16 v[22:25], v[170:173], v[178:181], v[22:25]
	v_mfma_f32_16x16x32_bf16 v[66:69], v[142:145], v[198:201], v[66:69]
	v_mfma_f32_16x16x32_bf16 v[62:65], v[150:153], v[198:201], v[62:65]
	v_mfma_f32_16x16x32_bf16 v[50:53], v[142:145], v[190:193], v[50:53]
	v_mfma_f32_16x16x32_bf16 v[46:49], v[150:153], v[190:193], v[46:49]
	v_mfma_f32_16x16x32_bf16 v[34:37], v[142:145], v[182:185], v[34:37]
	v_mfma_f32_16x16x32_bf16 v[30:33], v[150:153], v[182:185], v[30:33]
	v_mfma_f32_16x16x32_bf16 v[18:21], v[142:145], v[174:177], v[18:21]
	v_mfma_f32_16x16x32_bf16 v[14:17], v[150:153], v[174:177], v[14:17]
	v_mfma_f32_16x16x32_bf16 v[66:69], v[146:149], v[202:205], v[66:69]
	v_mfma_f32_16x16x32_bf16 v[62:65], v[154:157], v[202:205], v[62:65]
	v_mfma_f32_16x16x32_bf16 v[50:53], v[146:149], v[194:197], v[50:53]
	v_mfma_f32_16x16x32_bf16 v[46:49], v[154:157], v[194:197], v[46:49]
	v_mfma_f32_16x16x32_bf16 v[34:37], v[146:149], v[186:189], v[34:37]
	v_mfma_f32_16x16x32_bf16 v[30:33], v[154:157], v[186:189], v[30:33]
	v_mfma_f32_16x16x32_bf16 v[18:21], v[146:149], v[178:181], v[18:21]
	v_mfma_f32_16x16x32_bf16 v[14:17], v[154:157], v[178:181], v[14:17]
	s_barrier
	s_setprio 0
	s_add_i32 s4, s90, 2
	s_cmp_ge_i32 s90, s65
	s_cbranch_scc1 .LBB0_1378
	s_mov_b32 s90, s4
	s_branch .LBB0_1359

; #define PG8_STAGEX(b, gbase) do { if constexpr (XR) { if (lane < 16) __builtin_amdgcn_global_load_lds((const unsigned*)((const char*)(gbase) + voffX), (PG8_LAS unsigned*)(lds + XR_OFF + (b) * 2048 + wid * 256), 16, 0, 0); } } while (0)
; #define PG8_LDX(b) do { if constexpr (XR) { _Pragma("unroll") for (int k = 0; k < 2; ++k) Ax_[k] = *(const PG8_LAS bf16x8*)(lds + XR_OFF + (b) * 2048 + aoffx + k * 1024); } } while (0)
; #define PG8_MMAX() do { if constexpr (XR) { if (hasx) { __builtin_amdgcn_s_setprio(1); if (wr == 0) PG8_MMAX_(B0); else PG8_MMAX_(B1); __builtin_amdgcn_s_setprio(0); } } } while (0)
; #define PG8_WAIT_LOOP() do { if constexpr (XR) PG8_WAIT_V(9); else PG8_WAIT_V(8); } while (0)
; #define PG8_STAGE(bufoff, gbase, voff) do { _Pragma("unroll") for (int _i = 0; _i < 2; ++_i) \
;         __builtin_amdgcn_global_load_lds((const unsigned*)((const char*)(gbase) + (voff)[_i]), (PG8_LAS unsigned*)(lds + (bufoff) + ldsw + _i * 8192), 16, 0, 0); } while (0)
; #define PG8_BAR __builtin_amdgcn_s_barrier()
; template <class Epi, class Sched, bool ALIGN_EPI = false, bool SP2 = false, bool DRAIN = true, bool XR = false>
; __device__ __forceinline__ void gemm_phase(PG8_LAS unsigned char* lds, const Gemm g, const Sched& S, const Epi& E) {
;     ...
;             PG8_LDB(B0, 0, 0); PG8_LDB(B1, 0, 1); PG8_SCHED; PG8_LDA(At, 0, 0); PG8_LDX(0); PG8_STAGE(PG8_SA(1, 1), a1 + hstepA, voffA);
;             PG8_WAIT_LOOP(); PG8_WAIT_L(0); PG8_BAR; PG8_MMA(0, 0, At, B0); PG8_MMA(0, 1, At, B1); PG8_MMAX(); PG8_BAR; PG8_SCHED;
;             PG8_LDA(At, 0, 1); PG8_STAGE(PG8_SB(0, 0), b2, voffB); PG8_STAGE(PG8_SB(0, 1), b2 + hstep, voffB); PG8_STAGE(PG8_SA(0, 0), a2, voffA); PG8_STAGEX(0, x2);
;             PG8_WAIT_LOOP(); PG8_WAIT_L(0); PG8_BAR; PG8_MMA(1, 0, At, B0); PG8_MMA(1, 1, At, B1); PG8_BAR; PG8_SCHED;
;             PG8_LDB(B0, 1, 0); PG8_LDB(B1, 1, 1); PG8_SCHED; PG8_LDA(At, 1, 0); PG8_LDX(1); PG8_STAGE(PG8_SA(0, 1), a2 + hstepA, voffA);
;             PG8_WAIT_LOOP(); PG8_WAIT_L(0); PG8_BAR; PG8_MMA(0, 0, At, B0); PG8_MMA(0, 1, At, B1); PG8_MMAX(); PG8_BAR; PG8_SCHED;
;             PG8_LDA(At, 1, 1); PG8_STAGE(PG8_SB(1, 0), b3, voffB); PG8_STAGE(PG8_SB(1, 1), b3 + hstep, voffB); PG8_STAGE(PG8_SA(1, 0), a3, voffA); PG8_STAGEX(1, x3);
;             PG8_WAIT_LOOP(); PG8_WAIT_L(0); PG8_BAR; PG8_MMA(1, 0, At, B0); PG8_MMA(1, 1, At, B1); PG8_BAR; PG8_SCHED;
.LBB0_1500:
	s_or_b64 exec, exec, s[4:5]
	s_waitcnt vmcnt(9)
	s_waitcnt lgkmcnt(0)
	s_setprio 1
	s_barrier
	v_mfma_f32_16x16x32_bf16 v[72:75], v[156:159], v[196:199], v[72:75]
	v_mfma_f32_16x16x32_bf16 v[68:71], v[164:167], v[196:199], v[68:71]
	v_mfma_f32_16x16x32_bf16 v[64:67], v[156:159], v[188:191], v[64:67]
	v_mfma_f32_16x16x32_bf16 v[60:63], v[164:167], v[188:191], v[60:63]
	v_mfma_f32_16x16x32_bf16 v[56:59], v[156:159], v[180:183], v[56:59]
	v_mfma_f32_16x16x32_bf16 v[52:55], v[164:167], v[180:183], v[52:55]
	v_mfma_f32_16x16x32_bf16 v[48:51], v[156:159], v[172:175], v[48:51]
	v_mfma_f32_16x16x32_bf16 v[44:47], v[164:167], v[172:175], v[44:47]
	v_mfma_f32_16x16x32_bf16 v[72:75], v[160:163], v[200:203], v[72:75]
	v_mfma_f32_16x16x32_bf16 v[68:71], v[168:171], v[200:203], v[68:71]
	v_mfma_f32_16x16x32_bf16 v[64:67], v[160:163], v[192:195], v[64:67]
	v_mfma_f32_16x16x32_bf16 v[60:63], v[168:171], v[192:195], v[60:63]
	v_mfma_f32_16x16x32_bf16 v[56:59], v[160:163], v[184:187], v[56:59]
	v_mfma_f32_16x16x32_bf16 v[52:55], v[168:171], v[184:187], v[52:55]
	v_mfma_f32_16x16x32_bf16 v[48:51], v[160:163], v[176:179], v[48:51]
	v_mfma_f32_16x16x32_bf16 v[44:47], v[168:171], v[176:179], v[44:47]
	v_mfma_f32_16x16x32_bf16 v[40:43], v[140:143], v[196:199], v[40:43]
	v_mfma_f32_16x16x32_bf16 v[36:39], v[148:151], v[196:199], v[36:39]
	v_mfma_f32_16x16x32_bf16 v[32:35], v[140:143], v[188:191], v[32:35]
	v_mfma_f32_16x16x32_bf16 v[28:31], v[148:151], v[188:191], v[28:31]
	v_mfma_f32_16x16x32_bf16 v[24:27], v[140:143], v[180:183], v[24:27]
	v_mfma_f32_16x16x32_bf16 v[20:23], v[148:151], v[180:183], v[20:23]
	v_mfma_f32_16x16x32_bf16 v[16:19], v[140:143], v[172:175], v[16:19]
	v_mfma_f32_16x16x32_bf16 v[12:15], v[148:151], v[172:175], v[12:15]
	v_mfma_f32_16x16x32_bf16 v[40:43], v[144:147], v[200:203], v[40:43]
	v_mfma_f32_16x16x32_bf16 v[36:39], v[152:155], v[200:203], v[36:39]
	v_mfma_f32_16x16x32_bf16 v[32:35], v[144:147], v[192:195], v[32:35]
	v_mfma_f32_16x16x32_bf16 v[28:31], v[152:155], v[192:195], v[28:31]
	v_mfma_f32_16x16x32_bf16 v[24:27], v[144:147], v[184:187], v[24:27]
	v_mfma_f32_16x16x32_bf16 v[20:23], v[152:155], v[184:187], v[20:23]
	v_mfma_f32_16x16x32_bf16 v[16:19], v[144:147], v[176:179], v[16:19]
	v_mfma_f32_16x16x32_bf16 v[12:15], v[152:155], v[176:179], v[12:15]
	s_barrier
	s_setprio 0
	s_add_i32 s70, s70, 2
	s_cmp_ge_i32 s70, s14
	s_cbranch_scc1 .LBB0_1517
.LBB0_1501:
	s_add_i32 s64, s83, s70
	v_add_u32_e32 v140, 0x10000, v248
	v_add_u32_e32 v152, 0x14000, v248
	s_and_b32 s6, s64, s97
	ds_read_b128 v[156:159], v140
	ds_read_b128 v[160:163], v140 offset:1024
	ds_read_b128 v[164:167], v140 offset:2048
	ds_read_b128 v[168:171], v140 offset:3072
	ds_read_b128 v[140:143], v152
	ds_read_b128 v[144:147], v152 offset:1024
	ds_read_b128 v[148:151], v152 offset:2048
	ds_read_b128 v[152:155], v152 offset:3072
	s_lshr_b32 s84, s6, 2
	s_lshl_b32 s6, s6, 7
	s_lshl_b64 s[4:5], s[84:85], 9
	s_and_b32 s6, s6, 0x100
	s_add_u32 s4, s40, s4
	s_addc_u32 s5, s41, s5
	s_add_u32 s4, s4, s6
	s_addc_u32 s5, s5, 0
	s_add_u32 s4, s4, s28
	s_addc_u32 s5, s5, s29
	v_lshl_add_u64 v[212:213], s[4:5], 0, v[204:205]
	v_add_u32_e32 v176, 0x22400, v250
	v_lshl_add_u64 v[212:213], v[212:213], 0, s[86:87]
	s_add_i32 m0, s90, 0xc000
	ds_read_b128 v[180:183], v249
	ds_read_b128 v[184:187], v249 offset:1024
	ds_read_b128 v[188:191], v249 offset:2048
	ds_read_b128 v[192:195], v249 offset:3072
	ds_read_b128 v[196:199], v249 offset:4096
	ds_read_b128 v[200:203], v249 offset:5120
	ds_read_b128 v[206:209], v249 offset:6144
	ds_read_b128 v[222:225], v249 offset:7168
	ds_read_b128 v[172:175], v176
	ds_read_b128 v[176:179], v176 offset:1024
	global_load_lds_dwordx4 v[212:213], off
	v_lshl_add_u64 v[212:213], s[4:5], 0, v[216:217]
	v_lshl_add_u64 v[212:213], v[212:213], 0, s[86:87]
	s_add_i32 m0, s90, 0xe000
	s_nop 0
	global_load_lds_dwordx4 v[212:213], off
	s_waitcnt vmcnt(9)
	s_waitcnt lgkmcnt(0)
	s_setprio 1
	s_barrier
	v_mfma_f32_16x16x32_bf16 v[136:139], v[156:159], v[180:183], v[136:139]
	v_mfma_f32_16x16x32_bf16 v[132:135], v[164:167], v[180:183], v[132:135]
	v_mfma_f32_16x16x32_bf16 v[128:131], v[156:159], v[188:191], v[128:131]
	v_mfma_f32_16x16x32_bf16 v[124:127], v[164:167], v[188:191], v[124:127]
	v_mfma_f32_16x16x32_bf16 v[120:123], v[156:159], v[196:199], v[120:123]
	v_mfma_f32_16x16x32_bf16 v[116:119], v[164:167], v[196:199], v[116:119]
	v_mfma_f32_16x16x32_bf16 v[112:115], v[156:159], v[206:209], v[112:115]
	v_mfma_f32_16x16x32_bf16 v[108:111], v[164:167], v[206:209], v[108:111]
	v_mfma_f32_16x16x32_bf16 v[136:139], v[160:163], v[184:187], v[136:139]
	v_mfma_f32_16x16x32_bf16 v[132:135], v[168:171], v[184:187], v[132:135]
	v_mfma_f32_16x16x32_bf16 v[128:131], v[160:163], v[192:195], v[128:131]
	v_mfma_f32_16x16x32_bf16 v[124:127], v[168:171], v[192:195], v[124:127]
	v_mfma_f32_16x16x32_bf16 v[120:123], v[160:163], v[200:203], v[120:123]
	v_mfma_f32_16x16x32_bf16 v[116:119], v[168:171], v[200:203], v[116:119]
	v_mfma_f32_16x16x32_bf16 v[112:115], v[160:163], v[222:225], v[112:115]
	v_mfma_f32_16x16x32_bf16 v[108:111], v[168:171], v[222:225], v[108:111]
	v_mfma_f32_16x16x32_bf16 v[104:107], v[140:143], v[180:183], v[104:107]
	v_mfma_f32_16x16x32_bf16 v[100:103], v[148:151], v[180:183], v[100:103]
	v_mfma_f32_16x16x32_bf16 v[96:99], v[140:143], v[188:191], v[96:99]
	v_mfma_f32_16x16x32_bf16 v[92:95], v[148:151], v[188:191], v[92:95]
	v_mfma_f32_16x16x32_bf16 v[88:91], v[140:143], v[196:199], v[88:91]
	v_mfma_f32_16x16x32_bf16 v[84:87], v[148:151], v[196:199], v[84:87]
	v_mfma_f32_16x16x32_bf16 v[80:83], v[140:143], v[206:209], v[80:83]
	v_mfma_f32_16x16x32_bf16 v[76:79], v[148:151], v[206:209], v[76:79]
	v_mfma_f32_16x16x32_bf16 v[104:107], v[144:147], v[184:187], v[104:107]
	v_mfma_f32_16x16x32_bf16 v[100:103], v[152:155], v[184:187], v[100:103]
	v_mfma_f32_16x16x32_bf16 v[96:99], v[144:147], v[192:195], v[96:99]
	v_mfma_f32_16x16x32_bf16 v[92:95], v[152:155], v[192:195], v[92:95]
	v_mfma_f32_16x16x32_bf16 v[88:91], v[144:147], v[200:203], v[88:91]
	v_mfma_f32_16x16x32_bf16 v[84:87], v[152:155], v[200:203], v[84:87]
	v_mfma_f32_16x16x32_bf16 v[80:83], v[144:147], v[222:225], v[80:83]
	v_mfma_f32_16x16x32_bf16 v[76:79], v[152:155], v[222:225], v[76:79]
	s_setprio 0
	v_cndmask_b32_e64 v180, 0, 1, s[46:47]
	v_cmp_ne_u32_e64 s[6:7], 1, v180
	v_cndmask_b32_e64 v180, 0, 1, s[52:53]
	s_andn2_b64 vcc, exec, s[46:47]
	v_cmp_ne_u32_e64 s[4:5], 1, v180
	s_cbranch_vccnz .LBB0_1507
	s_setprio 1
	s_and_b64 vcc, exec, s[4:5]
	s_mov_b64 s[62:63], -1
	s_cbranch_vccnz .LBB0_1504
	v_mfma_f32_16x16x32_bf16 v[8:11], v[140:143], v[172:175], v[8:11]
	s_mov_b64 s[62:63], 0
	v_mfma_f32_16x16x32_bf16 v[4:7], v[148:151], v[172:175], v[4:7]
	v_mfma_f32_16x16x32_bf16 v[8:11], v[144:147], v[176:179], v[8:11]
	v_mfma_f32_16x16x32_bf16 v[4:7], v[152:155], v[176:179], v[4:7]

; #define PG8_LDX(b) do { if constexpr (XR) { _Pragma("unroll") for (int k = 0; k < 2; ++k) Ax_[k] = *(const PG8_LAS bf16x8*)(lds + XR_OFF + (b) * 2048 + aoffx + k * 1024); } } while (0)
; #define PG8_MMAX() do { if constexpr (XR) { if (hasx) { __builtin_amdgcn_s_setprio(1); if (wr == 0) PG8_MMAX_(B0); else PG8_MMAX_(B1); __builtin_amdgcn_s_setprio(0); } } } while (0)
; #define PG8_WAIT_LOOP() do { if constexpr (XR) PG8_WAIT_V(9); else PG8_WAIT_V(8); } while (0)
; #define PG8_STAGE(bufoff, gbase, voff) do { _Pragma("unroll") for (int _i = 0; _i < 2; ++_i) \
;         __builtin_amdgcn_global_load_lds((const unsigned*)((const char*)(gbase) + (voff)[_i]), (PG8_LAS unsigned*)(lds + (bufoff) + ldsw + _i * 8192), 16, 0, 0); } while (0)
; #define PG8_LDA(dst, b, h) do { _Pragma("unroll") for (int m = 0; m < 4; ++m) _Pragma("unroll") for (int k = 0; k < 2; ++k) dst[m][k] = *(const PG8_LAS bf16x8*)(lds + PG8_SA(b, h) + aoff + m * 2048 + k * 1024); } while (0)
; #define PG8_LDB(dst, b, h) do { _Pragma("unroll") for (int n = 0; n < 2; ++n) _Pragma("unroll") for (int k = 0; k < 2; ++k) dst[n][k] = *(const PG8_LAS bf16x8*)(lds + PG8_SB(b, h) + boff + n * 2048 + k * 1024); } while (0)
; #define PG8_MMA(ai, bj, At, Bt) do { __builtin_amdgcn_s_setprio(1); _Pragma("unroll") for (int m = 0; m < 4; ++m) _Pragma("unroll") for (int n = 0; n < 2; ++n) _Pragma("unroll") for (int k = 0; k < 2; ++k) \
;         acc[ai][bj][m][n] = __builtin_amdgcn_mfma_f32_16x16x32_bf16(Bt[n][k], At[m][k], acc[ai][bj][m][n], 0, 0, 0); __builtin_amdgcn_s_setprio(0); } while (0)
; #define PG8_WAIT_L(n) asm volatile("s_waitcnt lgkmcnt(" #n ")" ::: "memory")
; #define PG8_BAR __builtin_amdgcn_s_barrier()
; #define PG8_SCHED __builtin_amdgcn_sched_barrier(0)
; template <class Epi, class Sched, bool ALIGN_EPI = false, bool SP2 = false, bool DRAIN = true, bool XR = false>
; __device__ __forceinline__ void gemm_phase(PG8_LAS unsigned char* lds, const Gemm g, const Sched& S, const Epi& E) {
;     ...
;             PG8_WAIT_LOOP(); PG8_WAIT_L(0); PG8_BAR; PG8_MMA(1, 0, At, B0); PG8_MMA(1, 1, At, B1); PG8_BAR; PG8_SCHED;
;             PG8_LDB(B0, 1, 0); PG8_LDB(B1, 1, 1); PG8_SCHED; PG8_LDA(At, 1, 0); PG8_LDX(1); PG8_STAGE(PG8_SA(0, 1), a2 + hstepA, voffA);
;             PG8_WAIT_LOOP(); PG8_WAIT_L(0); PG8_BAR; PG8_MMA(0, 0, At, B0); PG8_MMA(0, 1, At, B1); PG8_MMAX(); PG8_BAR; PG8_SCHED;
.LBB0_1509:
	s_or_b64 exec, exec, s[64:65]
	s_waitcnt vmcnt(9)
	s_waitcnt lgkmcnt(0)
	s_setprio 1
	s_barrier
	v_mfma_f32_16x16x32_bf16 v[72:75], v[156:159], v[196:199], v[72:75]
	v_mfma_f32_16x16x32_bf16 v[68:71], v[164:167], v[196:199], v[68:71]
	v_mfma_f32_16x16x32_bf16 v[64:67], v[156:159], v[188:191], v[64:67]
	v_mfma_f32_16x16x32_bf16 v[60:63], v[164:167], v[188:191], v[60:63]
	v_mfma_f32_16x16x32_bf16 v[56:59], v[156:159], v[180:183], v[56:59]
	v_mfma_f32_16x16x32_bf16 v[52:55], v[164:167], v[180:183], v[52:55]
	v_mfma_f32_16x16x32_bf16 v[48:51], v[156:159], v[172:175], v[48:51]
	v_mfma_f32_16x16x32_bf16 v[44:47], v[164:167], v[172:175], v[44:47]
	v_mfma_f32_16x16x32_bf16 v[72:75], v[160:163], v[200:203], v[72:75]
	v_mfma_f32_16x16x32_bf16 v[68:71], v[168:171], v[200:203], v[68:71]
	v_mfma_f32_16x16x32_bf16 v[64:67], v[160:163], v[192:195], v[64:67]
	v_mfma_f32_16x16x32_bf16 v[60:63], v[168:171], v[192:195], v[60:63]
	v_mfma_f32_16x16x32_bf16 v[56:59], v[160:163], v[184:187], v[56:59]
	v_mfma_f32_16x16x32_bf16 v[52:55], v[168:171], v[184:187], v[52:55]
	v_mfma_f32_16x16x32_bf16 v[48:51], v[160:163], v[176:179], v[48:51]
	v_mfma_f32_16x16x32_bf16 v[44:47], v[168:171], v[176:179], v[44:47]
	v_mfma_f32_16x16x32_bf16 v[40:43], v[140:143], v[196:199], v[40:43]
	v_mfma_f32_16x16x32_bf16 v[36:39], v[148:151], v[196:199], v[36:39]
	v_mfma_f32_16x16x32_bf16 v[32:35], v[140:143], v[188:191], v[32:35]
	v_mfma_f32_16x16x32_bf16 v[28:31], v[148:151], v[188:191], v[28:31]
	v_mfma_f32_16x16x32_bf16 v[24:27], v[140:143], v[180:183], v[24:27]
	v_mfma_f32_16x16x32_bf16 v[20:23], v[148:151], v[180:183], v[20:23]
	v_mfma_f32_16x16x32_bf16 v[16:19], v[140:143], v[172:175], v[16:19]
	v_mfma_f32_16x16x32_bf16 v[12:15], v[148:151], v[172:175], v[12:15]
	v_mfma_f32_16x16x32_bf16 v[40:43], v[144:147], v[200:203], v[40:43]
	v_mfma_f32_16x16x32_bf16 v[36:39], v[152:155], v[200:203], v[36:39]
	v_mfma_f32_16x16x32_bf16 v[32:35], v[144:147], v[192:195], v[32:35]
	v_mfma_f32_16x16x32_bf16 v[28:31], v[152:155], v[192:195], v[28:31]
	v_mfma_f32_16x16x32_bf16 v[24:27], v[144:147], v[184:187], v[24:27]
	v_mfma_f32_16x16x32_bf16 v[20:23], v[152:155], v[184:187], v[20:23]
	v_mfma_f32_16x16x32_bf16 v[16:19], v[144:147], v[176:179], v[16:19]
	v_mfma_f32_16x16x32_bf16 v[12:15], v[152:155], v[176:179], v[12:15]
	s_barrier
	s_setprio 0
	v_add_u32_e32 v140, 0x18000, v248
	v_add_u32_e32 v152, 0x1c000, v248
	ds_read_b128 v[156:159], v140
	ds_read_b128 v[160:163], v140 offset:1024
	ds_read_b128 v[164:167], v140 offset:2048
	ds_read_b128 v[168:171], v140 offset:3072
	ds_read_b128 v[140:143], v152
	ds_read_b128 v[144:147], v152 offset:1024
	ds_read_b128 v[148:151], v152 offset:2048
	ds_read_b128 v[152:155], v152 offset:3072
	s_add_u32 s62, s62, s28
	s_addc_u32 s63, s63, s29
	s_mov_b32 m0, s12
	v_add_u32_e32 v176, 0x22c00, v250
	v_lshl_add_u64 v[212:213], s[62:63], 0, v[204:205]
	ds_read_b128 v[180:183], v249 offset:32768
	ds_read_b128 v[184:187], v249 offset:33792
	ds_read_b128 v[188:191], v249 offset:34816
	ds_read_b128 v[192:195], v249 offset:35840
	ds_read_b128 v[196:199], v249 offset:36864
	ds_read_b128 v[200:203], v249 offset:37888
	ds_read_b128 v[206:209], v249 offset:38912
	ds_read_b128 v[242:245], v249 offset:39936
	ds_read_b128 v[172:175], v176
	ds_read_b128 v[176:179], v176 offset:1024
	global_load_lds_dwordx4 v[212:213], off
	v_lshl_add_u64 v[212:213], s[62:63], 0, v[216:217]
	s_mov_b32 m0, s13
	s_nop 0
	global_load_lds_dwordx4 v[212:213], off
	s_waitcnt vmcnt(9)
	s_waitcnt lgkmcnt(0)
	s_setprio 1
	s_barrier
	v_mfma_f32_16x16x32_bf16 v[136:139], v[156:159], v[180:183], v[136:139]
	v_mfma_f32_16x16x32_bf16 v[132:135], v[164:167], v[180:183], v[132:135]
	v_mfma_f32_16x16x32_bf16 v[128:131], v[156:159], v[188:191], v[128:131]
	v_mfma_f32_16x16x32_bf16 v[124:127], v[164:167], v[188:191], v[124:127]
	v_mfma_f32_16x16x32_bf16 v[120:123], v[156:159], v[196:199], v[120:123]
	v_mfma_f32_16x16x32_bf16 v[116:119], v[164:167], v[196:199], v[116:119]
	v_mfma_f32_16x16x32_bf16 v[112:115], v[156:159], v[206:209], v[112:115]
	v_mfma_f32_16x16x32_bf16 v[108:111], v[164:167], v[206:209], v[108:111]
	v_mfma_f32_16x16x32_bf16 v[136:139], v[160:163], v[184:187], v[136:139]
	v_mfma_f32_16x16x32_bf16 v[132:135], v[168:171], v[184:187], v[132:135]
	v_mfma_f32_16x16x32_bf16 v[128:131], v[160:163], v[192:195], v[128:131]
	v_mfma_f32_16x16x32_bf16 v[124:127], v[168:171], v[192:195], v[124:127]
	v_mfma_f32_16x16x32_bf16 v[120:123], v[160:163], v[200:203], v[120:123]
	v_mfma_f32_16x16x32_bf16 v[116:119], v[168:171], v[200:203], v[116:119]
	v_mfma_f32_16x16x32_bf16 v[112:115], v[160:163], v[242:245], v[112:115]
	v_mfma_f32_16x16x32_bf16 v[108:111], v[168:171], v[242:245], v[108:111]
	v_mfma_f32_16x16x32_bf16 v[104:107], v[140:143], v[180:183], v[104:107]
	v_mfma_f32_16x16x32_bf16 v[100:103], v[148:151], v[180:183], v[100:103]
	v_mfma_f32_16x16x32_bf16 v[96:99], v[140:143], v[188:191], v[96:99]
	v_mfma_f32_16x16x32_bf16 v[92:95], v[148:151], v[188:191], v[92:95]
	v_mfma_f32_16x16x32_bf16 v[88:91], v[140:143], v[196:199], v[88:91]
	v_mfma_f32_16x16x32_bf16 v[84:87], v[148:151], v[196:199], v[84:87]
	v_mfma_f32_16x16x32_bf16 v[80:83], v[140:143], v[206:209], v[80:83]
	v_mfma_f32_16x16x32_bf16 v[76:79], v[148:151], v[206:209], v[76:79]
	v_mfma_f32_16x16x32_bf16 v[104:107], v[144:147], v[184:187], v[104:107]
	v_mfma_f32_16x16x32_bf16 v[100:103], v[152:155], v[184:187], v[100:103]
	v_mfma_f32_16x16x32_bf16 v[96:99], v[144:147], v[192:195], v[96:99]
	v_mfma_f32_16x16x32_bf16 v[92:95], v[152:155], v[192:195], v[92:95]
	v_mfma_f32_16x16x32_bf16 v[88:91], v[144:147], v[200:203], v[88:91]
	v_mfma_f32_16x16x32_bf16 v[84:87], v[152:155], v[200:203], v[84:87]
	v_mfma_f32_16x16x32_bf16 v[80:83], v[144:147], v[242:245], v[80:83]
	v_mfma_f32_16x16x32_bf16 v[76:79], v[152:155], v[242:245], v[76:79]
	s_setprio 0
	s_and_b64 vcc, exec, s[6:7]
	s_cbranch_vccnz .LBB0_1515
	s_setprio 1
	s_and_b64 vcc, exec, s[4:5]
	s_mov_b64 s[4:5], -1
	s_cbranch_vccnz .LBB0_1512
	v_mfma_f32_16x16x32_bf16 v[8:11], v[140:143], v[172:175], v[8:11]
	s_mov_b64 s[4:5], 0
	v_mfma_f32_16x16x32_bf16 v[4:7], v[148:151], v[172:175], v[4:7]
	v_mfma_f32_16x16x32_bf16 v[8:11], v[144:147], v[176:179], v[8:11]
	v_mfma_f32_16x16x32_bf16 v[4:7], v[152:155], v[176:179], v[4:7]

; #define PG8_STAGEX(b, gbase) do { if constexpr (XR) { if (lane < 16) __builtin_amdgcn_global_load_lds((const unsigned*)((const char*)(gbase) + voffX), (PG8_LAS unsigned*)(lds + XR_OFF + (b) * 2048 + wid * 256), 16, 0, 0); } } while (0)
; #define PG8_LDX(b) do { if constexpr (XR) { _Pragma("unroll") for (int k = 0; k < 2; ++k) Ax_[k] = *(const PG8_LAS bf16x8*)(lds + XR_OFF + (b) * 2048 + aoffx + k * 1024); } } while (0)
; #define PG8_MMAX() do { if constexpr (XR) { if (hasx) { __builtin_amdgcn_s_setprio(1); if (wr == 0) PG8_MMAX_(B0); else PG8_MMAX_(B1); __builtin_amdgcn_s_setprio(0); } } } while (0)
; #define PG8_WAIT_LOOP() do { if constexpr (XR) PG8_WAIT_V(9); else PG8_WAIT_V(8); } while (0)
; #define PG8_STAGE(bufoff, gbase, voff) do { _Pragma("unroll") for (int _i = 0; _i < 2; ++_i) \
;         __builtin_amdgcn_global_load_lds((const unsigned*)((const char*)(gbase) + (voff)[_i]), (PG8_LAS unsigned*)(lds + (bufoff) + ldsw + _i * 8192), 16, 0, 0); } while (0)
; #define PG8_BAR __builtin_amdgcn_s_barrier()
; template <class Epi, class Sched, bool ALIGN_EPI = false, bool SP2 = false, bool DRAIN = true, bool XR = false>
; __device__ __forceinline__ void gemm_phase(PG8_LAS unsigned char* lds, const Gemm g, const Sched& S, const Epi& E) {
;     ...
;             PG8_LDB(B0, 0, 0); PG8_LDB(B1, 0, 1); PG8_SCHED; PG8_LDA(At, 0, 0); PG8_LDX(0); PG8_STAGE(PG8_SA(1, 1), a1 + hstepA, voffA);
;             PG8_WAIT_LOOP(); PG8_WAIT_L(0); PG8_BAR; PG8_MMA(0, 0, At, B0); PG8_MMA(0, 1, At, B1); PG8_MMAX(); PG8_BAR; PG8_SCHED;
;             PG8_LDA(At, 0, 1); PG8_STAGE(PG8_SB(0, 0), b2, voffB); PG8_STAGE(PG8_SB(0, 1), b2 + hstep, voffB); PG8_STAGE(PG8_SA(0, 0), a2, voffA); PG8_STAGEX(0, x2);
;             PG8_WAIT_LOOP(); PG8_WAIT_L(0); PG8_BAR; PG8_MMA(1, 0, At, B0); PG8_MMA(1, 1, At, B1); PG8_BAR; PG8_SCHED;
;             PG8_LDB(B0, 1, 0); PG8_LDB(B1, 1, 1); PG8_SCHED; PG8_LDA(At, 1, 0); PG8_LDX(1); PG8_STAGE(PG8_SA(0, 1), a2 + hstepA, voffA);
;             PG8_WAIT_LOOP(); PG8_WAIT_L(0); PG8_BAR; PG8_MMA(0, 0, At, B0); PG8_MMA(0, 1, At, B1); PG8_MMAX(); PG8_BAR; PG8_SCHED;
;             PG8_LDA(At, 1, 1); PG8_STAGE(PG8_SB(1, 0), b3, voffB); PG8_STAGE(PG8_SB(1, 1), b3 + hstep, voffB); PG8_STAGE(PG8_SA(1, 0), a3, voffA); PG8_STAGEX(1, x3);
;             PG8_WAIT_LOOP(); PG8_WAIT_L(0); PG8_BAR; PG8_MMA(1, 0, At, B0); PG8_MMA(1, 1, At, B1); PG8_BAR; PG8_SCHED;
.LBB0_1651:
	s_or_b64 exec, exec, s[0:1]
	s_waitcnt vmcnt(9)
	s_waitcnt lgkmcnt(0)
	s_setprio 1
	s_barrier
	v_mfma_f32_16x16x32_bf16 v[74:77], v[158:161], v[198:201], v[74:77]
	v_mfma_f32_16x16x32_bf16 v[70:73], v[166:169], v[198:201], v[70:73]
	v_mfma_f32_16x16x32_bf16 v[58:61], v[158:161], v[190:193], v[58:61]
	v_mfma_f32_16x16x32_bf16 v[54:57], v[166:169], v[190:193], v[54:57]
	v_mfma_f32_16x16x32_bf16 v[42:45], v[158:161], v[182:185], v[42:45]
	v_mfma_f32_16x16x32_bf16 v[38:41], v[166:169], v[182:185], v[38:41]
	v_mfma_f32_16x16x32_bf16 v[26:29], v[158:161], v[174:177], v[26:29]
	v_mfma_f32_16x16x32_bf16 v[22:25], v[166:169], v[174:177], v[22:25]
	v_mfma_f32_16x16x32_bf16 v[74:77], v[162:165], v[202:205], v[74:77]
	v_mfma_f32_16x16x32_bf16 v[70:73], v[170:173], v[202:205], v[70:73]
	v_mfma_f32_16x16x32_bf16 v[58:61], v[162:165], v[194:197], v[58:61]
	v_mfma_f32_16x16x32_bf16 v[54:57], v[170:173], v[194:197], v[54:57]
	v_mfma_f32_16x16x32_bf16 v[42:45], v[162:165], v[186:189], v[42:45]
	v_mfma_f32_16x16x32_bf16 v[38:41], v[170:173], v[186:189], v[38:41]
	v_mfma_f32_16x16x32_bf16 v[26:29], v[162:165], v[178:181], v[26:29]
	v_mfma_f32_16x16x32_bf16 v[22:25], v[170:173], v[178:181], v[22:25]
	v_mfma_f32_16x16x32_bf16 v[66:69], v[142:145], v[198:201], v[66:69]
	v_mfma_f32_16x16x32_bf16 v[62:65], v[150:153], v[198:201], v[62:65]
	v_mfma_f32_16x16x32_bf16 v[50:53], v[142:145], v[190:193], v[50:53]
	v_mfma_f32_16x16x32_bf16 v[46:49], v[150:153], v[190:193], v[46:49]
	v_mfma_f32_16x16x32_bf16 v[34:37], v[142:145], v[182:185], v[34:37]
	v_mfma_f32_16x16x32_bf16 v[30:33], v[150:153], v[182:185], v[30:33]
	v_mfma_f32_16x16x32_bf16 v[18:21], v[142:145], v[174:177], v[18:21]
	v_mfma_f32_16x16x32_bf16 v[14:17], v[150:153], v[174:177], v[14:17]
	v_mfma_f32_16x16x32_bf16 v[66:69], v[146:149], v[202:205], v[66:69]
	v_mfma_f32_16x16x32_bf16 v[62:65], v[154:157], v[202:205], v[62:65]
	v_mfma_f32_16x16x32_bf16 v[50:53], v[146:149], v[194:197], v[50:53]
	v_mfma_f32_16x16x32_bf16 v[46:49], v[154:157], v[194:197], v[46:49]
	v_mfma_f32_16x16x32_bf16 v[34:37], v[146:149], v[186:189], v[34:37]
	v_mfma_f32_16x16x32_bf16 v[30:33], v[154:157], v[186:189], v[30:33]
	v_mfma_f32_16x16x32_bf16 v[18:21], v[146:149], v[178:181], v[18:21]
	v_mfma_f32_16x16x32_bf16 v[14:17], v[154:157], v[178:181], v[14:17]
	s_barrier
	s_setprio 0
	s_add_i32 s89, s89, 2
	s_cmp_ge_i32 s89, s58
	s_cbranch_scc1 .LBB0_1669
.LBB0_1652:
	v_add_u32_e32 v2, 0x10000, v248
	s_add_i32 s46, s54, s89
	ds_read_b128 v[158:161], v2
	ds_read_b128 v[162:165], v2 offset:1024
	ds_read_b128 v[166:169], v2 offset:2048
	ds_read_b128 v[170:173], v2 offset:3072
	v_add_u32_e32 v2, 0x14000, v248
	s_and_b32 s6, s46, s59
	ds_read_b128 v[142:145], v2
	ds_read_b128 v[146:149], v2 offset:1024
	ds_read_b128 v[150:153], v2 offset:2048
	ds_read_b128 v[154:157], v2 offset:3072
	s_lshr_b32 s84, s6, 2
	s_lshl_b32 s6, s6, 7
	s_lshl_b64 s[0:1], s[84:85], 17
	s_and_b32 s6, s6, 0x100
	s_add_u32 s0, s40, s0
	s_addc_u32 s1, s41, s1
	s_add_u32 s0, s0, s6
	s_addc_u32 s1, s1, 0
	s_add_u32 s0, s0, 0x10080
	s_addc_u32 s1, s1, 0
	v_add_u32_e32 v2, 0x22400, v250
	v_lshl_add_u64 v[4:5], s[0:1], 0, v[214:215]
	s_add_i32 m0, s63, 0xc000
	ds_read_b128 v[182:185], v249
	ds_read_b128 v[186:189], v249 offset:1024
	ds_read_b128 v[190:193], v249 offset:2048
	ds_read_b128 v[194:197], v249 offset:3072
	ds_read_b128 v[198:201], v249 offset:4096
	ds_read_b128 v[202:205], v249 offset:5120
	ds_read_b128 v[206:209], v249 offset:6144
	ds_read_b128 v[224:227], v249 offset:7168
	ds_read_b128 v[174:177], v2
	ds_read_b128 v[178:181], v2 offset:1024
	global_load_lds_dwordx4 v[4:5], off
	v_lshl_add_u64 v[4:5], s[0:1], 0, v[218:219]
	s_add_i32 m0, s63, 0xe000
	s_nop 0
	global_load_lds_dwordx4 v[4:5], off
	s_waitcnt vmcnt(9)
	s_waitcnt lgkmcnt(0)
	s_setprio 1
	s_barrier
	v_mfma_f32_16x16x32_bf16 v[138:141], v[158:161], v[182:185], v[138:141]
	v_mfma_f32_16x16x32_bf16 v[134:137], v[166:169], v[182:185], v[134:137]
	v_mfma_f32_16x16x32_bf16 v[122:125], v[158:161], v[190:193], v[122:125]
	v_mfma_f32_16x16x32_bf16 v[118:121], v[166:169], v[190:193], v[118:121]
	v_mfma_f32_16x16x32_bf16 v[106:109], v[158:161], v[198:201], v[106:109]
	v_mfma_f32_16x16x32_bf16 v[102:105], v[166:169], v[198:201], v[102:105]
	v_mfma_f32_16x16x32_bf16 v[90:93], v[158:161], v[206:209], v[90:93]
	v_mfma_f32_16x16x32_bf16 v[86:89], v[166:169], v[206:209], v[86:89]
	v_mfma_f32_16x16x32_bf16 v[138:141], v[162:165], v[186:189], v[138:141]
	v_mfma_f32_16x16x32_bf16 v[134:137], v[170:173], v[186:189], v[134:137]
	v_mfma_f32_16x16x32_bf16 v[122:125], v[162:165], v[194:197], v[122:125]
	v_mfma_f32_16x16x32_bf16 v[118:121], v[170:173], v[194:197], v[118:121]
	v_mfma_f32_16x16x32_bf16 v[106:109], v[162:165], v[202:205], v[106:109]
	v_mfma_f32_16x16x32_bf16 v[102:105], v[170:173], v[202:205], v[102:105]
	v_mfma_f32_16x16x32_bf16 v[90:93], v[162:165], v[224:227], v[90:93]
	v_mfma_f32_16x16x32_bf16 v[86:89], v[170:173], v[224:227], v[86:89]
	v_mfma_f32_16x16x32_bf16 v[130:133], v[142:145], v[182:185], v[130:133]
	v_mfma_f32_16x16x32_bf16 v[126:129], v[150:153], v[182:185], v[126:129]
	v_mfma_f32_16x16x32_bf16 v[114:117], v[142:145], v[190:193], v[114:117]
	v_mfma_f32_16x16x32_bf16 v[110:113], v[150:153], v[190:193], v[110:113]
	v_mfma_f32_16x16x32_bf16 v[98:101], v[142:145], v[198:201], v[98:101]
	v_mfma_f32_16x16x32_bf16 v[94:97], v[150:153], v[198:201], v[94:97]
	v_mfma_f32_16x16x32_bf16 v[82:85], v[142:145], v[206:209], v[82:85]
	v_mfma_f32_16x16x32_bf16 v[78:81], v[150:153], v[206:209], v[78:81]
	v_mfma_f32_16x16x32_bf16 v[130:133], v[146:149], v[186:189], v[130:133]
	v_mfma_f32_16x16x32_bf16 v[126:129], v[154:157], v[186:189], v[126:129]
	v_mfma_f32_16x16x32_bf16 v[114:117], v[146:149], v[194:197], v[114:117]
	v_mfma_f32_16x16x32_bf16 v[110:113], v[154:157], v[194:197], v[110:113]
	v_mfma_f32_16x16x32_bf16 v[98:101], v[146:149], v[202:205], v[98:101]
	v_mfma_f32_16x16x32_bf16 v[94:97], v[154:157], v[202:205], v[94:97]
	v_mfma_f32_16x16x32_bf16 v[82:85], v[146:149], v[224:227], v[82:85]
	v_mfma_f32_16x16x32_bf16 v[78:81], v[154:157], v[224:227], v[78:81]
	s_setprio 0
	v_cndmask_b32_e64 v2, 0, 1, s[30:31]
	v_cmp_ne_u32_e64 s[6:7], 1, v2
	v_cndmask_b32_e64 v2, 0, 1, s[22:23]
	s_andn2_b64 vcc, exec, s[30:31]
	v_cmp_ne_u32_e64 s[0:1], 1, v2
	s_cbranch_vccnz .LBB0_1658
	s_setprio 1
	s_and_b64 vcc, exec, s[0:1]
	s_mov_b64 s[44:45], -1
	s_cbranch_vccnz .LBB0_1655
	v_mfma_f32_16x16x32_bf16 v[10:13], v[142:145], v[174:177], v[10:13]
	s_mov_b64 s[44:45], 0
	v_mfma_f32_16x16x32_bf16 v[6:9], v[150:153], v[174:177], v[6:9]
	v_mfma_f32_16x16x32_bf16 v[10:13], v[146:149], v[178:181], v[10:13]
	v_mfma_f32_16x16x32_bf16 v[6:9], v[154:157], v[178:181], v[6:9]

; #define PG8_LDX(b) do { if constexpr (XR) { _Pragma("unroll") for (int k = 0; k < 2; ++k) Ax_[k] = *(const PG8_LAS bf16x8*)(lds + XR_OFF + (b) * 2048 + aoffx + k * 1024); } } while (0)
; #define PG8_MMAX() do { if constexpr (XR) { if (hasx) { __builtin_amdgcn_s_setprio(1); if (wr == 0) PG8_MMAX_(B0); else PG8_MMAX_(B1); __builtin_amdgcn_s_setprio(0); } } } while (0)
; #define PG8_WAIT_LOOP() do { if constexpr (XR) PG8_WAIT_V(9); else PG8_WAIT_V(8); } while (0)
; #define PG8_STAGE(bufoff, gbase, voff) do { _Pragma("unroll") for (int _i = 0; _i < 2; ++_i) \
;         __builtin_amdgcn_global_load_lds((const unsigned*)((const char*)(gbase) + (voff)[_i]), (PG8_LAS unsigned*)(lds + (bufoff) + ldsw + _i * 8192), 16, 0, 0); } while (0)
; #define PG8_LDA(dst, b, h) do { _Pragma("unroll") for (int m = 0; m < 4; ++m) _Pragma("unroll") for (int k = 0; k < 2; ++k) dst[m][k] = *(const PG8_LAS bf16x8*)(lds + PG8_SA(b, h) + aoff + m * 2048 + k * 1024); } while (0)
; #define PG8_LDB(dst, b, h) do { _Pragma("unroll") for (int n = 0; n < 2; ++n) _Pragma("unroll") for (int k = 0; k < 2; ++k) dst[n][k] = *(const PG8_LAS bf16x8*)(lds + PG8_SB(b, h) + boff + n * 2048 + k * 1024); } while (0)
; #define PG8_MMA(ai, bj, At, Bt) do { __builtin_amdgcn_s_setprio(1); _Pragma("unroll") for (int m = 0; m < 4; ++m) _Pragma("unroll") for (int n = 0; n < 2; ++n) _Pragma("unroll") for (int k = 0; k < 2; ++k) \
;         acc[ai][bj][m][n] = __builtin_amdgcn_mfma_f32_16x16x32_bf16(Bt[n][k], At[m][k], acc[ai][bj][m][n], 0, 0, 0); __builtin_amdgcn_s_setprio(0); } while (0)
; #define PG8_WAIT_L(n) asm volatile("s_waitcnt lgkmcnt(" #n ")" ::: "memory")
; #define PG8_BAR __builtin_amdgcn_s_barrier()
; #define PG8_SCHED __builtin_amdgcn_sched_barrier(0)
; template <class Epi, class Sched, bool ALIGN_EPI = false, bool SP2 = false, bool DRAIN = true, bool XR = false>
; __device__ __forceinline__ void gemm_phase(PG8_LAS unsigned char* lds, const Gemm g, const Sched& S, const Epi& E) {
;     ...
;             PG8_WAIT_LOOP(); PG8_WAIT_L(0); PG8_BAR; PG8_MMA(1, 0, At, B0); PG8_MMA(1, 1, At, B1); PG8_BAR; PG8_SCHED;
;             PG8_LDB(B0, 1, 0); PG8_LDB(B1, 1, 1); PG8_SCHED; PG8_LDA(At, 1, 0); PG8_LDX(1); PG8_STAGE(PG8_SA(0, 1), a2 + hstepA, voffA);
;             PG8_WAIT_LOOP(); PG8_WAIT_L(0); PG8_BAR; PG8_MMA(0, 0, At, B0); PG8_MMA(0, 1, At, B1); PG8_MMAX(); PG8_BAR; PG8_SCHED;
.LBB0_1660:
	s_or_b64 exec, exec, s[46:47]
	s_waitcnt vmcnt(9)
	s_waitcnt lgkmcnt(0)
	s_setprio 1
	s_barrier
	v_mfma_f32_16x16x32_bf16 v[74:77], v[158:161], v[198:201], v[74:77]
	v_mfma_f32_16x16x32_bf16 v[70:73], v[166:169], v[198:201], v[70:73]
	v_mfma_f32_16x16x32_bf16 v[58:61], v[158:161], v[190:193], v[58:61]
	v_mfma_f32_16x16x32_bf16 v[54:57], v[166:169], v[190:193], v[54:57]
	v_mfma_f32_16x16x32_bf16 v[42:45], v[158:161], v[182:185], v[42:45]
	v_mfma_f32_16x16x32_bf16 v[38:41], v[166:169], v[182:185], v[38:41]
	v_mfma_f32_16x16x32_bf16 v[26:29], v[158:161], v[174:177], v[26:29]
	v_mfma_f32_16x16x32_bf16 v[22:25], v[166:169], v[174:177], v[22:25]
	v_mfma_f32_16x16x32_bf16 v[74:77], v[162:165], v[202:205], v[74:77]
	v_mfma_f32_16x16x32_bf16 v[70:73], v[170:173], v[202:205], v[70:73]
	v_mfma_f32_16x16x32_bf16 v[58:61], v[162:165], v[194:197], v[58:61]
	v_mfma_f32_16x16x32_bf16 v[54:57], v[170:173], v[194:197], v[54:57]
	v_mfma_f32_16x16x32_bf16 v[42:45], v[162:165], v[186:189], v[42:45]
	v_mfma_f32_16x16x32_bf16 v[38:41], v[170:173], v[186:189], v[38:41]
	v_mfma_f32_16x16x32_bf16 v[26:29], v[162:165], v[178:181], v[26:29]
	v_mfma_f32_16x16x32_bf16 v[22:25], v[170:173], v[178:181], v[22:25]
	v_mfma_f32_16x16x32_bf16 v[66:69], v[142:145], v[198:201], v[66:69]
	v_mfma_f32_16x16x32_bf16 v[62:65], v[150:153], v[198:201], v[62:65]
	v_mfma_f32_16x16x32_bf16 v[50:53], v[142:145], v[190:193], v[50:53]
	v_mfma_f32_16x16x32_bf16 v[46:49], v[150:153], v[190:193], v[46:49]
	v_mfma_f32_16x16x32_bf16 v[34:37], v[142:145], v[182:185], v[34:37]
	v_mfma_f32_16x16x32_bf16 v[30:33], v[150:153], v[182:185], v[30:33]
	v_mfma_f32_16x16x32_bf16 v[18:21], v[142:145], v[174:177], v[18:21]
	v_mfma_f32_16x16x32_bf16 v[14:17], v[150:153], v[174:177], v[14:17]
	v_mfma_f32_16x16x32_bf16 v[66:69], v[146:149], v[202:205], v[66:69]
	v_mfma_f32_16x16x32_bf16 v[62:65], v[154:157], v[202:205], v[62:65]
	v_mfma_f32_16x16x32_bf16 v[50:53], v[146:149], v[194:197], v[50:53]
	v_mfma_f32_16x16x32_bf16 v[46:49], v[154:157], v[194:197], v[46:49]
	v_mfma_f32_16x16x32_bf16 v[34:37], v[146:149], v[186:189], v[34:37]
	v_mfma_f32_16x16x32_bf16 v[30:33], v[154:157], v[186:189], v[30:33]
	v_mfma_f32_16x16x32_bf16 v[18:21], v[146:149], v[178:181], v[18:21]
	v_mfma_f32_16x16x32_bf16 v[14:17], v[154:157], v[178:181], v[14:17]
	s_barrier
	s_setprio 0
	v_add_u32_e32 v2, 0x18000, v248
	ds_read_b128 v[158:161], v2
	ds_read_b128 v[162:165], v2 offset:1024
	ds_read_b128 v[166:169], v2 offset:2048
	ds_read_b128 v[170:173], v2 offset:3072
	v_add_u32_e32 v2, 0x1c000, v248
	ds_read_b128 v[142:145], v2
	ds_read_b128 v[146:149], v2 offset:1024
	ds_read_b128 v[150:153], v2 offset:2048
	ds_read_b128 v[154:157], v2 offset:3072
	s_add_u32 s44, s44, 0x10000
	s_addc_u32 s45, s45, 0
	s_mov_b32 m0, s72
	v_add_u32_e32 v2, 0x22c00, v250
	v_lshl_add_u64 v[212:213], s[44:45], 0, v[214:215]
	ds_read_b128 v[182:185], v249 offset:32768
	ds_read_b128 v[186:189], v249 offset:33792
	ds_read_b128 v[190:193], v249 offset:34816
	ds_read_b128 v[194:197], v249 offset:35840
	ds_read_b128 v[198:201], v249 offset:36864
	ds_read_b128 v[202:205], v249 offset:37888
	ds_read_b128 v[206:209], v249 offset:38912
	ds_read_b128 v[240:243], v249 offset:39936
	ds_read_b128 v[174:177], v2
	ds_read_b128 v[178:181], v2 offset:1024
	global_load_lds_dwordx4 v[212:213], off
	v_lshl_add_u64 v[212:213], s[44:45], 0, v[218:219]
	s_mov_b32 m0, s73
	s_nop 0
	global_load_lds_dwordx4 v[212:213], off
	s_waitcnt vmcnt(9)
	s_waitcnt lgkmcnt(0)
	s_setprio 1
	s_barrier
	v_mfma_f32_16x16x32_bf16 v[138:141], v[158:161], v[182:185], v[138:141]
	v_mfma_f32_16x16x32_bf16 v[134:137], v[166:169], v[182:185], v[134:137]
	v_mfma_f32_16x16x32_bf16 v[122:125], v[158:161], v[190:193], v[122:125]
	v_mfma_f32_16x16x32_bf16 v[118:121], v[166:169], v[190:193], v[118:121]
	v_mfma_f32_16x16x32_bf16 v[106:109], v[158:161], v[198:201], v[106:109]
	v_mfma_f32_16x16x32_bf16 v[102:105], v[166:169], v[198:201], v[102:105]
	v_mfma_f32_16x16x32_bf16 v[90:93], v[158:161], v[206:209], v[90:93]
	v_mfma_f32_16x16x32_bf16 v[86:89], v[166:169], v[206:209], v[86:89]
	v_mfma_f32_16x16x32_bf16 v[138:141], v[162:165], v[186:189], v[138:141]
	v_mfma_f32_16x16x32_bf16 v[134:137], v[170:173], v[186:189], v[134:137]
	v_mfma_f32_16x16x32_bf16 v[122:125], v[162:165], v[194:197], v[122:125]
	v_mfma_f32_16x16x32_bf16 v[118:121], v[170:173], v[194:197], v[118:121]
	v_mfma_f32_16x16x32_bf16 v[106:109], v[162:165], v[202:205], v[106:109]
	v_mfma_f32_16x16x32_bf16 v[102:105], v[170:173], v[202:205], v[102:105]
	v_mfma_f32_16x16x32_bf16 v[90:93], v[162:165], v[240:243], v[90:93]
	v_mfma_f32_16x16x32_bf16 v[86:89], v[170:173], v[240:243], v[86:89]
	v_mfma_f32_16x16x32_bf16 v[130:133], v[142:145], v[182:185], v[130:133]
	v_mfma_f32_16x16x32_bf16 v[126:129], v[150:153], v[182:185], v[126:129]
	v_mfma_f32_16x16x32_bf16 v[114:117], v[142:145], v[190:193], v[114:117]
	v_mfma_f32_16x16x32_bf16 v[110:113], v[150:153], v[190:193], v[110:113]
	v_mfma_f32_16x16x32_bf16 v[98:101], v[142:145], v[198:201], v[98:101]
	v_mfma_f32_16x16x32_bf16 v[94:97], v[150:153], v[198:201], v[94:97]
	v_mfma_f32_16x16x32_bf16 v[82:85], v[142:145], v[206:209], v[82:85]
	v_mfma_f32_16x16x32_bf16 v[78:81], v[150:153], v[206:209], v[78:81]
	v_mfma_f32_16x16x32_bf16 v[130:133], v[146:149], v[186:189], v[130:133]
	v_mfma_f32_16x16x32_bf16 v[126:129], v[154:157], v[186:189], v[126:129]
	v_mfma_f32_16x16x32_bf16 v[114:117], v[146:149], v[194:197], v[114:117]
	v_mfma_f32_16x16x32_bf16 v[110:113], v[154:157], v[194:197], v[110:113]
	v_mfma_f32_16x16x32_bf16 v[98:101], v[146:149], v[202:205], v[98:101]
	v_mfma_f32_16x16x32_bf16 v[94:97], v[154:157], v[202:205], v[94:97]
	v_mfma_f32_16x16x32_bf16 v[82:85], v[146:149], v[240:243], v[82:85]
	v_mfma_f32_16x16x32_bf16 v[78:81], v[154:157], v[240:243], v[78:81]
	s_setprio 0
	s_and_b64 vcc, exec, s[6:7]
	s_cbranch_vccnz .LBB0_1666
	s_setprio 1
	s_and_b64 vcc, exec, s[0:1]
	s_mov_b64 s[0:1], -1
	s_cbranch_vccnz .LBB0_1663
	v_mfma_f32_16x16x32_bf16 v[10:13], v[142:145], v[174:177], v[10:13]
	s_mov_b64 s[0:1], 0
	v_mfma_f32_16x16x32_bf16 v[6:9], v[150:153], v[174:177], v[6:9]
	v_mfma_f32_16x16x32_bf16 v[10:13], v[146:149], v[178:181], v[10:13]
	v_mfma_f32_16x16x32_bf16 v[6:9], v[154:157], v[178:181], v[6:9]

; #define PG8_STAGEX(b, gbase) do { if constexpr (XR) { if (lane < 16) __builtin_amdgcn_global_load_lds((const unsigned*)((const char*)(gbase) + voffX), (PG8_LAS unsigned*)(lds + XR_OFF + (b) * 2048 + wid * 256), 16, 0, 0); } } while (0)
; #define PG8_LDX(b) do { if constexpr (XR) { _Pragma("unroll") for (int k = 0; k < 2; ++k) Ax_[k] = *(const PG8_LAS bf16x8*)(lds + XR_OFF + (b) * 2048 + aoffx + k * 1024); } } while (0)
; #define PG8_MMAX() do { if constexpr (XR) { if (hasx) { __builtin_amdgcn_s_setprio(1); if (wr == 0) PG8_MMAX_(B0); else PG8_MMAX_(B1); __builtin_amdgcn_s_setprio(0); } } } while (0)
; #define PG8_WAIT_LOOP() do { if constexpr (XR) PG8_WAIT_V(9); else PG8_WAIT_V(8); } while (0)
; #define PG8_STAGE(bufoff, gbase, voff) do { _Pragma("unroll") for (int _i = 0; _i < 2; ++_i) \
;         __builtin_amdgcn_global_load_lds((const unsigned*)((const char*)(gbase) + (voff)[_i]), (PG8_LAS unsigned*)(lds + (bufoff) + ldsw + _i * 8192), 16, 0, 0); } while (0)
; #define PG8_BAR __builtin_amdgcn_s_barrier()
; template <class Epi, class Sched, bool ALIGN_EPI = false, bool SP2 = false, bool DRAIN = true, bool XR = false>
; __device__ __forceinline__ void gemm_phase(PG8_LAS unsigned char* lds, const Gemm g, const Sched& S, const Epi& E) {
;     ...
;             PG8_LDB(B0, 0, 0); PG8_LDB(B1, 0, 1); PG8_SCHED; PG8_LDA(At, 0, 0); PG8_LDX(0); PG8_STAGE(PG8_SA(1, 1), a1 + hstepA, voffA);
;             PG8_WAIT_LOOP(); PG8_WAIT_L(0); PG8_BAR; PG8_MMA(0, 0, At, B0); PG8_MMA(0, 1, At, B1); PG8_MMAX(); PG8_BAR; PG8_SCHED;
;             PG8_LDA(At, 0, 1); PG8_STAGE(PG8_SB(0, 0), b2, voffB); PG8_STAGE(PG8_SB(0, 1), b2 + hstep, voffB); PG8_STAGE(PG8_SA(0, 0), a2, voffA); PG8_STAGEX(0, x2);
;             PG8_WAIT_LOOP(); PG8_WAIT_L(0); PG8_BAR; PG8_MMA(1, 0, At, B0); PG8_MMA(1, 1, At, B1); PG8_BAR; PG8_SCHED;
;             PG8_LDB(B0, 1, 0); PG8_LDB(B1, 1, 1); PG8_SCHED; PG8_LDA(At, 1, 0); PG8_LDX(1); PG8_STAGE(PG8_SA(0, 1), a2 + hstepA, voffA);
;             PG8_WAIT_LOOP(); PG8_WAIT_L(0); PG8_BAR; PG8_MMA(0, 0, At, B0); PG8_MMA(0, 1, At, B1); PG8_MMAX(); PG8_BAR; PG8_SCHED;
;             PG8_LDA(At, 1, 1); PG8_STAGE(PG8_SB(1, 0), b3, voffB); PG8_STAGE(PG8_SB(1, 1), b3 + hstep, voffB); PG8_STAGE(PG8_SA(1, 0), a3, voffA); PG8_STAGEX(1, x3);
;             PG8_WAIT_LOOP(); PG8_WAIT_L(0); PG8_BAR; PG8_MMA(1, 0, At, B0); PG8_MMA(1, 1, At, B1); PG8_BAR; PG8_SCHED;
.LBB0_1855:
	s_or_b64 exec, exec, s[0:1]
	s_waitcnt vmcnt(9)
	s_waitcnt lgkmcnt(0)
	s_setprio 1
	s_barrier
	v_mfma_f32_16x16x32_bf16 v[74:77], v[158:161], v[198:201], v[74:77]
	v_mfma_f32_16x16x32_bf16 v[70:73], v[166:169], v[198:201], v[70:73]
	v_mfma_f32_16x16x32_bf16 v[66:69], v[158:161], v[190:193], v[66:69]
	v_mfma_f32_16x16x32_bf16 v[62:65], v[166:169], v[190:193], v[62:65]
	v_mfma_f32_16x16x32_bf16 v[58:61], v[158:161], v[182:185], v[58:61]
	v_mfma_f32_16x16x32_bf16 v[54:57], v[166:169], v[182:185], v[54:57]
	v_mfma_f32_16x16x32_bf16 v[50:53], v[158:161], v[174:177], v[50:53]
	v_mfma_f32_16x16x32_bf16 v[46:49], v[166:169], v[174:177], v[46:49]
	v_mfma_f32_16x16x32_bf16 v[74:77], v[162:165], v[202:205], v[74:77]
	v_mfma_f32_16x16x32_bf16 v[70:73], v[170:173], v[202:205], v[70:73]
	v_mfma_f32_16x16x32_bf16 v[66:69], v[162:165], v[194:197], v[66:69]
	v_mfma_f32_16x16x32_bf16 v[62:65], v[170:173], v[194:197], v[62:65]
	v_mfma_f32_16x16x32_bf16 v[58:61], v[162:165], v[186:189], v[58:61]
	v_mfma_f32_16x16x32_bf16 v[54:57], v[170:173], v[186:189], v[54:57]
	v_mfma_f32_16x16x32_bf16 v[50:53], v[162:165], v[178:181], v[50:53]
	v_mfma_f32_16x16x32_bf16 v[46:49], v[170:173], v[178:181], v[46:49]
	v_mfma_f32_16x16x32_bf16 v[42:45], v[142:145], v[198:201], v[42:45]
	v_mfma_f32_16x16x32_bf16 v[38:41], v[150:153], v[198:201], v[38:41]
	v_mfma_f32_16x16x32_bf16 v[34:37], v[142:145], v[190:193], v[34:37]
	v_mfma_f32_16x16x32_bf16 v[30:33], v[150:153], v[190:193], v[30:33]
	v_mfma_f32_16x16x32_bf16 v[26:29], v[142:145], v[182:185], v[26:29]
	v_mfma_f32_16x16x32_bf16 v[22:25], v[150:153], v[182:185], v[22:25]
	v_mfma_f32_16x16x32_bf16 v[18:21], v[142:145], v[174:177], v[18:21]
	v_mfma_f32_16x16x32_bf16 v[14:17], v[150:153], v[174:177], v[14:17]
	v_mfma_f32_16x16x32_bf16 v[42:45], v[146:149], v[202:205], v[42:45]
	v_mfma_f32_16x16x32_bf16 v[38:41], v[154:157], v[202:205], v[38:41]
	v_mfma_f32_16x16x32_bf16 v[34:37], v[146:149], v[194:197], v[34:37]
	v_mfma_f32_16x16x32_bf16 v[30:33], v[154:157], v[194:197], v[30:33]
	v_mfma_f32_16x16x32_bf16 v[26:29], v[146:149], v[186:189], v[26:29]
	v_mfma_f32_16x16x32_bf16 v[22:25], v[154:157], v[186:189], v[22:25]
	v_mfma_f32_16x16x32_bf16 v[18:21], v[146:149], v[178:181], v[18:21]
	v_mfma_f32_16x16x32_bf16 v[14:17], v[154:157], v[178:181], v[14:17]
	s_barrier
	s_setprio 0
	s_add_i32 s45, s45, 2
	s_cmp_ge_i32 s45, s71
	s_cbranch_scc1 .LBB0_1872
.LBB0_1856:
	v_add_u32_e32 v2, 0x10000, v237
	s_add_i32 s56, s88, s45
	ds_read_b128 v[158:161], v2
	ds_read_b128 v[162:165], v2 offset:1024
	ds_read_b128 v[166:169], v2 offset:2048
	ds_read_b128 v[170:173], v2 offset:3072
	v_add_u32_e32 v2, 0x14000, v237
	s_and_b32 s8, s56, s67
	ds_read_b128 v[142:145], v2
	ds_read_b128 v[146:149], v2 offset:1024
	ds_read_b128 v[150:153], v2 offset:2048
	ds_read_b128 v[154:157], v2 offset:3072
	s_lshr_b32 s84, s8, 2
	s_lshl_b32 s8, s8, 7
	s_lshl_b64 s[0:1], s[84:85], 9
	s_and_b32 s8, s8, 0x100
	s_add_u32 s0, s24, s0
	s_addc_u32 s1, s25, s1
	s_add_u32 s0, s0, s8
	s_addc_u32 s1, s1, 0
	s_add_u32 s0, s0, s18
	s_addc_u32 s1, s1, s19
	v_lshl_add_u64 v[4:5], s[0:1], 0, v[214:215]
	v_add_u32_e32 v2, 0x22400, v239
	v_lshl_add_u64 v[4:5], v[4:5], 0, s[86:87]
	s_add_i32 m0, s72, 0xc000
	ds_read_b128 v[182:185], v238
	ds_read_b128 v[186:189], v238 offset:1024
	ds_read_b128 v[190:193], v238 offset:2048
	ds_read_b128 v[194:197], v238 offset:3072
	ds_read_b128 v[198:201], v238 offset:4096
	ds_read_b128 v[202:205], v238 offset:5120
	ds_read_b128 v[206:209], v238 offset:6144
	ds_read_b128 v[224:227], v238 offset:7168
	ds_read_b128 v[174:177], v2
	ds_read_b128 v[178:181], v2 offset:1024
	global_load_lds_dwordx4 v[4:5], off
	v_lshl_add_u64 v[4:5], s[0:1], 0, v[218:219]
	v_lshl_add_u64 v[4:5], v[4:5], 0, s[86:87]
	s_add_i32 m0, s72, 0xe000
	s_nop 0
	global_load_lds_dwordx4 v[4:5], off
	s_waitcnt vmcnt(9)
	s_waitcnt lgkmcnt(0)
	s_setprio 1
	s_barrier
	v_mfma_f32_16x16x32_bf16 v[138:141], v[158:161], v[182:185], v[138:141]
	v_mfma_f32_16x16x32_bf16 v[134:137], v[166:169], v[182:185], v[134:137]
	v_mfma_f32_16x16x32_bf16 v[130:133], v[158:161], v[190:193], v[130:133]
	v_mfma_f32_16x16x32_bf16 v[126:129], v[166:169], v[190:193], v[126:129]
	v_mfma_f32_16x16x32_bf16 v[122:125], v[158:161], v[198:201], v[122:125]
	v_mfma_f32_16x16x32_bf16 v[118:121], v[166:169], v[198:201], v[118:121]
	v_mfma_f32_16x16x32_bf16 v[114:117], v[158:161], v[206:209], v[114:117]
	v_mfma_f32_16x16x32_bf16 v[110:113], v[166:169], v[206:209], v[110:113]
	v_mfma_f32_16x16x32_bf16 v[138:141], v[162:165], v[186:189], v[138:141]
	v_mfma_f32_16x16x32_bf16 v[134:137], v[170:173], v[186:189], v[134:137]
	v_mfma_f32_16x16x32_bf16 v[130:133], v[162:165], v[194:197], v[130:133]
	v_mfma_f32_16x16x32_bf16 v[126:129], v[170:173], v[194:197], v[126:129]
	v_mfma_f32_16x16x32_bf16 v[122:125], v[162:165], v[202:205], v[122:125]
	v_mfma_f32_16x16x32_bf16 v[118:121], v[170:173], v[202:205], v[118:121]
	v_mfma_f32_16x16x32_bf16 v[114:117], v[162:165], v[224:227], v[114:117]
	v_mfma_f32_16x16x32_bf16 v[110:113], v[170:173], v[224:227], v[110:113]
	v_mfma_f32_16x16x32_bf16 v[106:109], v[142:145], v[182:185], v[106:109]
	v_mfma_f32_16x16x32_bf16 v[102:105], v[150:153], v[182:185], v[102:105]
	v_mfma_f32_16x16x32_bf16 v[98:101], v[142:145], v[190:193], v[98:101]
	v_mfma_f32_16x16x32_bf16 v[94:97], v[150:153], v[190:193], v[94:97]
	v_mfma_f32_16x16x32_bf16 v[90:93], v[142:145], v[198:201], v[90:93]
	v_mfma_f32_16x16x32_bf16 v[86:89], v[150:153], v[198:201], v[86:89]
	v_mfma_f32_16x16x32_bf16 v[82:85], v[142:145], v[206:209], v[82:85]
	v_mfma_f32_16x16x32_bf16 v[78:81], v[150:153], v[206:209], v[78:81]
	v_mfma_f32_16x16x32_bf16 v[106:109], v[146:149], v[186:189], v[106:109]
	v_mfma_f32_16x16x32_bf16 v[102:105], v[154:157], v[186:189], v[102:105]
	v_mfma_f32_16x16x32_bf16 v[98:101], v[146:149], v[194:197], v[98:101]
	v_mfma_f32_16x16x32_bf16 v[94:97], v[154:157], v[194:197], v[94:97]
	v_mfma_f32_16x16x32_bf16 v[90:93], v[146:149], v[202:205], v[90:93]
	v_mfma_f32_16x16x32_bf16 v[86:89], v[154:157], v[202:205], v[86:89]
	v_mfma_f32_16x16x32_bf16 v[82:85], v[146:149], v[224:227], v[82:85]
	v_mfma_f32_16x16x32_bf16 v[78:81], v[154:157], v[224:227], v[78:81]
	s_setprio 0
	v_cndmask_b32_e64 v2, 0, 1, s[40:41]
	v_cmp_ne_u32_e64 s[8:9], 1, v2
	v_cndmask_b32_e64 v2, 0, 1, s[46:47]
	s_andn2_b64 vcc, exec, s[40:41]
	v_cmp_ne_u32_e64 s[0:1], 1, v2
	s_cbranch_vccnz .LBB0_1862
	s_setprio 1
	s_and_b64 vcc, exec, s[0:1]
	s_mov_b64 s[54:55], -1
	s_cbranch_vccnz .LBB0_1859
	v_mfma_f32_16x16x32_bf16 v[10:13], v[142:145], v[174:177], v[10:13]
	s_mov_b64 s[54:55], 0
	v_mfma_f32_16x16x32_bf16 v[6:9], v[150:153], v[174:177], v[6:9]
	v_mfma_f32_16x16x32_bf16 v[10:13], v[146:149], v[178:181], v[10:13]
	v_mfma_f32_16x16x32_bf16 v[6:9], v[154:157], v[178:181], v[6:9]

; #define PG8_LDX(b) do { if constexpr (XR) { _Pragma("unroll") for (int k = 0; k < 2; ++k) Ax_[k] = *(const PG8_LAS bf16x8*)(lds + XR_OFF + (b) * 2048 + aoffx + k * 1024); } } while (0)
; #define PG8_MMAX() do { if constexpr (XR) { if (hasx) { __builtin_amdgcn_s_setprio(1); if (wr == 0) PG8_MMAX_(B0); else PG8_MMAX_(B1); __builtin_amdgcn_s_setprio(0); } } } while (0)
; #define PG8_WAIT_LOOP() do { if constexpr (XR) PG8_WAIT_V(9); else PG8_WAIT_V(8); } while (0)
; #define PG8_STAGE(bufoff, gbase, voff) do { _Pragma("unroll") for (int _i = 0; _i < 2; ++_i) \
;         __builtin_amdgcn_global_load_lds((const unsigned*)((const char*)(gbase) + (voff)[_i]), (PG8_LAS unsigned*)(lds + (bufoff) + ldsw + _i * 8192), 16, 0, 0); } while (0)
; #define PG8_LDA(dst, b, h) do { _Pragma("unroll") for (int m = 0; m < 4; ++m) _Pragma("unroll") for (int k = 0; k < 2; ++k) dst[m][k] = *(const PG8_LAS bf16x8*)(lds + PG8_SA(b, h) + aoff + m * 2048 + k * 1024); } while (0)
; #define PG8_LDB(dst, b, h) do { _Pragma("unroll") for (int n = 0; n < 2; ++n) _Pragma("unroll") for (int k = 0; k < 2; ++k) dst[n][k] = *(const PG8_LAS bf16x8*)(lds + PG8_SB(b, h) + boff + n * 2048 + k * 1024); } while (0)
; #define PG8_MMA(ai, bj, At, Bt) do { __builtin_amdgcn_s_setprio(1); _Pragma("unroll") for (int m = 0; m < 4; ++m) _Pragma("unroll") for (int n = 0; n < 2; ++n) _Pragma("unroll") for (int k = 0; k < 2; ++k) \
;         acc[ai][bj][m][n] = __builtin_amdgcn_mfma_f32_16x16x32_bf16(Bt[n][k], At[m][k], acc[ai][bj][m][n], 0, 0, 0); __builtin_amdgcn_s_setprio(0); } while (0)
; #define PG8_WAIT_L(n) asm volatile("s_waitcnt lgkmcnt(" #n ")" ::: "memory")
; #define PG8_BAR __builtin_amdgcn_s_barrier()
; #define PG8_SCHED __builtin_amdgcn_sched_barrier(0)
; template <class Epi, class Sched, bool ALIGN_EPI = false, bool SP2 = false, bool DRAIN = true, bool XR = false>
; __device__ __forceinline__ void gemm_phase(PG8_LAS unsigned char* lds, const Gemm g, const Sched& S, const Epi& E) {
;     ...
;             PG8_WAIT_LOOP(); PG8_WAIT_L(0); PG8_BAR; PG8_MMA(1, 0, At, B0); PG8_MMA(1, 1, At, B1); PG8_BAR; PG8_SCHED;
;             PG8_LDB(B0, 1, 0); PG8_LDB(B1, 1, 1); PG8_SCHED; PG8_LDA(At, 1, 0); PG8_LDX(1); PG8_STAGE(PG8_SA(0, 1), a2 + hstepA, voffA);
;             PG8_WAIT_LOOP(); PG8_WAIT_L(0); PG8_BAR; PG8_MMA(0, 0, At, B0); PG8_MMA(0, 1, At, B1); PG8_MMAX(); PG8_BAR; PG8_SCHED;
.LBB0_1864:
	s_or_b64 exec, exec, s[56:57]
	s_waitcnt vmcnt(9)
	s_waitcnt lgkmcnt(0)
	s_setprio 1
	s_barrier
	v_mfma_f32_16x16x32_bf16 v[74:77], v[158:161], v[198:201], v[74:77]
	v_mfma_f32_16x16x32_bf16 v[70:73], v[166:169], v[198:201], v[70:73]
	v_mfma_f32_16x16x32_bf16 v[66:69], v[158:161], v[190:193], v[66:69]
	v_mfma_f32_16x16x32_bf16 v[62:65], v[166:169], v[190:193], v[62:65]
	v_mfma_f32_16x16x32_bf16 v[58:61], v[158:161], v[182:185], v[58:61]
	v_mfma_f32_16x16x32_bf16 v[54:57], v[166:169], v[182:185], v[54:57]
	v_mfma_f32_16x16x32_bf16 v[50:53], v[158:161], v[174:177], v[50:53]
	v_mfma_f32_16x16x32_bf16 v[46:49], v[166:169], v[174:177], v[46:49]
	v_mfma_f32_16x16x32_bf16 v[74:77], v[162:165], v[202:205], v[74:77]
	v_mfma_f32_16x16x32_bf16 v[70:73], v[170:173], v[202:205], v[70:73]
	v_mfma_f32_16x16x32_bf16 v[66:69], v[162:165], v[194:197], v[66:69]
	v_mfma_f32_16x16x32_bf16 v[62:65], v[170:173], v[194:197], v[62:65]
	v_mfma_f32_16x16x32_bf16 v[58:61], v[162:165], v[186:189], v[58:61]
	v_mfma_f32_16x16x32_bf16 v[54:57], v[170:173], v[186:189], v[54:57]
	v_mfma_f32_16x16x32_bf16 v[50:53], v[162:165], v[178:181], v[50:53]
	v_mfma_f32_16x16x32_bf16 v[46:49], v[170:173], v[178:181], v[46:49]
	v_mfma_f32_16x16x32_bf16 v[42:45], v[142:145], v[198:201], v[42:45]
	v_mfma_f32_16x16x32_bf16 v[38:41], v[150:153], v[198:201], v[38:41]
	v_mfma_f32_16x16x32_bf16 v[34:37], v[142:145], v[190:193], v[34:37]
	v_mfma_f32_16x16x32_bf16 v[30:33], v[150:153], v[190:193], v[30:33]
	v_mfma_f32_16x16x32_bf16 v[26:29], v[142:145], v[182:185], v[26:29]
	v_mfma_f32_16x16x32_bf16 v[22:25], v[150:153], v[182:185], v[22:25]
	v_mfma_f32_16x16x32_bf16 v[18:21], v[142:145], v[174:177], v[18:21]
	v_mfma_f32_16x16x32_bf16 v[14:17], v[150:153], v[174:177], v[14:17]
	v_mfma_f32_16x16x32_bf16 v[42:45], v[146:149], v[202:205], v[42:45]
	v_mfma_f32_16x16x32_bf16 v[38:41], v[154:157], v[202:205], v[38:41]
	v_mfma_f32_16x16x32_bf16 v[34:37], v[146:149], v[194:197], v[34:37]
	v_mfma_f32_16x16x32_bf16 v[30:33], v[154:157], v[194:197], v[30:33]
	v_mfma_f32_16x16x32_bf16 v[26:29], v[146:149], v[186:189], v[26:29]
	v_mfma_f32_16x16x32_bf16 v[22:25], v[154:157], v[186:189], v[22:25]
	v_mfma_f32_16x16x32_bf16 v[18:21], v[146:149], v[178:181], v[18:21]
	v_mfma_f32_16x16x32_bf16 v[14:17], v[154:157], v[178:181], v[14:17]
	s_barrier
	s_setprio 0
	v_add_u32_e32 v2, 0x18000, v237
	ds_read_b128 v[158:161], v2
	ds_read_b128 v[162:165], v2 offset:1024
	ds_read_b128 v[166:169], v2 offset:2048
	ds_read_b128 v[170:173], v2 offset:3072
	v_add_u32_e32 v2, 0x1c000, v237
	ds_read_b128 v[142:145], v2
	ds_read_b128 v[146:149], v2 offset:1024
	ds_read_b128 v[150:153], v2 offset:2048
	ds_read_b128 v[154:157], v2 offset:3072
	s_add_u32 s54, s54, s18
	s_addc_u32 s55, s55, s19
	s_mov_b32 m0, s79
	v_add_u32_e32 v2, 0x22c00, v239
	v_lshl_add_u64 v[212:213], s[54:55], 0, v[214:215]
	ds_read_b128 v[182:185], v238 offset:32768
	ds_read_b128 v[186:189], v238 offset:33792
	ds_read_b128 v[190:193], v238 offset:34816
	ds_read_b128 v[194:197], v238 offset:35840
	ds_read_b128 v[198:201], v238 offset:36864
	ds_read_b128 v[202:205], v238 offset:37888
	ds_read_b128 v[206:209], v238 offset:38912
	ds_read_b128 v[240:243], v238 offset:39936
	ds_read_b128 v[174:177], v2
	ds_read_b128 v[178:181], v2 offset:1024
	global_load_lds_dwordx4 v[212:213], off
	v_lshl_add_u64 v[212:213], s[54:55], 0, v[218:219]
	s_mov_b32 m0, s80
	s_nop 0
	global_load_lds_dwordx4 v[212:213], off
	s_waitcnt vmcnt(9)
	s_waitcnt lgkmcnt(0)
	s_setprio 1
	s_barrier
	v_mfma_f32_16x16x32_bf16 v[138:141], v[158:161], v[182:185], v[138:141]
	v_mfma_f32_16x16x32_bf16 v[134:137], v[166:169], v[182:185], v[134:137]
	v_mfma_f32_16x16x32_bf16 v[130:133], v[158:161], v[190:193], v[130:133]
	v_mfma_f32_16x16x32_bf16 v[126:129], v[166:169], v[190:193], v[126:129]
	v_mfma_f32_16x16x32_bf16 v[122:125], v[158:161], v[198:201], v[122:125]
	v_mfma_f32_16x16x32_bf16 v[118:121], v[166:169], v[198:201], v[118:121]
	v_mfma_f32_16x16x32_bf16 v[114:117], v[158:161], v[206:209], v[114:117]
	v_mfma_f32_16x16x32_bf16 v[110:113], v[166:169], v[206:209], v[110:113]
	v_mfma_f32_16x16x32_bf16 v[138:141], v[162:165], v[186:189], v[138:141]
	v_mfma_f32_16x16x32_bf16 v[134:137], v[170:173], v[186:189], v[134:137]
	v_mfma_f32_16x16x32_bf16 v[130:133], v[162:165], v[194:197], v[130:133]
	v_mfma_f32_16x16x32_bf16 v[126:129], v[170:173], v[194:197], v[126:129]
	v_mfma_f32_16x16x32_bf16 v[122:125], v[162:165], v[202:205], v[122:125]
	v_mfma_f32_16x16x32_bf16 v[118:121], v[170:173], v[202:205], v[118:121]
	v_mfma_f32_16x16x32_bf16 v[114:117], v[162:165], v[240:243], v[114:117]
	v_mfma_f32_16x16x32_bf16 v[110:113], v[170:173], v[240:243], v[110:113]
	v_mfma_f32_16x16x32_bf16 v[106:109], v[142:145], v[182:185], v[106:109]
	v_mfma_f32_16x16x32_bf16 v[102:105], v[150:153], v[182:185], v[102:105]
	v_mfma_f32_16x16x32_bf16 v[98:101], v[142:145], v[190:193], v[98:101]
	v_mfma_f32_16x16x32_bf16 v[94:97], v[150:153], v[190:193], v[94:97]
	v_mfma_f32_16x16x32_bf16 v[90:93], v[142:145], v[198:201], v[90:93]
	v_mfma_f32_16x16x32_bf16 v[86:89], v[150:153], v[198:201], v[86:89]
	v_mfma_f32_16x16x32_bf16 v[82:85], v[142:145], v[206:209], v[82:85]
	v_mfma_f32_16x16x32_bf16 v[78:81], v[150:153], v[206:209], v[78:81]
	v_mfma_f32_16x16x32_bf16 v[106:109], v[146:149], v[186:189], v[106:109]
	v_mfma_f32_16x16x32_bf16 v[102:105], v[154:157], v[186:189], v[102:105]
	v_mfma_f32_16x16x32_bf16 v[98:101], v[146:149], v[194:197], v[98:101]
	v_mfma_f32_16x16x32_bf16 v[94:97], v[154:157], v[194:197], v[94:97]
	v_mfma_f32_16x16x32_bf16 v[90:93], v[146:149], v[202:205], v[90:93]
	v_mfma_f32_16x16x32_bf16 v[86:89], v[154:157], v[202:205], v[86:89]
	v_mfma_f32_16x16x32_bf16 v[82:85], v[146:149], v[240:243], v[82:85]
	v_mfma_f32_16x16x32_bf16 v[78:81], v[154:157], v[240:243], v[78:81]
	s_setprio 0
	s_and_b64 vcc, exec, s[8:9]
	s_cbranch_vccnz .LBB0_1870
	s_setprio 1
	s_and_b64 vcc, exec, s[0:1]
	s_mov_b64 s[0:1], -1
	s_cbranch_vccnz .LBB0_1867
	v_mfma_f32_16x16x32_bf16 v[10:13], v[142:145], v[174:177], v[10:13]
	s_mov_b64 s[0:1], 0
	v_mfma_f32_16x16x32_bf16 v[6:9], v[150:153], v[174:177], v[6:9]
	v_mfma_f32_16x16x32_bf16 v[10:13], v[146:149], v[178:181], v[10:13]
	v_mfma_f32_16x16x32_bf16 v[6:9], v[154:157], v[178:181], v[6:9]

; #define PG8_STAGEX(b, gbase) do { if constexpr (XR) { if (lane < 16) __builtin_amdgcn_global_load_lds((const unsigned*)((const char*)(gbase) + voffX), (PG8_LAS unsigned*)(lds + XR_OFF + (b) * 2048 + wid * 256), 16, 0, 0); } } while (0)
; #define PG8_LDX(b) do { if constexpr (XR) { _Pragma("unroll") for (int k = 0; k < 2; ++k) Ax_[k] = *(const PG8_LAS bf16x8*)(lds + XR_OFF + (b) * 2048 + aoffx + k * 1024); } } while (0)
; #define PG8_MMAX() do { if constexpr (XR) { if (hasx) { __builtin_amdgcn_s_setprio(1); if (wr == 0) PG8_MMAX_(B0); else PG8_MMAX_(B1); __builtin_amdgcn_s_setprio(0); } } } while (0)
; #define PG8_WAIT_LOOP() do { if constexpr (XR) PG8_WAIT_V(9); else PG8_WAIT_V(8); } while (0)
; #define PG8_STAGE(bufoff, gbase, voff) do { _Pragma("unroll") for (int _i = 0; _i < 2; ++_i) \
;         __builtin_amdgcn_global_load_lds((const unsigned*)((const char*)(gbase) + (voff)[_i]), (PG8_LAS unsigned*)(lds + (bufoff) + ldsw + _i * 8192), 16, 0, 0); } while (0)
; #define PG8_WAIT_L(n) asm volatile("s_waitcnt lgkmcnt(" #n ")" ::: "memory")
; template <class Epi, class Sched, bool ALIGN_EPI = false, bool SP2 = false, bool DRAIN = true, bool XR = false>
; __device__ __forceinline__ void gemm_phase(PG8_LAS unsigned char* lds, const Gemm g, const Sched& S, const Epi& E) {
;     ...
;         for (int t = 0; t < nt; t += 2) {
;             if constexpr (Epi::MIDSCALE) { if (t == (nt >> 1)) E.midscale(acc, cur, wr, fr); }
;             const bool last = (t == nt - 2);
;             const char* a1 = cA + PG8_KOA(t) + kstep;
;             const char* a2 = last ? nA + ka0 : cA + PG8_KOA(t + 2); const char* b2 = last ? nB + kb0 : cB + PG8_KOB(t + 2);
;             const char* x2 = XR ? (last ? nX + kx0 : cX + PG8_KOX(t + 2)) : nullptr; const char* x3 = XR ? x2 + kstep : nullptr;
;             const char* a3 = a2 + kstep; const char* b3 = b2 + kstep;
;             if (last && has_next) S.a_ready(nxt);
;             if constexpr (SP2) {
;             PG8_LDB(B0, 0, 0); PG8_LDB(B1, 0, 1); PG8_SCHED; PG8_LDA(At, 0, 0); PG8_LDX(0); PG8_STAGE(PG8_SA(1, 1), a1 + hstepA, voffA);
;             PG8_WAIT_LOOP(); PG8_WAIT_L(0); PG8_BAR; PG8_MMA(0, 0, At, B0); PG8_MMA(0, 1, At, B1); PG8_MMAX(); PG8_BAR; PG8_SCHED;
;             PG8_LDA(At, 0, 1); PG8_STAGE(PG8_SB(0, 0), b2, voffB); PG8_STAGE(PG8_SB(0, 1), b2 + hstep, voffB); PG8_STAGE(PG8_SA(0, 0), a2, voffA); PG8_STAGEX(0, x2);
.LBB0_2023:
	s_add_i32 s40, s88, s25
	s_and_b32 s41, s40, s93
	s_lshr_b32 s84, s41, 2
	s_lshl_b32 s36, s41, 7
	s_lshl_b64 s[0:1], s[84:85], 9
	s_and_b32 s36, s36, 0x100
	s_add_u32 s0, s58, s0
	s_addc_u32 s1, s59, s1
	s_add_u32 s42, s0, s36
	s_addc_u32 s43, s1, 0
	s_add_i32 s40, s40, 2
	s_and_b32 s0, s40, s93
	s_lshr_b32 s84, s0, 2
	s_lshl_b32 s1, s0, 7
	s_lshl_b64 s[40:41], s[84:85], 9
	s_and_b32 s1, s1, 0x100
	s_add_u32 s36, s58, s40
	s_addc_u32 s40, s59, s41
	s_add_u32 s36, s36, s1
	s_mov_b32 s1, s85
	s_addc_u32 s40, s40, 0
	s_lshl_b64 s[0:1], s[0:1], 7
	s_add_u32 s44, s56, s0
	s_addc_u32 s41, s57, s1
	s_add_i32 s45, 0, 0x10000
	s_cmp_eq_u32 s92, s25
	s_cselect_b32 s1, s22, s40
	s_cselect_b32 s0, s9, s36
	v_add_u32_e32 v2, s45, v182
	s_cselect_b32 s41, s24, s41
	s_cselect_b32 s40, s23, s44
	s_add_i32 s36, 0, 0x14000
	ds_read_b128 v[134:137], v2
	ds_read_b128 v[138:141], v2 offset:1024
	ds_read_b128 v[142:145], v2 offset:2048
	ds_read_b128 v[146:149], v2 offset:3072
	v_add_u32_e32 v2, s36, v182
	ds_read_b128 v[150:153], v2
	ds_read_b128 v[154:157], v2 offset:1024
	ds_read_b128 v[158:161], v2 offset:2048
	ds_read_b128 v[162:165], v2 offset:3072
	s_add_u32 s42, s42, s68
	s_addc_u32 s43, s43, s69
	v_lshl_add_u64 v[4:5], s[42:43], 0, v[172:173]
	v_lshl_add_u64 v[4:5], v[4:5], 0, s[86:87]
	s_add_i32 m0, s49, 0xc000
	ds_read_b128 v[174:177], v199
	ds_read_b128 v[200:203], v199 offset:1024
	ds_read_b128 v[204:207], v199 offset:2048
	ds_read_b128 v[214:217], v199 offset:3072
	ds_read_b128 v[218:221], v199 offset:4096
	ds_read_b128 v[222:225], v199 offset:5120
	ds_read_b128 v[226:229], v199 offset:6144
	ds_read_b128 v[230:233], v199 offset:7168
	global_load_lds_dwordx4 v[4:5], off
	v_lshl_add_u64 v[4:5], s[42:43], 0, v[168:169]
	v_lshl_add_u64 v[4:5], v[4:5], 0, s[86:87]
	s_add_i32 m0, s49, 0xe000
	s_nop 0
	global_load_lds_dwordx4 v[4:5], off
	s_waitcnt vmcnt(8)
	s_waitcnt lgkmcnt(0)
	s_setprio 1
	s_barrier
	v_mfma_f32_16x16x32_bf16 v[130:133], v[134:137], v[174:177], v[130:133]
	v_mfma_f32_16x16x32_bf16 v[98:101], v[142:145], v[174:177], v[98:101]
	v_mfma_f32_16x16x32_bf16 v[126:129], v[134:137], v[204:207], v[126:129]
	v_mfma_f32_16x16x32_bf16 v[90:93], v[142:145], v[204:207], v[90:93]
	v_mfma_f32_16x16x32_bf16 v[122:125], v[134:137], v[218:221], v[122:125]
	v_mfma_f32_16x16x32_bf16 v[82:85], v[142:145], v[218:221], v[82:85]
	v_mfma_f32_16x16x32_bf16 v[118:121], v[134:137], v[226:229], v[118:121]
	v_mfma_f32_16x16x32_bf16 v[74:77], v[142:145], v[226:229], v[74:77]
	v_mfma_f32_16x16x32_bf16 v[130:133], v[138:141], v[200:203], v[130:133]
	v_mfma_f32_16x16x32_bf16 v[98:101], v[146:149], v[200:203], v[98:101]
	v_mfma_f32_16x16x32_bf16 v[126:129], v[138:141], v[214:217], v[126:129]
	v_mfma_f32_16x16x32_bf16 v[90:93], v[146:149], v[214:217], v[90:93]
	v_mfma_f32_16x16x32_bf16 v[122:125], v[138:141], v[222:225], v[122:125]
	v_mfma_f32_16x16x32_bf16 v[82:85], v[146:149], v[222:225], v[82:85]
	v_mfma_f32_16x16x32_bf16 v[118:121], v[138:141], v[230:233], v[118:121]
	v_mfma_f32_16x16x32_bf16 v[74:77], v[146:149], v[230:233], v[74:77]
	v_mfma_f32_16x16x32_bf16 v[114:117], v[150:153], v[174:177], v[114:117]
	v_mfma_f32_16x16x32_bf16 v[66:69], v[158:161], v[174:177], v[66:69]
	v_mfma_f32_16x16x32_bf16 v[110:113], v[150:153], v[204:207], v[110:113]
	v_mfma_f32_16x16x32_bf16 v[58:61], v[158:161], v[204:207], v[58:61]
	v_mfma_f32_16x16x32_bf16 v[106:109], v[150:153], v[218:221], v[106:109]
	v_mfma_f32_16x16x32_bf16 v[50:53], v[158:161], v[218:221], v[50:53]
	v_mfma_f32_16x16x32_bf16 v[102:105], v[150:153], v[226:229], v[102:105]
	v_mfma_f32_16x16x32_bf16 v[42:45], v[158:161], v[226:229], v[42:45]
	v_mfma_f32_16x16x32_bf16 v[114:117], v[154:157], v[200:203], v[114:117]
	v_mfma_f32_16x16x32_bf16 v[66:69], v[162:165], v[200:203], v[66:69]
	v_mfma_f32_16x16x32_bf16 v[110:113], v[154:157], v[214:217], v[110:113]
	v_mfma_f32_16x16x32_bf16 v[58:61], v[162:165], v[214:217], v[58:61]
	v_mfma_f32_16x16x32_bf16 v[106:109], v[154:157], v[222:225], v[106:109]
	v_mfma_f32_16x16x32_bf16 v[50:53], v[162:165], v[222:225], v[50:53]
	v_mfma_f32_16x16x32_bf16 v[102:105], v[154:157], v[230:233], v[102:105]
	v_mfma_f32_16x16x32_bf16 v[42:45], v[162:165], v[230:233], v[42:45]
	s_barrier
	s_setprio 0
	s_add_i32 s42, s45, s48
	v_lshl_add_u64 v[178:179], s[40:41], 0, v[170:171]
	s_mov_b32 m0, s42
	ds_read_b128 v[174:177], v199 offset:16384
	ds_read_b128 v[200:203], v199 offset:17408
	ds_read_b128 v[204:207], v199 offset:18432
	ds_read_b128 v[214:217], v199 offset:19456
	ds_read_b128 v[218:221], v199 offset:20480
	ds_read_b128 v[222:225], v199 offset:21504
	ds_read_b128 v[226:229], v199 offset:22528
	ds_read_b128 v[230:233], v199 offset:23552
	global_load_lds_dwordx4 v[178:179], off
	s_add_i32 m0, s42, 0x2000
	v_lshl_add_u64 v[208:209], s[40:41], 0, v[166:167]
	s_add_u32 s40, s40, s68
	s_addc_u32 s41, s41, s69
	s_add_i32 s36, s36, s48
	global_load_lds_dwordx4 v[208:209], off
	v_lshl_add_u64 v[212:213], s[40:41], 0, v[170:171]
	s_mov_b32 m0, s36
	v_lshl_add_u64 v[234:235], s[40:41], 0, v[166:167]
	global_load_lds_dwordx4 v[212:213], off
	s_add_i32 m0, s36, 0x2000
	v_lshl_add_u64 v[236:237], s[0:1], 0, v[172:173]
	global_load_lds_dwordx4 v[234:235], off
	s_mov_b32 m0, s49
	v_lshl_add_u64 v[238:239], s[0:1], 0, v[168:169]
	global_load_lds_dwordx4 v[236:237], off
	s_mov_b32 m0, s83
	s_nop 0
	global_load_lds_dwordx4 v[238:239], off
	s_waitcnt vmcnt(8)
	s_waitcnt lgkmcnt(0)
	s_setprio 1
	s_barrier
; #define PG8_LDX(b) do { if constexpr (XR) { _Pragma("unroll") for (int k = 0; k < 2; ++k) Ax_[k] = *(const PG8_LAS bf16x8*)(lds + XR_OFF + (b) * 2048 + aoffx + k * 1024); } } while (0)
; #define PG8_MMAX() do { if constexpr (XR) { if (hasx) { __builtin_amdgcn_s_setprio(1); if (wr == 0) PG8_MMAX_(B0); else PG8_MMAX_(B1); __builtin_amdgcn_s_setprio(0); } } } while (0)
; #define PG8_WAIT_LOOP() do { if constexpr (XR) PG8_WAIT_V(9); else PG8_WAIT_V(8); } while (0)
; #define PG8_STAGE(bufoff, gbase, voff) do { _Pragma("unroll") for (int _i = 0; _i < 2; ++_i) \
;         __builtin_amdgcn_global_load_lds((const unsigned*)((const char*)(gbase) + (voff)[_i]), (PG8_LAS unsigned*)(lds + (bufoff) + ldsw + _i * 8192), 16, 0, 0); } while (0)
; #define PG8_LDA(dst, b, h) do { _Pragma("unroll") for (int m = 0; m < 4; ++m) _Pragma("unroll") for (int k = 0; k < 2; ++k) dst[m][k] = *(const PG8_LAS bf16x8*)(lds + PG8_SA(b, h) + aoff + m * 2048 + k * 1024); } while (0)
; #define PG8_LDB(dst, b, h) do { _Pragma("unroll") for (int n = 0; n < 2; ++n) _Pragma("unroll") for (int k = 0; k < 2; ++k) dst[n][k] = *(const PG8_LAS bf16x8*)(lds + PG8_SB(b, h) + boff + n * 2048 + k * 1024); } while (0)
; #define PG8_MMA(ai, bj, At, Bt) do { __builtin_amdgcn_s_setprio(1); _Pragma("unroll") for (int m = 0; m < 4; ++m) _Pragma("unroll") for (int n = 0; n < 2; ++n) _Pragma("unroll") for (int k = 0; k < 2; ++k) \
;         acc[ai][bj][m][n] = __builtin_amdgcn_mfma_f32_16x16x32_bf16(Bt[n][k], At[m][k], acc[ai][bj][m][n], 0, 0, 0); __builtin_amdgcn_s_setprio(0); } while (0)
; #define PG8_WAIT_L(n) asm volatile("s_waitcnt lgkmcnt(" #n ")" ::: "memory")
; #define PG8_BAR __builtin_amdgcn_s_barrier()
; #define PG8_SCHED __builtin_amdgcn_sched_barrier(0)
; template <class Epi, class Sched, bool ALIGN_EPI = false, bool SP2 = false, bool DRAIN = true, bool XR = false>
; __device__ __forceinline__ void gemm_phase(PG8_LAS unsigned char* lds, const Gemm g, const Sched& S, const Epi& E) {
;     ...
;             PG8_WAIT_LOOP(); PG8_WAIT_L(0); PG8_BAR; PG8_MMA(1, 0, At, B0); PG8_MMA(1, 1, At, B1); PG8_BAR; PG8_SCHED;
;             PG8_LDB(B0, 1, 0); PG8_LDB(B1, 1, 1); PG8_SCHED; PG8_LDA(At, 1, 0); PG8_LDX(1); PG8_STAGE(PG8_SA(0, 1), a2 + hstepA, voffA);
;             PG8_WAIT_LOOP(); PG8_WAIT_L(0); PG8_BAR; PG8_MMA(0, 0, At, B0); PG8_MMA(0, 1, At, B1); PG8_MMAX(); PG8_BAR; PG8_SCHED;
	v_mfma_f32_16x16x32_bf16 v[94:97], v[134:137], v[174:177], v[94:97]
	v_mfma_f32_16x16x32_bf16 v[34:37], v[142:145], v[174:177], v[34:37]
	v_mfma_f32_16x16x32_bf16 v[86:89], v[134:137], v[204:207], v[86:89]
	v_mfma_f32_16x16x32_bf16 v[30:33], v[142:145], v[204:207], v[30:33]
	v_mfma_f32_16x16x32_bf16 v[78:81], v[134:137], v[218:221], v[78:81]
	v_mfma_f32_16x16x32_bf16 v[26:29], v[142:145], v[218:221], v[26:29]
	v_mfma_f32_16x16x32_bf16 v[70:73], v[134:137], v[226:229], v[70:73]
	v_mfma_f32_16x16x32_bf16 v[22:25], v[142:145], v[226:229], v[22:25]
	v_mfma_f32_16x16x32_bf16 v[94:97], v[138:141], v[200:203], v[94:97]
	v_mfma_f32_16x16x32_bf16 v[34:37], v[146:149], v[200:203], v[34:37]
	v_mfma_f32_16x16x32_bf16 v[86:89], v[138:141], v[214:217], v[86:89]
	v_mfma_f32_16x16x32_bf16 v[30:33], v[146:149], v[214:217], v[30:33]
	v_mfma_f32_16x16x32_bf16 v[78:81], v[138:141], v[222:225], v[78:81]
	v_mfma_f32_16x16x32_bf16 v[26:29], v[146:149], v[222:225], v[26:29]
	v_mfma_f32_16x16x32_bf16 v[70:73], v[138:141], v[230:233], v[70:73]
	v_mfma_f32_16x16x32_bf16 v[22:25], v[146:149], v[230:233], v[22:25]
	v_mfma_f32_16x16x32_bf16 v[62:65], v[150:153], v[174:177], v[62:65]
	v_mfma_f32_16x16x32_bf16 v[18:21], v[158:161], v[174:177], v[18:21]
	v_mfma_f32_16x16x32_bf16 v[54:57], v[150:153], v[204:207], v[54:57]
	v_mfma_f32_16x16x32_bf16 v[14:17], v[158:161], v[204:207], v[14:17]
	v_mfma_f32_16x16x32_bf16 v[46:49], v[150:153], v[218:221], v[46:49]
	v_mfma_f32_16x16x32_bf16 v[10:13], v[158:161], v[218:221], v[10:13]
	v_mfma_f32_16x16x32_bf16 v[38:41], v[150:153], v[226:229], v[38:41]
	v_mfma_f32_16x16x32_bf16 v[4:7], v[158:161], v[226:229], v[6:9]
	v_mfma_f32_16x16x32_bf16 v[62:65], v[154:157], v[200:203], v[62:65]
	v_mfma_f32_16x16x32_bf16 v[18:21], v[162:165], v[200:203], v[18:21]
	v_mfma_f32_16x16x32_bf16 v[54:57], v[154:157], v[214:217], v[54:57]
	v_mfma_f32_16x16x32_bf16 v[14:17], v[162:165], v[214:217], v[14:17]
	v_mfma_f32_16x16x32_bf16 v[46:49], v[154:157], v[222:225], v[46:49]
	v_mfma_f32_16x16x32_bf16 v[10:13], v[162:165], v[222:225], v[10:13]
	v_mfma_f32_16x16x32_bf16 v[38:41], v[154:157], v[230:233], v[38:41]
	v_mfma_f32_16x16x32_bf16 v[4:7], v[162:165], v[230:233], v[4:7]
	s_barrier
	s_setprio 0
	s_add_i32 s36, 0, 0x18000
	v_add_u32_e32 v2, s36, v182
	s_add_i32 s40, 0, 0x1c000
	ds_read_b128 v[134:137], v2
	ds_read_b128 v[138:141], v2 offset:1024
	ds_read_b128 v[142:145], v2 offset:2048
	ds_read_b128 v[146:149], v2 offset:3072
	v_add_u32_e32 v2, s40, v182
	ds_read_b128 v[150:153], v2
	ds_read_b128 v[154:157], v2 offset:1024
	ds_read_b128 v[158:161], v2 offset:2048
	ds_read_b128 v[162:165], v2 offset:3072
	s_add_u32 s0, s0, s68
	s_addc_u32 s1, s1, s69
	s_mov_b32 m0, s4
	v_lshl_add_u64 v[8:9], s[0:1], 0, v[172:173]
	ds_read_b128 v[174:177], v199 offset:32768
	ds_read_b128 v[200:203], v199 offset:33792
	ds_read_b128 v[204:207], v199 offset:34816
	ds_read_b128 v[214:217], v199 offset:35840
	ds_read_b128 v[218:221], v199 offset:36864
	ds_read_b128 v[222:225], v199 offset:37888
	ds_read_b128 v[226:229], v199 offset:38912
	ds_read_b128 v[230:233], v199 offset:39936
	global_load_lds_dwordx4 v[8:9], off
	v_lshl_add_u64 v[8:9], s[0:1], 0, v[168:169]
	s_mov_b32 m0, s5
	s_nop 0
	global_load_lds_dwordx4 v[8:9], off
	s_waitcnt vmcnt(8)
	s_waitcnt lgkmcnt(0)
	s_setprio 1
	s_barrier
	v_mfma_f32_16x16x32_bf16 v[130:133], v[134:137], v[174:177], v[130:133]
	v_mfma_f32_16x16x32_bf16 v[98:101], v[142:145], v[174:177], v[98:101]
	v_mfma_f32_16x16x32_bf16 v[126:129], v[134:137], v[204:207], v[126:129]
	v_mfma_f32_16x16x32_bf16 v[90:93], v[142:145], v[204:207], v[90:93]
	v_mfma_f32_16x16x32_bf16 v[122:125], v[134:137], v[218:221], v[122:125]
	v_mfma_f32_16x16x32_bf16 v[82:85], v[142:145], v[218:221], v[82:85]
	v_mfma_f32_16x16x32_bf16 v[118:121], v[134:137], v[226:229], v[118:121]
	v_mfma_f32_16x16x32_bf16 v[74:77], v[142:145], v[226:229], v[74:77]
	v_mfma_f32_16x16x32_bf16 v[130:133], v[138:141], v[200:203], v[130:133]
	v_mfma_f32_16x16x32_bf16 v[98:101], v[146:149], v[200:203], v[98:101]
	v_mfma_f32_16x16x32_bf16 v[126:129], v[138:141], v[214:217], v[126:129]
	v_mfma_f32_16x16x32_bf16 v[90:93], v[146:149], v[214:217], v[90:93]
	v_mfma_f32_16x16x32_bf16 v[122:125], v[138:141], v[222:225], v[122:125]
	v_mfma_f32_16x16x32_bf16 v[82:85], v[146:149], v[222:225], v[82:85]
	v_mfma_f32_16x16x32_bf16 v[118:121], v[138:141], v[230:233], v[118:121]
	v_mfma_f32_16x16x32_bf16 v[74:77], v[146:149], v[230:233], v[74:77]
	v_mfma_f32_16x16x32_bf16 v[114:117], v[150:153], v[174:177], v[114:117]
	v_mfma_f32_16x16x32_bf16 v[66:69], v[158:161], v[174:177], v[66:69]
	v_mfma_f32_16x16x32_bf16 v[110:113], v[150:153], v[204:207], v[110:113]
	v_mfma_f32_16x16x32_bf16 v[58:61], v[158:161], v[204:207], v[58:61]
	v_mfma_f32_16x16x32_bf16 v[106:109], v[150:153], v[218:221], v[106:109]
	v_mfma_f32_16x16x32_bf16 v[50:53], v[158:161], v[218:221], v[50:53]
	v_mfma_f32_16x16x32_bf16 v[102:105], v[150:153], v[226:229], v[102:105]
	v_mfma_f32_16x16x32_bf16 v[42:45], v[158:161], v[226:229], v[42:45]
	v_mfma_f32_16x16x32_bf16 v[114:117], v[154:157], v[200:203], v[114:117]
	v_mfma_f32_16x16x32_bf16 v[66:69], v[162:165], v[200:203], v[66:69]
	v_mfma_f32_16x16x32_bf16 v[110:113], v[154:157], v[214:217], v[110:113]
	v_mfma_f32_16x16x32_bf16 v[58:61], v[162:165], v[214:217], v[58:61]
	v_mfma_f32_16x16x32_bf16 v[106:109], v[154:157], v[222:225], v[106:109]
	v_mfma_f32_16x16x32_bf16 v[50:53], v[162:165], v[222:225], v[50:53]
	v_mfma_f32_16x16x32_bf16 v[102:105], v[154:157], v[230:233], v[102:105]
	v_mfma_f32_16x16x32_bf16 v[42:45], v[162:165], v[230:233], v[42:45]
	s_barrier
; #define PG8_STAGEX(b, gbase) do { if constexpr (XR) { if (lane < 16) __builtin_amdgcn_global_load_lds((const unsigned*)((const char*)(gbase) + voffX), (PG8_LAS unsigned*)(lds + XR_OFF + (b) * 2048 + wid * 256), 16, 0, 0); } } while (0)
; #define PG8_WAIT_LOOP() do { if constexpr (XR) PG8_WAIT_V(9); else PG8_WAIT_V(8); } while (0)
; #define PG8_STAGE(bufoff, gbase, voff) do { _Pragma("unroll") for (int _i = 0; _i < 2; ++_i) \
;         __builtin_amdgcn_global_load_lds((const unsigned*)((const char*)(gbase) + (voff)[_i]), (PG8_LAS unsigned*)(lds + (bufoff) + ldsw + _i * 8192), 16, 0, 0); } while (0)
; #define PG8_LDA(dst, b, h) do { _Pragma("unroll") for (int m = 0; m < 4; ++m) _Pragma("unroll") for (int k = 0; k < 2; ++k) dst[m][k] = *(const PG8_LAS bf16x8*)(lds + PG8_SA(b, h) + aoff + m * 2048 + k * 1024); } while (0)
; #define PG8_MMA(ai, bj, At, Bt) do { __builtin_amdgcn_s_setprio(1); _Pragma("unroll") for (int m = 0; m < 4; ++m) _Pragma("unroll") for (int n = 0; n < 2; ++n) _Pragma("unroll") for (int k = 0; k < 2; ++k) \
;         acc[ai][bj][m][n] = __builtin_amdgcn_mfma_f32_16x16x32_bf16(Bt[n][k], At[m][k], acc[ai][bj][m][n], 0, 0, 0); __builtin_amdgcn_s_setprio(0); } while (0)
; #define PG8_WAIT_L(n) asm volatile("s_waitcnt lgkmcnt(" #n ")" ::: "memory")
; #define PG8_BAR __builtin_amdgcn_s_barrier()
; #define PG8_SCHED __builtin_amdgcn_sched_barrier(0)
; template <class Epi, class Sched, bool ALIGN_EPI = false, bool SP2 = false, bool DRAIN = true, bool XR = false>
; __device__ __forceinline__ void gemm_phase(PG8_LAS unsigned char* lds, const Gemm g, const Sched& S, const Epi& E) {
;     ...
;         for (int t = 0; t < nt; t += 2) {
;     ...
;             PG8_LDA(At, 1, 1); PG8_STAGE(PG8_SB(1, 0), b3, voffB); PG8_STAGE(PG8_SB(1, 1), b3 + hstep, voffB); PG8_STAGE(PG8_SA(1, 0), a3, voffA); PG8_STAGEX(1, x3);
;             PG8_WAIT_LOOP(); PG8_WAIT_L(0); PG8_BAR; PG8_MMA(1, 0, At, B0); PG8_MMA(1, 1, At, B1); PG8_BAR; PG8_SCHED;
	s_setprio 0
	s_add_i32 s0, s36, s48
	v_lshl_add_u64 v[8:9], v[178:179], 0, s[86:87]
	s_mov_b32 m0, s0
	ds_read_b128 v[174:177], v199 offset:49152
	ds_read_b128 v[200:203], v199 offset:50176
	ds_read_b128 v[204:207], v199 offset:51200
	ds_read_b128 v[214:217], v199 offset:52224
	ds_read_b128 v[218:221], v199 offset:53248
	ds_read_b128 v[222:225], v199 offset:54272
	ds_read_b128 v[226:229], v199 offset:55296
	ds_read_b128 v[230:233], v199 offset:56320
	global_load_lds_dwordx4 v[8:9], off
	v_lshl_add_u64 v[8:9], v[208:209], 0, s[86:87]
	s_add_i32 m0, s0, 0x2000
	s_add_i32 s0, s40, s48
	global_load_lds_dwordx4 v[8:9], off
	v_lshl_add_u64 v[8:9], v[212:213], 0, s[86:87]
	s_mov_b32 m0, s0
	s_nop 0
	global_load_lds_dwordx4 v[8:9], off
	v_lshl_add_u64 v[8:9], v[234:235], 0, s[86:87]
	s_add_i32 m0, s0, 0x2000
	s_nop 0
	global_load_lds_dwordx4 v[8:9], off
	v_lshl_add_u64 v[8:9], v[236:237], 0, s[86:87]
	s_mov_b32 m0, s77
	s_nop 0
	global_load_lds_dwordx4 v[8:9], off
	v_lshl_add_u64 v[8:9], v[238:239], 0, s[86:87]
	s_mov_b32 m0, s6
	s_nop 0
	global_load_lds_dwordx4 v[8:9], off
	s_waitcnt vmcnt(8)
	s_waitcnt lgkmcnt(0)
	s_setprio 1
	s_barrier
	v_mfma_f32_16x16x32_bf16 v[94:97], v[134:137], v[174:177], v[94:97]
	v_mfma_f32_16x16x32_bf16 v[34:37], v[142:145], v[174:177], v[34:37]
	v_mfma_f32_16x16x32_bf16 v[86:89], v[134:137], v[204:207], v[86:89]
	v_mfma_f32_16x16x32_bf16 v[30:33], v[142:145], v[204:207], v[30:33]
	v_mfma_f32_16x16x32_bf16 v[78:81], v[134:137], v[218:221], v[78:81]
	v_mfma_f32_16x16x32_bf16 v[26:29], v[142:145], v[218:221], v[26:29]
	v_mfma_f32_16x16x32_bf16 v[70:73], v[134:137], v[226:229], v[70:73]
	v_mfma_f32_16x16x32_bf16 v[22:25], v[142:145], v[226:229], v[22:25]
	v_mfma_f32_16x16x32_bf16 v[94:97], v[138:141], v[200:203], v[94:97]
	v_mfma_f32_16x16x32_bf16 v[34:37], v[146:149], v[200:203], v[34:37]
	v_mfma_f32_16x16x32_bf16 v[86:89], v[138:141], v[214:217], v[86:89]
	v_mfma_f32_16x16x32_bf16 v[30:33], v[146:149], v[214:217], v[30:33]
	v_mfma_f32_16x16x32_bf16 v[78:81], v[138:141], v[222:225], v[78:81]
	v_mfma_f32_16x16x32_bf16 v[26:29], v[146:149], v[222:225], v[26:29]
	v_mfma_f32_16x16x32_bf16 v[70:73], v[138:141], v[230:233], v[70:73]
	v_mfma_f32_16x16x32_bf16 v[22:25], v[146:149], v[230:233], v[22:25]
	v_mfma_f32_16x16x32_bf16 v[62:65], v[150:153], v[174:177], v[62:65]
	v_mfma_f32_16x16x32_bf16 v[18:21], v[158:161], v[174:177], v[18:21]
	v_mfma_f32_16x16x32_bf16 v[54:57], v[150:153], v[204:207], v[54:57]
	v_mfma_f32_16x16x32_bf16 v[14:17], v[158:161], v[204:207], v[14:17]
	v_mfma_f32_16x16x32_bf16 v[46:49], v[150:153], v[218:221], v[46:49]
	v_mfma_f32_16x16x32_bf16 v[8:11], v[158:161], v[218:221], v[10:13]
	v_mfma_f32_16x16x32_bf16 v[38:41], v[150:153], v[226:229], v[38:41]
	v_mfma_f32_16x16x32_bf16 v[4:7], v[158:161], v[226:229], v[4:7]
	v_mfma_f32_16x16x32_bf16 v[62:65], v[154:157], v[200:203], v[62:65]
	v_mfma_f32_16x16x32_bf16 v[18:21], v[162:165], v[200:203], v[18:21]
	v_mfma_f32_16x16x32_bf16 v[54:57], v[154:157], v[214:217], v[54:57]
	v_mfma_f32_16x16x32_bf16 v[14:17], v[162:165], v[214:217], v[14:17]
	v_mfma_f32_16x16x32_bf16 v[46:49], v[154:157], v[222:225], v[46:49]
	v_mfma_f32_16x16x32_bf16 v[10:13], v[162:165], v[222:225], v[8:11]
	v_mfma_f32_16x16x32_bf16 v[38:41], v[154:157], v[230:233], v[38:41]
	v_mfma_f32_16x16x32_bf16 v[6:9], v[162:165], v[230:233], v[4:7]
	s_barrier
	s_setprio 0
	s_add_i32 s25, s25, 2
	s_cmp_ge_i32 s25, s78
	s_cbranch_scc0 .LBB0_2023
